# strategy 4: one static s_setprio 1 for waves 4-7 before the layer loop, all per-segment priority flips in the K-loops deleted
# baseline (speedup 1.0000x reference)
; #define LAS __attribute__((address_space(3)))
; __device__ __forceinline__ void xcd_barrier_complete(unsigned* bar, unsigned x, unsigned& nloc, unsigned& nx) {
;     const unsigned G = gridDim.x * gridDim.y * gridDim.z;
;     unsigned sum, cnt, mine, sp = 0u;
;     for (;;) {
;         sum = 0u; cnt = 0u; mine = 0u;
; #pragma unroll
;         for (unsigned j = 0; j < 16; ++j) { const unsigned c = xb_ld(&bar[XB_XCNT(j)]); sum += c; cnt += (c > 0u) ? 1u : 0u; mine = (j == x) ? c : mine; }
;         if (sum == G) break;
;         __builtin_amdgcn_s_sleep(1);
;         if ((++sp & 255u) == 0u) { if (xb_ld(&bar[XB_TMO])) break; if (sp > XB_SPIN_CAP) { atomicAdd(&bar[XB_TMO], 1u); break; } }
;     }
;     nloc = mine > 0u ? mine : 1u; nx = cnt > 0u ? cnt : 1u;
; }
; __device__ __forceinline__ void xcd_barrier(const XcdBarrier& b, int wave) {
;     asm volatile("s_waitcnt vmcnt(0)" ::: "memory");
;     __syncthreads();
;     if (xb_leader(wave)) {
;         unsigned* bar = b.bar;
;         __builtin_amdgcn_s_waitcnt(0);
;         unsigned nloc = b.st[0], nx = b.st[1];
;         if (nloc == 0u) { xcd_barrier_complete(bar, b.x, nloc, nx); b.st[0] = nloc; b.st[1] = nx; }
;         const unsigned old = xb_add(&bar[XB_XSUB(b.x)], 1u);
;         const unsigned gen = old / nloc;
;         if (old + 1u == (gen + 1u) * nloc) {
;             __builtin_amdgcn_fence(__ATOMIC_RELEASE, "agent");
;             asm volatile("s_waitcnt vmcnt(0)" ::: "memory");
;             const unsigned og = xb_add(&bar[XB_TOP], 1u);
;             const unsigned tg = og / nx;
;             if (og + 1u == (tg + 1u) * nx) xb_add(&bar[XB_TOPGEN], 1u);
;             else XB_SPIN(xb_ld(&bar[XB_TOPGEN]) == tg, bar);
;             __builtin_amdgcn_fence(__ATOMIC_ACQUIRE, "agent");
;             xb_add(&bar[XB_XGEN(b.x)], 1u);
;             asm volatile("s_waitcnt vmcnt(0)" ::: "memory");
;         } else {
;             XB_SPIN(xb_ld(&bar[XB_XGEN(b.x)]) == gen, bar);
;             __builtin_amdgcn_fence(__ATOMIC_ACQUIRE, "agent");
;             asm volatile("s_waitcnt vmcnt(0)" ::: "memory");
;         }
;     }
;     __syncthreads();
; }
; __global__ void __launch_bounds__(NTHREADS, 2) mega_fwd(Args args) {
;     ...
;     const XcdBarrier xbar = xcd_barrier_post((unsigned*)(args.ws + WS_BAR), (volatile LAS unsigned*)(lds + XB_ST_OFF), wave);
; #pragma unroll 1
;     for (int l = 0; l < DEPTH; ++l) {
.LBB0_201:
	s_or_b64 exec, exec, s[4:5]
	s_load_dwordx4 s[12:15], s[0:1], 0x88
	s_load_dword s5, s[0:1], 0x98
	v_add_u32_e32 v0, 64, v74
	v_cmp_lt_i32_e32 vcc, v73, v0
	v_mov_b32_e32 v220, 0x358637bd
	s_waitcnt lgkmcnt(0)
	s_mul_i32 s4, s15, s14
	s_mul_i32 s36, s4, s5
	s_add_u32 s4, s12, 0x80200
	s_addc_u32 s5, s13, 0
	s_add_u32 s58, s12, 0x80400
	v_writelane_b32 v254, s4, 4
	s_addc_u32 s59, s13, 0
	v_cndmask_b32_e32 v1, v211, v73, vcc
	v_writelane_b32 v254, s5, 5
	s_add_u32 s4, s12, 0x80500
	s_addc_u32 s5, s13, 0
	v_writelane_b32 v254, s4, 6
	v_cmp_lt_i32_e32 vcc, v72, v0
	v_lshlrev_b32_e32 v218, 2, v1
	v_writelane_b32 v254, s5, 7
	s_add_u32 s4, s12, 0x80600
	s_addc_u32 s5, s13, 0
	v_writelane_b32 v254, s4, 8
	v_cndmask_b32_e32 v0, v211, v72, vcc
	v_lshlrev_b32_e32 v219, 2, v0
	v_writelane_b32 v254, s5, 9
	s_add_u32 s4, s12, 0x80700
	s_addc_u32 s5, s13, 0
	v_writelane_b32 v254, s4, 10
	s_movk_i32 s33, 0x2000
	v_mov_b32_e32 v97, 0
	v_writelane_b32 v254, s5, 11
	s_add_u32 s4, s12, 0x80800
	s_addc_u32 s5, s13, 0
	v_writelane_b32 v254, s4, 12
	s_mov_b32 s62, 0xffff0000
	s_movk_i32 s63, 0x2c00
	v_writelane_b32 v254, s5, 13
	s_add_u32 s4, s12, 0x80900
	s_addc_u32 s5, s13, 0
	v_writelane_b32 v254, s4, 14
	v_mov_b32_e32 v221, 1
	v_mov_b64_e32 v[194:195], 0x57f
	v_writelane_b32 v254, s5, 15
	s_add_u32 s4, s12, 0x80a00
	s_addc_u32 s5, s13, 0
	v_writelane_b32 v254, s4, 16
	v_mov_b64_e32 v[252:253], 0x580
	v_mov_b64_e32 v[200:201], 0xff
	v_writelane_b32 v254, s5, 17
	s_add_u32 s4, s12, 0x80b00
	s_addc_u32 s5, s13, 0
	v_writelane_b32 v254, s4, 18
	v_mov_b32_e32 v222, 0xff800000
	v_mov_b32_e32 v223, 0x42800000
	v_writelane_b32 v254, s5, 19
	s_add_u32 s4, s12, 0x80c00
	s_addc_u32 s5, s13, 0
	v_writelane_b32 v254, s4, 20
	v_not_b32_e32 v224, 63
	v_mov_b32_e32 v225, 0x1fff
	v_writelane_b32 v254, s5, 21
	s_add_u32 s4, s12, 0x80d00
	s_addc_u32 s5, s13, 0
	v_writelane_b32 v254, s4, 22
	s_mov_b64 s[34:35], 0
	s_mov_b64 s[22:23], 0x80
	v_writelane_b32 v254, s5, 23
	s_add_u32 s4, s12, 0x80e00
	s_addc_u32 s5, s13, 0
	v_writelane_b32 v254, s4, 24
	s_mov_b64 s[24:25], 0x100
	s_mov_b32 s56, s77
	v_writelane_b32 v254, s5, 25
	s_add_u32 s4, s12, 0x80f00
	s_addc_u32 s5, s13, 0
	v_writelane_b32 v254, s4, 26
	s_nop 1
	v_writelane_b32 v254, s5, 27
	s_add_u32 s4, s12, 0x81000
	s_addc_u32 s5, s13, 0
	v_writelane_b32 v254, s4, 28
	s_nop 1
	v_writelane_b32 v254, s5, 29
	s_add_u32 s4, s12, 0x81100
	s_addc_u32 s5, s13, 0
	v_writelane_b32 v254, s4, 30
	s_nop 1
	v_writelane_b32 v254, s5, 31
	s_add_u32 s4, s12, 0x81200
	s_addc_u32 s5, s13, 0
	v_writelane_b32 v254, s4, 32
	s_nop 1
	v_writelane_b32 v254, s5, 33
	s_add_u32 s4, s12, 0x81300
	s_addc_u32 s5, s13, 0
	v_writelane_b32 v254, s4, 34
	s_cmp_eq_u32 s8, 15
	s_nop 0
	v_writelane_b32 v254, s5, 35
	s_cselect_b64 s[4:5], -1, 0
	v_writelane_b32 v254, s4, 36
	s_cmp_eq_u32 s8, 14
	s_nop 0
	v_writelane_b32 v254, s5, 37
	s_cselect_b64 s[4:5], -1, 0
	v_writelane_b32 v254, s4, 38
	s_cmp_eq_u32 s8, 13
	s_nop 0
	v_writelane_b32 v254, s5, 39
	s_cselect_b64 s[4:5], -1, 0
	v_writelane_b32 v254, s4, 40
	s_cmp_eq_u32 s8, 12
	s_nop 0
	v_writelane_b32 v254, s5, 41
	s_cselect_b64 s[4:5], -1, 0
	v_writelane_b32 v254, s4, 42
	s_cmp_eq_u32 s8, 11
	s_nop 0
	v_writelane_b32 v254, s5, 43
	s_cselect_b64 s[4:5], -1, 0
	v_writelane_b32 v254, s4, 44
	s_cmp_eq_u32 s8, 10
	s_nop 0
	v_writelane_b32 v254, s5, 45
	s_cselect_b64 s[4:5], -1, 0
	v_writelane_b32 v254, s4, 46
	s_cmp_eq_u32 s8, 9
	s_nop 0
	v_writelane_b32 v254, s5, 47
	s_cselect_b64 s[4:5], -1, 0
	v_writelane_b32 v254, s4, 48
	s_cmp_eq_u32 s8, 8
	s_nop 0
	v_writelane_b32 v254, s5, 49
	s_cselect_b64 s[4:5], -1, 0
	v_writelane_b32 v254, s4, 50
	s_cmp_eq_u32 s8, 7
	s_nop 0
	v_writelane_b32 v254, s5, 51
	s_cselect_b64 s[4:5], -1, 0
	v_writelane_b32 v254, s4, 52
	s_cmp_eq_u32 s8, 6
	s_nop 0
	v_writelane_b32 v254, s5, 53
	s_cselect_b64 s[4:5], -1, 0
	v_writelane_b32 v254, s4, 54
	s_cmp_eq_u32 s8, 5
	s_nop 0
	v_writelane_b32 v254, s5, 55
	s_cselect_b64 s[4:5], -1, 0
	v_writelane_b32 v254, s4, 56
	s_cmp_eq_u32 s8, 4
	s_nop 0
	v_writelane_b32 v254, s5, 57
	s_cselect_b64 s[4:5], -1, 0
	v_writelane_b32 v254, s4, 58
	s_cmp_eq_u32 s8, 3
	s_nop 0
	v_writelane_b32 v254, s5, 59
	s_cselect_b64 s[4:5], -1, 0
	v_writelane_b32 v254, s4, 60
	s_cmp_eq_u32 s8, 2
	s_nop 0
	v_writelane_b32 v254, s5, 61
	s_cselect_b64 s[4:5], -1, 0
	v_writelane_b32 v254, s4, 62
	s_cmp_eq_u32 s8, 1
	s_nop 0
	v_writelane_b32 v254, s5, 63
	s_cselect_b64 s[4:5], -1, 0
	v_writelane_b32 v255, s4, 0
	s_cmp_eq_u32 s8, 0
	s_nop 0
	v_writelane_b32 v255, s5, 1
	s_cselect_b64 s[4:5], -1, 0
	v_writelane_b32 v255, s4, 2
	s_nop 1
	v_writelane_b32 v255, s5, 3
	s_lshl_b32 s4, s9, 2
	s_add_u32 s2, s2, s4
	s_addc_u32 s3, s3, 0
	s_add_u32 s4, s2, 0x1400
	s_addc_u32 s5, s3, 0
	v_writelane_b32 v255, s4, 4
	s_add_u32 s2, s2, 0x2400
	s_addc_u32 s3, s3, 0
	v_writelane_b32 v255, s5, 5
	v_writelane_b32 v255, s2, 6
	s_load_dwordx2 s[20:21], s[0:1], 0x80
	s_load_dwordx4 s[8:11], s[0:1], 0x38
	v_writelane_b32 v255, s0, 62
	v_writelane_b32 v255, s1, 63
	v_writelane_b32 v255, s3, 7
	s_add_u32 s2, s12, 0x83400
	s_addc_u32 s3, s13, 0
	v_writelane_b32 v255, s2, 8
	s_movk_i32 s4, 0x81
	s_movk_i32 s5, 0x7fff
	v_writelane_b32 v255, s3, 9
	s_add_u32 s2, s12, 0x83500
	s_addc_u32 s3, s13, 0
	v_writelane_b32 v255, s2, 10
	s_nop 1
	v_writelane_b32 v255, s3, 11
	s_add_i32 s2, 0, 0x26440
	v_writelane_b32 v255, s2, 12
	s_add_i32 s2, 0, 0x26444
	v_writelane_b32 v255, s2, 13
	s_waitcnt lgkmcnt(0)
	v_writelane_b32 v255, s8, 14
	s_mov_b64 s[2:3], -1
	s_nop 0
	v_writelane_b32 v255, s9, 15
	v_writelane_b32 v255, s10, 16
	v_writelane_b32 v255, s11, 17
	v_writelane_b32 v255, s72, 18
	v_writelane_b32 v255, s73, 19
	v_writelane_b32 v255, s78, 20
	s_nop 1
	v_writelane_b32 v255, s79, 21
	v_writelane_b32 v255, s36, 22
	v_writelane_b32 v255, s58, 23
	s_nop 1
	v_writelane_b32 v255, s59, 24
	s_cmp_ge_u32 s73, 4
	s_cbranch_scc0 .Lprio_done
	s_setprio 1
.Lprio_done:
	s_branch .LBB0_205
.LBB0_202:
	s_or_b64 exec, exec, s[14:15]
	s_waitcnt vmcnt(0)

; #define PG8_STAGE(bufoff, gbase, voff) do { _Pragma("unroll") for (int _i = 0; _i < 2; ++_i) \
;         __builtin_amdgcn_global_load_lds((const unsigned*)((const char*)(gbase) + (voff)[_i]), (PG8_LAS unsigned*)(lds + (bufoff) + ldsw + _i * 8192), 16, 0, 0); } while (0)
; #define PG8_LDA(dst, b, h) do { _Pragma("unroll") for (int m = 0; m < 4; ++m) _Pragma("unroll") for (int k = 0; k < 2; ++k) dst[m][k] = *(const PG8_LAS bf16x8*)(lds + PG8_SA(b, h) + aoff + m * 2048 + k * 1024); } while (0)
; #define PG8_LDB(dst, b, h) do { _Pragma("unroll") for (int n = 0; n < 2; ++n) _Pragma("unroll") for (int k = 0; k < 2; ++k) dst[n][k] = *(const PG8_LAS bf16x8*)(lds + PG8_SB(b, h) + boff + n * 2048 + k * 1024); } while (0)
; #define PG8_MMA(ai, bj, At, Bt) do { __builtin_amdgcn_s_setprio(1); _Pragma("unroll") for (int m = 0; m < 4; ++m) _Pragma("unroll") for (int n = 0; n < 2; ++n) _Pragma("unroll") for (int k = 0; k < 2; ++k) \
;         acc[ai][bj][m][n] = __builtin_amdgcn_mfma_f32_16x16x32_bf16(Bt[n][k], At[m][k], acc[ai][bj][m][n], 0, 0, 0); __builtin_amdgcn_s_setprio(0); } while (0)
; #define PG8_WAIT_V(n) asm volatile("s_waitcnt vmcnt(" #n ")" ::: "memory")
; #define PG8_BAR __builtin_amdgcn_s_barrier()
; template <class Epi, class Sched, bool ALIGN_EPI, bool SP2, int KK, int LDA, int APN>
; __device__ __forceinline__ void gemm_phase(PG8_LAS unsigned char* lds, const Gemm g, const Sched& S, const Epi& E, const int wid) {
;     ...
;         for (int t = 0; t < nt; t += 2) {
;             const bool last = (t == nt - 2);
;             const char* a1 = cA + (size_t)(t + 1) * kstep;
;             const char* a2 = last ? nA : cA + (size_t)(t + 2) * kstep; const char* b2 = last ? nB : cB + (size_t)(t + 2) * kstep;
;             const char* a3 = a2 + kstep; const char* b3 = b2 + kstep;
;             if (last && has_next) S.a_ready(nxt);
;             if constexpr (SP2) {
;             PG8_LDB(B0, 0, 0); PG8_LDB(B1, 0, 1); PG8_SCHED; PG8_LDA(At, 0, 0); PG8_STAGE(PG8_SA(1, 1), a1 + hstepA, voffA);
;             PG8_WAIT_V(8); PG8_WAIT_L(0); PG8_BAR; PG8_MMA(0, 0, At, B0); PG8_MMA(0, 1, At, B1); PG8_BAR; PG8_SCHED;
;             PG8_LDA(At, 0, 1); PG8_STAGE(PG8_SB(0, 0), b2, voffB); PG8_STAGE(PG8_SB(0, 1), b2 + hstep, voffB); PG8_STAGE(PG8_SA(0, 0), a2, voffA);
;             PG8_WAIT_V(8); PG8_WAIT_L(0); PG8_BAR; PG8_MMA(1, 0, At, B0); PG8_MMA(1, 1, At, B1); PG8_BAR; PG8_SCHED;
.LBB0_220:
	s_add_u32 s44, s30, 0xfff80080
	s_addc_u32 s45, s31, -1
	s_add_i32 s67, 0, 0x10000
	s_cmp_eq_u32 s66, 28
	s_cselect_b32 s47, s37, s45
	s_cselect_b32 s46, s60, s44
	v_add_u32_e32 v140, s67, v143
	s_cselect_b32 s45, s27, s65
	s_cselect_b32 s44, s61, s64
	s_add_i32 s70, 0, 0x14000
	ds_read_b128 v[148:151], v140
	ds_read_b128 v[152:155], v140 offset:1024
	ds_read_b128 v[156:159], v140 offset:2048
	ds_read_b128 v[160:163], v140 offset:3072
	v_add_u32_e32 v140, s70, v143
	ds_read_b128 v[164:167], v140
	ds_read_b128 v[168:171], v140 offset:1024
	ds_read_b128 v[172:175], v140 offset:2048
	ds_read_b128 v[176:179], v140 offset:3072
	v_lshl_add_u64 v[140:141], s[30:31], 0, v[138:139]
	s_add_i32 m0, s51, 0xc000
	ds_read_b128 v[180:183], v146
	ds_read_b128 v[184:187], v146 offset:1024
	ds_read_b128 v[188:191], v146 offset:2048
	ds_read_b128 v[202:205], v146 offset:3072
	ds_read_b128 v[206:209], v146 offset:4096
	ds_read_b128 v[212:215], v146 offset:5120
	ds_read_b128 v[226:229], v146 offset:6144
	ds_read_b128 v[230:233], v146 offset:7168
	global_load_lds_dwordx4 v[140:141], off
	v_lshl_add_u64 v[140:141], s[30:31], 0, v[136:137]
	s_add_i32 m0, s51, 0xe000
	s_nop 0
	global_load_lds_dwordx4 v[140:141], off
	s_waitcnt vmcnt(8)
	s_waitcnt lgkmcnt(0)
	s_barrier
	v_mfma_f32_16x16x32_bf16 v[126:129], v[148:151], v[180:183], v[126:129]
	v_mfma_f32_16x16x32_bf16 v[118:121], v[156:159], v[180:183], v[118:121]
	v_mfma_f32_16x16x32_bf16 v[110:113], v[148:151], v[188:191], v[110:113]
	v_mfma_f32_16x16x32_bf16 v[102:105], v[156:159], v[188:191], v[102:105]
	v_mfma_f32_16x16x32_bf16 v[92:95], v[148:151], v[206:209], v[92:95]
	v_mfma_f32_16x16x32_bf16 v[84:87], v[156:159], v[206:209], v[84:87]
	v_mfma_f32_16x16x32_bf16 v[76:79], v[148:151], v[226:229], v[76:79]
	v_mfma_f32_16x16x32_bf16 v[68:71], v[156:159], v[226:229], v[68:71]
	v_mfma_f32_16x16x32_bf16 v[126:129], v[152:155], v[184:187], v[126:129]
	v_mfma_f32_16x16x32_bf16 v[118:121], v[160:163], v[184:187], v[118:121]
	v_mfma_f32_16x16x32_bf16 v[110:113], v[152:155], v[202:205], v[110:113]
	v_mfma_f32_16x16x32_bf16 v[102:105], v[160:163], v[202:205], v[102:105]
	v_mfma_f32_16x16x32_bf16 v[92:95], v[152:155], v[212:215], v[92:95]
	v_mfma_f32_16x16x32_bf16 v[84:87], v[160:163], v[212:215], v[84:87]
	v_mfma_f32_16x16x32_bf16 v[76:79], v[152:155], v[230:233], v[76:79]
	v_mfma_f32_16x16x32_bf16 v[68:71], v[160:163], v[230:233], v[68:71]
	v_mfma_f32_16x16x32_bf16 v[122:125], v[164:167], v[180:183], v[122:125]
	v_mfma_f32_16x16x32_bf16 v[114:117], v[172:175], v[180:183], v[114:117]
	v_mfma_f32_16x16x32_bf16 v[106:109], v[164:167], v[188:191], v[106:109]
	v_mfma_f32_16x16x32_bf16 v[98:101], v[172:175], v[188:191], v[98:101]
	v_mfma_f32_16x16x32_bf16 v[88:91], v[164:167], v[206:209], v[88:91]
	v_mfma_f32_16x16x32_bf16 v[80:83], v[172:175], v[206:209], v[80:83]
	v_mfma_f32_16x16x32_bf16 v[72:75], v[164:167], v[226:229], v[72:75]
	v_mfma_f32_16x16x32_bf16 v[64:67], v[172:175], v[226:229], v[64:67]
	v_mfma_f32_16x16x32_bf16 v[122:125], v[168:171], v[184:187], v[122:125]
	v_mfma_f32_16x16x32_bf16 v[114:117], v[176:179], v[184:187], v[114:117]
	v_mfma_f32_16x16x32_bf16 v[106:109], v[168:171], v[202:205], v[106:109]
	v_mfma_f32_16x16x32_bf16 v[98:101], v[176:179], v[202:205], v[98:101]
	v_mfma_f32_16x16x32_bf16 v[88:91], v[168:171], v[212:215], v[88:91]
	v_mfma_f32_16x16x32_bf16 v[80:83], v[176:179], v[212:215], v[80:83]
	v_mfma_f32_16x16x32_bf16 v[72:75], v[168:171], v[230:233], v[72:75]
	v_mfma_f32_16x16x32_bf16 v[64:67], v[176:179], v[230:233], v[64:67]
	s_barrier
	s_add_i32 s67, s67, s48
	v_lshl_add_u64 v[140:141], s[44:45], 0, v[96:97]
	s_mov_b32 m0, s67
	ds_read_b128 v[180:183], v146 offset:16384
	ds_read_b128 v[184:187], v146 offset:17408
	ds_read_b128 v[188:191], v146 offset:18432
	ds_read_b128 v[202:205], v146 offset:19456
	ds_read_b128 v[206:209], v146 offset:20480
	ds_read_b128 v[212:215], v146 offset:21504
	ds_read_b128 v[226:229], v146 offset:22528
	ds_read_b128 v[230:233], v146 offset:23552
	global_load_lds_dwordx4 v[140:141], off
	s_add_i32 m0, s67, 0x2000
	s_add_u32 s68, s44, 0x80000
	v_lshl_add_u64 v[192:193], s[44:45], 0, v[134:135]
	s_addc_u32 s69, s45, 0
	s_add_i32 s67, s70, s48
	global_load_lds_dwordx4 v[192:193], off
	v_lshl_add_u64 v[196:197], s[68:69], 0, v[96:97]
	s_mov_b32 m0, s67
	v_lshl_add_u64 v[198:199], s[46:47], 0, v[132:133]
	global_load_lds_dwordx4 v[196:197], off
	v_lshl_add_u64 v[196:197], s[68:69], 0, v[134:135]
	s_add_i32 m0, s67, 0x2000
	s_nop 0
	global_load_lds_dwordx4 v[196:197], off
	v_lshl_add_u64 v[196:197], s[46:47], 0, v[130:131]
	s_mov_b32 m0, s51
	s_nop 0
	global_load_lds_dwordx4 v[196:197], off
	s_mov_b32 m0, s52
	s_nop 0
	global_load_lds_dwordx4 v[198:199], off
	s_waitcnt vmcnt(8)
	s_waitcnt lgkmcnt(0)
	s_barrier
; #define PG8_STAGE(bufoff, gbase, voff) do { _Pragma("unroll") for (int _i = 0; _i < 2; ++_i) \
;         __builtin_amdgcn_global_load_lds((const unsigned*)((const char*)(gbase) + (voff)[_i]), (PG8_LAS unsigned*)(lds + (bufoff) + ldsw + _i * 8192), 16, 0, 0); } while (0)
; #define PG8_LDA(dst, b, h) do { _Pragma("unroll") for (int m = 0; m < 4; ++m) _Pragma("unroll") for (int k = 0; k < 2; ++k) dst[m][k] = *(const PG8_LAS bf16x8*)(lds + PG8_SA(b, h) + aoff + m * 2048 + k * 1024); } while (0)
; #define PG8_LDB(dst, b, h) do { _Pragma("unroll") for (int n = 0; n < 2; ++n) _Pragma("unroll") for (int k = 0; k < 2; ++k) dst[n][k] = *(const PG8_LAS bf16x8*)(lds + PG8_SB(b, h) + boff + n * 2048 + k * 1024); } while (0)
; #define PG8_MMA(ai, bj, At, Bt) do { __builtin_amdgcn_s_setprio(1); _Pragma("unroll") for (int m = 0; m < 4; ++m) _Pragma("unroll") for (int n = 0; n < 2; ++n) _Pragma("unroll") for (int k = 0; k < 2; ++k) \
;         acc[ai][bj][m][n] = __builtin_amdgcn_mfma_f32_16x16x32_bf16(Bt[n][k], At[m][k], acc[ai][bj][m][n], 0, 0, 0); __builtin_amdgcn_s_setprio(0); } while (0)
; #define PG8_WAIT_V(n) asm volatile("s_waitcnt vmcnt(" #n ")" ::: "memory")
; #define PG8_WAIT_L(n) asm volatile("s_waitcnt lgkmcnt(" #n ")" ::: "memory")
; #define PG8_BAR __builtin_amdgcn_s_barrier()
; #define PG8_SCHED __builtin_amdgcn_sched_barrier(0)
; template <class Epi, class Sched, bool ALIGN_EPI, bool SP2, int KK, int LDA, int APN>
; __device__ __forceinline__ void gemm_phase(PG8_LAS unsigned char* lds, const Gemm g, const Sched& S, const Epi& E, const int wid) {
;     ...
;             PG8_WAIT_V(8); PG8_WAIT_L(0); PG8_BAR; PG8_MMA(1, 0, At, B0); PG8_MMA(1, 1, At, B1); PG8_BAR; PG8_SCHED;
;             PG8_LDB(B0, 1, 0); PG8_LDB(B1, 1, 1); PG8_SCHED; PG8_LDA(At, 1, 0); PG8_STAGE(PG8_SA(0, 1), a2 + hstepA, voffA);
;             PG8_WAIT_V(8); PG8_WAIT_L(0); PG8_BAR; PG8_MMA(0, 0, At, B0); PG8_MMA(0, 1, At, B1); PG8_BAR; PG8_SCHED;
;             PG8_LDA(At, 1, 1); PG8_STAGE(PG8_SB(1, 0), b3, voffB); PG8_STAGE(PG8_SB(1, 1), b3 + hstep, voffB); PG8_STAGE(PG8_SA(1, 0), a3, voffA);
	v_mfma_f32_16x16x32_bf16 v[60:63], v[148:151], v[180:183], v[60:63]
	v_mfma_f32_16x16x32_bf16 v[52:55], v[156:159], v[180:183], v[52:55]
	v_mfma_f32_16x16x32_bf16 v[44:47], v[148:151], v[188:191], v[44:47]
	v_mfma_f32_16x16x32_bf16 v[36:39], v[156:159], v[188:191], v[36:39]
	v_mfma_f32_16x16x32_bf16 v[28:31], v[148:151], v[206:209], v[28:31]
	v_mfma_f32_16x16x32_bf16 v[20:23], v[156:159], v[206:209], v[20:23]
	v_mfma_f32_16x16x32_bf16 v[12:15], v[148:151], v[226:229], v[12:15]
	v_mfma_f32_16x16x32_bf16 v[4:7], v[156:159], v[226:229], v[4:7]
	v_mfma_f32_16x16x32_bf16 v[60:63], v[152:155], v[184:187], v[60:63]
	v_mfma_f32_16x16x32_bf16 v[52:55], v[160:163], v[184:187], v[52:55]
	v_mfma_f32_16x16x32_bf16 v[44:47], v[152:155], v[202:205], v[44:47]
	v_mfma_f32_16x16x32_bf16 v[36:39], v[160:163], v[202:205], v[36:39]
	v_mfma_f32_16x16x32_bf16 v[28:31], v[152:155], v[212:215], v[28:31]
	v_mfma_f32_16x16x32_bf16 v[20:23], v[160:163], v[212:215], v[20:23]
	v_mfma_f32_16x16x32_bf16 v[12:15], v[152:155], v[230:233], v[12:15]
	v_mfma_f32_16x16x32_bf16 v[4:7], v[160:163], v[230:233], v[4:7]
	v_mfma_f32_16x16x32_bf16 v[56:59], v[164:167], v[180:183], v[56:59]
	v_mfma_f32_16x16x32_bf16 v[48:51], v[172:175], v[180:183], v[48:51]
	v_mfma_f32_16x16x32_bf16 v[40:43], v[164:167], v[188:191], v[40:43]
	v_mfma_f32_16x16x32_bf16 v[32:35], v[172:175], v[188:191], v[32:35]
	v_mfma_f32_16x16x32_bf16 v[24:27], v[164:167], v[206:209], v[24:27]
	v_mfma_f32_16x16x32_bf16 v[16:19], v[172:175], v[206:209], v[16:19]
	v_mfma_f32_16x16x32_bf16 v[8:11], v[164:167], v[226:229], v[8:11]
	v_mfma_f32_16x16x32_bf16 v[0:3], v[172:175], v[226:229], v[0:3]
	v_mfma_f32_16x16x32_bf16 v[56:59], v[168:171], v[184:187], v[56:59]
	v_mfma_f32_16x16x32_bf16 v[48:51], v[176:179], v[184:187], v[48:51]
	v_mfma_f32_16x16x32_bf16 v[40:43], v[168:171], v[202:205], v[40:43]
	v_mfma_f32_16x16x32_bf16 v[32:35], v[176:179], v[202:205], v[32:35]
	v_mfma_f32_16x16x32_bf16 v[24:27], v[168:171], v[212:215], v[24:27]
	v_mfma_f32_16x16x32_bf16 v[16:19], v[176:179], v[212:215], v[16:19]
	v_mfma_f32_16x16x32_bf16 v[8:11], v[168:171], v[230:233], v[8:11]
	v_mfma_f32_16x16x32_bf16 v[0:3], v[176:179], v[230:233], v[0:3]
	s_barrier
	s_add_i32 s67, 0, 0x18000
	v_add_u32_e32 v147, s67, v143
	s_add_i32 s68, 0, 0x1c000
	ds_read_b128 v[148:151], v147
	ds_read_b128 v[152:155], v147 offset:1024
	ds_read_b128 v[156:159], v147 offset:2048
	ds_read_b128 v[160:163], v147 offset:3072
	v_add_u32_e32 v147, s68, v143
	ds_read_b128 v[164:167], v147
	ds_read_b128 v[168:171], v147 offset:1024
	ds_read_b128 v[172:175], v147 offset:2048
	ds_read_b128 v[176:179], v147 offset:3072
	s_add_u32 s46, s46, 0x80000
	s_addc_u32 s47, s47, 0
	s_mov_b32 m0, s53
	v_lshl_add_u64 v[216:217], s[46:47], 0, v[130:131]
	ds_read_b128 v[180:183], v146 offset:32768
	ds_read_b128 v[184:187], v146 offset:33792
	ds_read_b128 v[188:191], v146 offset:34816
	ds_read_b128 v[202:205], v146 offset:35840
	ds_read_b128 v[206:209], v146 offset:36864
	ds_read_b128 v[212:215], v146 offset:37888
	ds_read_b128 v[226:229], v146 offset:38912
	ds_read_b128 v[230:233], v146 offset:39936
	global_load_lds_dwordx4 v[216:217], off
	v_lshl_add_u64 v[216:217], s[46:47], 0, v[132:133]
	s_mov_b32 m0, s54
	s_nop 0
	global_load_lds_dwordx4 v[216:217], off
	s_waitcnt vmcnt(8)
	s_waitcnt lgkmcnt(0)
	s_barrier
	v_mfma_f32_16x16x32_bf16 v[126:129], v[148:151], v[180:183], v[126:129]
	v_mfma_f32_16x16x32_bf16 v[118:121], v[156:159], v[180:183], v[118:121]
	v_mfma_f32_16x16x32_bf16 v[110:113], v[148:151], v[188:191], v[110:113]
	v_mfma_f32_16x16x32_bf16 v[102:105], v[156:159], v[188:191], v[102:105]
	v_mfma_f32_16x16x32_bf16 v[92:95], v[148:151], v[206:209], v[92:95]
	v_mfma_f32_16x16x32_bf16 v[84:87], v[156:159], v[206:209], v[84:87]
	v_mfma_f32_16x16x32_bf16 v[76:79], v[148:151], v[226:229], v[76:79]
	v_mfma_f32_16x16x32_bf16 v[68:71], v[156:159], v[226:229], v[68:71]
	v_mfma_f32_16x16x32_bf16 v[126:129], v[152:155], v[184:187], v[126:129]
	v_mfma_f32_16x16x32_bf16 v[118:121], v[160:163], v[184:187], v[118:121]
	v_mfma_f32_16x16x32_bf16 v[110:113], v[152:155], v[202:205], v[110:113]
	v_mfma_f32_16x16x32_bf16 v[102:105], v[160:163], v[202:205], v[102:105]
	v_mfma_f32_16x16x32_bf16 v[92:95], v[152:155], v[212:215], v[92:95]
	v_mfma_f32_16x16x32_bf16 v[84:87], v[160:163], v[212:215], v[84:87]
	v_mfma_f32_16x16x32_bf16 v[76:79], v[152:155], v[230:233], v[76:79]
	v_mfma_f32_16x16x32_bf16 v[68:71], v[160:163], v[230:233], v[68:71]
	v_mfma_f32_16x16x32_bf16 v[122:125], v[164:167], v[180:183], v[122:125]
	v_mfma_f32_16x16x32_bf16 v[114:117], v[172:175], v[180:183], v[114:117]
	v_mfma_f32_16x16x32_bf16 v[106:109], v[164:167], v[188:191], v[106:109]
	v_mfma_f32_16x16x32_bf16 v[98:101], v[172:175], v[188:191], v[98:101]
	v_mfma_f32_16x16x32_bf16 v[88:91], v[164:167], v[206:209], v[88:91]
	v_mfma_f32_16x16x32_bf16 v[80:83], v[172:175], v[206:209], v[80:83]
	v_mfma_f32_16x16x32_bf16 v[72:75], v[164:167], v[226:229], v[72:75]
	v_mfma_f32_16x16x32_bf16 v[64:67], v[172:175], v[226:229], v[64:67]
	v_mfma_f32_16x16x32_bf16 v[122:125], v[168:171], v[184:187], v[122:125]
	v_mfma_f32_16x16x32_bf16 v[114:117], v[176:179], v[184:187], v[114:117]
	v_mfma_f32_16x16x32_bf16 v[106:109], v[168:171], v[202:205], v[106:109]
	v_mfma_f32_16x16x32_bf16 v[98:101], v[176:179], v[202:205], v[98:101]
	v_mfma_f32_16x16x32_bf16 v[88:91], v[168:171], v[212:215], v[88:91]
	v_mfma_f32_16x16x32_bf16 v[80:83], v[176:179], v[212:215], v[80:83]
	v_mfma_f32_16x16x32_bf16 v[72:75], v[168:171], v[230:233], v[72:75]
	v_mfma_f32_16x16x32_bf16 v[64:67], v[176:179], v[230:233], v[64:67]
	s_barrier
; #define PG8_STAGE(bufoff, gbase, voff) do { _Pragma("unroll") for (int _i = 0; _i < 2; ++_i) \
;         __builtin_amdgcn_global_load_lds((const unsigned*)((const char*)(gbase) + (voff)[_i]), (PG8_LAS unsigned*)(lds + (bufoff) + ldsw + _i * 8192), 16, 0, 0); } while (0)
; #define PG8_LDA(dst, b, h) do { _Pragma("unroll") for (int m = 0; m < 4; ++m) _Pragma("unroll") for (int k = 0; k < 2; ++k) dst[m][k] = *(const PG8_LAS bf16x8*)(lds + PG8_SA(b, h) + aoff + m * 2048 + k * 1024); } while (0)
; #define PG8_MMA(ai, bj, At, Bt) do { __builtin_amdgcn_s_setprio(1); _Pragma("unroll") for (int m = 0; m < 4; ++m) _Pragma("unroll") for (int n = 0; n < 2; ++n) _Pragma("unroll") for (int k = 0; k < 2; ++k) \
;         acc[ai][bj][m][n] = __builtin_amdgcn_mfma_f32_16x16x32_bf16(Bt[n][k], At[m][k], acc[ai][bj][m][n], 0, 0, 0); __builtin_amdgcn_s_setprio(0); } while (0)
; #define PG8_WAIT_V(n) asm volatile("s_waitcnt vmcnt(" #n ")" ::: "memory")
; #define PG8_WAIT_L(n) asm volatile("s_waitcnt lgkmcnt(" #n ")" ::: "memory")
; #define PG8_BAR __builtin_amdgcn_s_barrier()
; #define PG8_SCHED __builtin_amdgcn_sched_barrier(0)
; template <class Epi, class Sched, bool ALIGN_EPI, bool SP2, int KK, int LDA, int APN>
; __device__ __forceinline__ void gemm_phase(PG8_LAS unsigned char* lds, const Gemm g, const Sched& S, const Epi& E, const int wid) {
;     ...
;             PG8_LDA(At, 1, 1); PG8_STAGE(PG8_SB(1, 0), b3, voffB); PG8_STAGE(PG8_SB(1, 1), b3 + hstep, voffB); PG8_STAGE(PG8_SA(1, 0), a3, voffA);
;             PG8_WAIT_V(8); PG8_WAIT_L(0); PG8_BAR; PG8_MMA(1, 0, At, B0); PG8_MMA(1, 1, At, B1); PG8_BAR; PG8_SCHED;
;     ...
;         }
;         if constexpr (ALIGN_EPI) { if (wr == 0) PG8_BAR; }
	s_add_i32 s46, s67, s48
	v_lshl_add_u64 v[140:141], v[140:141], 0, s[22:23]
	s_mov_b32 m0, s46
	ds_read_b128 v[180:183], v146 offset:49152
	ds_read_b128 v[184:187], v146 offset:50176
	ds_read_b128 v[188:191], v146 offset:51200
	ds_read_b128 v[202:205], v146 offset:52224
	ds_read_b128 v[206:209], v146 offset:53248
	ds_read_b128 v[212:215], v146 offset:54272
	ds_read_b128 v[226:229], v146 offset:55296
	ds_read_b128 v[230:233], v146 offset:56320
	global_load_lds_dwordx4 v[140:141], off
	s_add_i32 m0, s46, 0x2000
	s_add_u32 s44, s44, 0x80080
	v_lshl_add_u64 v[140:141], v[192:193], 0, s[22:23]
	s_addc_u32 s45, s45, 0
	s_add_i32 s46, s68, s48
	global_load_lds_dwordx4 v[140:141], off
	v_lshl_add_u64 v[140:141], s[44:45], 0, v[96:97]
	s_mov_b32 m0, s46
	s_nop 0
	global_load_lds_dwordx4 v[140:141], off
	v_lshl_add_u64 v[140:141], s[44:45], 0, v[134:135]
	s_add_i32 m0, s46, 0x2000
	s_nop 0
	global_load_lds_dwordx4 v[140:141], off
	v_lshl_add_u64 v[140:141], v[196:197], 0, s[22:23]
	s_mov_b32 m0, s55
	s_nop 0
	global_load_lds_dwordx4 v[140:141], off
	v_lshl_add_u64 v[140:141], v[198:199], 0, s[22:23]
	s_mov_b32 m0, s57
	s_nop 0
	global_load_lds_dwordx4 v[140:141], off
	s_waitcnt vmcnt(8)
	s_waitcnt lgkmcnt(0)
	s_barrier
	v_mfma_f32_16x16x32_bf16 v[60:63], v[148:151], v[180:183], v[60:63]
	v_mfma_f32_16x16x32_bf16 v[52:55], v[156:159], v[180:183], v[52:55]
	v_mfma_f32_16x16x32_bf16 v[44:47], v[148:151], v[188:191], v[44:47]
	v_mfma_f32_16x16x32_bf16 v[36:39], v[156:159], v[188:191], v[36:39]
	v_mfma_f32_16x16x32_bf16 v[28:31], v[148:151], v[206:209], v[28:31]
	v_mfma_f32_16x16x32_bf16 v[20:23], v[156:159], v[206:209], v[20:23]
	v_mfma_f32_16x16x32_bf16 v[12:15], v[148:151], v[226:229], v[12:15]
	v_mfma_f32_16x16x32_bf16 v[4:7], v[156:159], v[226:229], v[4:7]
	v_mfma_f32_16x16x32_bf16 v[60:63], v[152:155], v[184:187], v[60:63]
	v_mfma_f32_16x16x32_bf16 v[52:55], v[160:163], v[184:187], v[52:55]
	v_mfma_f32_16x16x32_bf16 v[44:47], v[152:155], v[202:205], v[44:47]
	v_mfma_f32_16x16x32_bf16 v[36:39], v[160:163], v[202:205], v[36:39]
	v_mfma_f32_16x16x32_bf16 v[28:31], v[152:155], v[212:215], v[28:31]
	v_mfma_f32_16x16x32_bf16 v[20:23], v[160:163], v[212:215], v[20:23]
	v_mfma_f32_16x16x32_bf16 v[12:15], v[152:155], v[230:233], v[12:15]
	v_mfma_f32_16x16x32_bf16 v[4:7], v[160:163], v[230:233], v[4:7]
	v_mfma_f32_16x16x32_bf16 v[56:59], v[164:167], v[180:183], v[56:59]
	v_mfma_f32_16x16x32_bf16 v[48:51], v[172:175], v[180:183], v[48:51]
	v_mfma_f32_16x16x32_bf16 v[40:43], v[164:167], v[188:191], v[40:43]
	v_mfma_f32_16x16x32_bf16 v[32:35], v[172:175], v[188:191], v[32:35]
	v_mfma_f32_16x16x32_bf16 v[24:27], v[164:167], v[206:209], v[24:27]
	v_mfma_f32_16x16x32_bf16 v[16:19], v[172:175], v[206:209], v[16:19]
	v_mfma_f32_16x16x32_bf16 v[8:11], v[164:167], v[226:229], v[8:11]
	v_mfma_f32_16x16x32_bf16 v[0:3], v[172:175], v[226:229], v[0:3]
	v_mfma_f32_16x16x32_bf16 v[56:59], v[168:171], v[184:187], v[56:59]
	v_mfma_f32_16x16x32_bf16 v[48:51], v[176:179], v[184:187], v[48:51]
	v_mfma_f32_16x16x32_bf16 v[40:43], v[168:171], v[202:205], v[40:43]
	v_mfma_f32_16x16x32_bf16 v[32:35], v[176:179], v[202:205], v[32:35]
	v_mfma_f32_16x16x32_bf16 v[24:27], v[168:171], v[212:215], v[24:27]
	v_mfma_f32_16x16x32_bf16 v[16:19], v[176:179], v[212:215], v[16:19]
	v_mfma_f32_16x16x32_bf16 v[8:11], v[168:171], v[230:233], v[8:11]
	v_mfma_f32_16x16x32_bf16 v[0:3], v[176:179], v[230:233], v[0:3]
	s_barrier
	s_add_i32 s66, s66, 2
	s_add_u32 s64, s64, 0x100
	s_addc_u32 s65, s65, 0
	s_add_u32 s30, s30, 0x100
	s_addc_u32 s31, s31, 0
	s_cmp_gt_u32 s66, 29
	s_cbranch_scc0 .LBB0_220
	s_and_b64 vcc, exec, s[18:19]
	s_cbranch_vccz .LBB0_223
	s_barrier

; #define PG8_STAGE(bufoff, gbase, voff) do { _Pragma("unroll") for (int _i = 0; _i < 2; ++_i) \
;         __builtin_amdgcn_global_load_lds((const unsigned*)((const char*)(gbase) + (voff)[_i]), (PG8_LAS unsigned*)(lds + (bufoff) + ldsw + _i * 8192), 16, 0, 0); } while (0)
; #define PG8_LDA(dst, b, h) do { _Pragma("unroll") for (int m = 0; m < 4; ++m) _Pragma("unroll") for (int k = 0; k < 2; ++k) dst[m][k] = *(const PG8_LAS bf16x8*)(lds + PG8_SA(b, h) + aoff + m * 2048 + k * 1024); } while (0)
; #define PG8_LDB(dst, b, h) do { _Pragma("unroll") for (int n = 0; n < 2; ++n) _Pragma("unroll") for (int k = 0; k < 2; ++k) dst[n][k] = *(const PG8_LAS bf16x8*)(lds + PG8_SB(b, h) + boff + n * 2048 + k * 1024); } while (0)
; #define PG8_MMA(ai, bj, At, Bt) do { __builtin_amdgcn_s_setprio(1); _Pragma("unroll") for (int m = 0; m < 4; ++m) _Pragma("unroll") for (int n = 0; n < 2; ++n) _Pragma("unroll") for (int k = 0; k < 2; ++k) \
;         acc[ai][bj][m][n] = __builtin_amdgcn_mfma_f32_16x16x32_bf16(Bt[n][k], At[m][k], acc[ai][bj][m][n], 0, 0, 0); __builtin_amdgcn_s_setprio(0); } while (0)
; #define PG8_WAIT_V(n) asm volatile("s_waitcnt vmcnt(" #n ")" ::: "memory")
; #define PG8_BAR __builtin_amdgcn_s_barrier()
; template <class Epi, class Sched, bool ALIGN_EPI, bool SP2, int KK, int LDA, int APN>
; __device__ __forceinline__ void gemm_phase(PG8_LAS unsigned char* lds, const Gemm g, const Sched& S, const Epi& E, const int wid) {
;     ...
;         for (int t = 0; t < nt; t += 2) {
;             const bool last = (t == nt - 2);
;             const char* a1 = cA + (size_t)(t + 1) * kstep;
;             const char* a2 = last ? nA : cA + (size_t)(t + 2) * kstep; const char* b2 = last ? nB : cB + (size_t)(t + 2) * kstep;
;             const char* a3 = a2 + kstep; const char* b3 = b2 + kstep;
;             if (last && has_next) S.a_ready(nxt);
;             if constexpr (SP2) {
;             PG8_LDB(B0, 0, 0); PG8_LDB(B1, 0, 1); PG8_SCHED; PG8_LDA(At, 0, 0); PG8_STAGE(PG8_SA(1, 1), a1 + hstepA, voffA);
;             PG8_WAIT_V(8); PG8_WAIT_L(0); PG8_BAR; PG8_MMA(0, 0, At, B0); PG8_MMA(0, 1, At, B1); PG8_BAR; PG8_SCHED;
;             PG8_LDA(At, 0, 1); PG8_STAGE(PG8_SB(0, 0), b2, voffB); PG8_STAGE(PG8_SB(0, 1), b2 + hstep, voffB); PG8_STAGE(PG8_SA(0, 0), a2, voffA);
;             PG8_WAIT_V(8); PG8_WAIT_L(0); PG8_BAR; PG8_MMA(1, 0, At, B0); PG8_MMA(1, 1, At, B1); PG8_BAR; PG8_SCHED;
.LBB0_231:
	s_add_u32 s36, s14, s26
	s_addc_u32 s37, s15, s27
	s_add_u32 s28, s36, 0x100
	s_addc_u32 s29, s37, 0
	s_and_b64 s[8:9], s[18:19], exec
	s_cselect_b32 s29, s15, s29
	s_cselect_b32 s28, s14, s28
	s_add_u32 s8, s2, s26
	s_addc_u32 s9, s3, s27
	s_add_u32 s26, s8, 0x100
	s_addc_u32 s27, s9, 0
	s_add_i32 s51, 0, 0x10000
	s_and_b64 s[8:9], s[18:19], exec
	s_cselect_b32 s31, s3, s27
	s_cselect_b32 s30, s2, s26
	s_add_i32 s19, 0, 0x14000
	s_add_u32 s38, s36, 0x80080
	s_addc_u32 s39, s37, 0
	s_add_i32 s50, s51, s48
	s_add_i32 m0, s10, 0xc000
	s_add_i32 s53, s10, 0xe000
	s_add_i32 s46, s50, 0x2000
	s_add_u32 s36, s30, 0x10000
	v_add_u32_e32 v152, s51, v138
	v_add_u32_e32 v168, s19, v138
	s_addc_u32 s37, s31, 0
	s_add_i32 s49, s19, s48
	ds_read_b128 v[140:143], v152
	ds_read_b128 v[144:147], v152 offset:1024
	ds_read_b128 v[148:151], v152 offset:2048
	ds_read_b128 v[152:155], v152 offset:3072
	ds_read_b128 v[156:159], v168
	ds_read_b128 v[160:163], v168 offset:1024
	ds_read_b128 v[164:167], v168 offset:2048
	ds_read_b128 v[168:171], v168 offset:3072
	s_add_i32 s47, s49, 0x2000
	s_add_i32 s45, 0, 0x18000
	s_add_i32 s44, 0, 0x1c000
	s_add_u32 s26, s28, 0x80000
	s_addc_u32 s27, s29, 0
	s_add_i32 s9, s45, s48
	s_add_i32 s8, s9, 0x2000
	s_add_u32 s18, s30, 0x10080
	s_addc_u32 s19, s31, 0
	s_add_i32 s52, s44, s48
	s_add_i32 s51, s52, 0x2000
	v_lshl_add_u64 v[192:193], s[38:39], 0, v[134:135]
	ds_read_b128 v[172:175], v139
	ds_read_b128 v[176:179], v139 offset:1024
	ds_read_b128 v[180:183], v139 offset:2048
	ds_read_b128 v[184:187], v139 offset:3072
	ds_read_b128 v[188:191], v139 offset:4096
	ds_read_b128 v[202:205], v139 offset:5120
	ds_read_b128 v[206:209], v139 offset:6144
	ds_read_b128 v[212:215], v139 offset:7168
	global_load_lds_dwordx4 v[192:193], off
	v_lshl_add_u64 v[192:193], s[38:39], 0, v[132:133]
	s_mov_b32 m0, s53
	s_nop 0
	global_load_lds_dwordx4 v[192:193], off
	s_waitcnt vmcnt(8)
	s_waitcnt lgkmcnt(0)
	s_barrier
	v_mfma_f32_16x16x32_bf16 v[126:129], v[140:143], v[172:175], v[126:129]
	v_mfma_f32_16x16x32_bf16 v[122:125], v[148:151], v[172:175], v[122:125]
	v_mfma_f32_16x16x32_bf16 v[118:121], v[140:143], v[180:183], v[118:121]
	v_mfma_f32_16x16x32_bf16 v[110:113], v[148:151], v[180:183], v[110:113]
	v_mfma_f32_16x16x32_bf16 v[102:105], v[140:143], v[188:191], v[102:105]
	v_mfma_f32_16x16x32_bf16 v[92:95], v[148:151], v[188:191], v[92:95]
	v_mfma_f32_16x16x32_bf16 v[84:87], v[140:143], v[206:209], v[84:87]
	v_mfma_f32_16x16x32_bf16 v[76:79], v[148:151], v[206:209], v[76:79]
	v_mfma_f32_16x16x32_bf16 v[126:129], v[144:147], v[176:179], v[126:129]
	v_mfma_f32_16x16x32_bf16 v[122:125], v[152:155], v[176:179], v[122:125]
	v_mfma_f32_16x16x32_bf16 v[118:121], v[144:147], v[184:187], v[118:121]
	v_mfma_f32_16x16x32_bf16 v[110:113], v[152:155], v[184:187], v[110:113]
	v_mfma_f32_16x16x32_bf16 v[102:105], v[144:147], v[202:205], v[102:105]
	v_mfma_f32_16x16x32_bf16 v[92:95], v[152:155], v[202:205], v[92:95]
	v_mfma_f32_16x16x32_bf16 v[84:87], v[144:147], v[212:215], v[84:87]
	v_mfma_f32_16x16x32_bf16 v[76:79], v[152:155], v[212:215], v[76:79]
	v_mfma_f32_16x16x32_bf16 v[114:117], v[156:159], v[172:175], v[114:117]
	v_mfma_f32_16x16x32_bf16 v[106:109], v[164:167], v[172:175], v[106:109]
	v_mfma_f32_16x16x32_bf16 v[98:101], v[156:159], v[180:183], v[98:101]
	v_mfma_f32_16x16x32_bf16 v[88:91], v[164:167], v[180:183], v[88:91]
	v_mfma_f32_16x16x32_bf16 v[80:83], v[156:159], v[188:191], v[80:83]
	v_mfma_f32_16x16x32_bf16 v[72:75], v[164:167], v[188:191], v[72:75]
	v_mfma_f32_16x16x32_bf16 v[68:71], v[156:159], v[206:209], v[68:71]
	v_mfma_f32_16x16x32_bf16 v[64:67], v[164:167], v[206:209], v[64:67]
	v_mfma_f32_16x16x32_bf16 v[114:117], v[160:163], v[176:179], v[114:117]
	v_mfma_f32_16x16x32_bf16 v[106:109], v[168:171], v[176:179], v[106:109]
	v_mfma_f32_16x16x32_bf16 v[98:101], v[160:163], v[184:187], v[98:101]
	v_mfma_f32_16x16x32_bf16 v[88:91], v[168:171], v[184:187], v[88:91]
	v_mfma_f32_16x16x32_bf16 v[80:83], v[160:163], v[202:205], v[80:83]
	v_mfma_f32_16x16x32_bf16 v[72:75], v[168:171], v[202:205], v[72:75]
	v_mfma_f32_16x16x32_bf16 v[68:71], v[160:163], v[212:215], v[68:71]
	v_mfma_f32_16x16x32_bf16 v[64:67], v[168:171], v[212:215], v[64:67]
	s_barrier
	s_mov_b32 m0, s50
	v_lshl_add_u64 v[192:193], s[30:31], 0, v[96:97]
	ds_read_b128 v[172:175], v139 offset:16384
	ds_read_b128 v[176:179], v139 offset:17408
	ds_read_b128 v[180:183], v139 offset:18432
	ds_read_b128 v[184:187], v139 offset:19456
	ds_read_b128 v[188:191], v139 offset:20480
	ds_read_b128 v[202:205], v139 offset:21504
	ds_read_b128 v[206:209], v139 offset:22528
	ds_read_b128 v[212:215], v139 offset:23552
	global_load_lds_dwordx4 v[192:193], off
	v_lshl_add_u64 v[196:197], s[30:31], 0, v[130:131]
	s_mov_b32 m0, s46
	v_lshl_add_u64 v[198:199], s[36:37], 0, v[96:97]
	global_load_lds_dwordx4 v[196:197], off
	s_mov_b32 m0, s49
	v_lshl_add_u64 v[216:217], s[28:29], 0, v[132:133]
	global_load_lds_dwordx4 v[198:199], off
	v_lshl_add_u64 v[198:199], s[36:37], 0, v[130:131]
	s_mov_b32 m0, s47
	s_nop 0
	global_load_lds_dwordx4 v[198:199], off
	v_lshl_add_u64 v[198:199], s[28:29], 0, v[134:135]
	s_mov_b32 m0, s10
	s_nop 0
	global_load_lds_dwordx4 v[198:199], off
	s_mov_b32 m0, s11
	s_nop 0
	global_load_lds_dwordx4 v[216:217], off
	s_waitcnt vmcnt(8)
	s_waitcnt lgkmcnt(0)
	s_barrier
; #define PG8_STAGE(bufoff, gbase, voff) do { _Pragma("unroll") for (int _i = 0; _i < 2; ++_i) \
;         __builtin_amdgcn_global_load_lds((const unsigned*)((const char*)(gbase) + (voff)[_i]), (PG8_LAS unsigned*)(lds + (bufoff) + ldsw + _i * 8192), 16, 0, 0); } while (0)
; #define PG8_LDA(dst, b, h) do { _Pragma("unroll") for (int m = 0; m < 4; ++m) _Pragma("unroll") for (int k = 0; k < 2; ++k) dst[m][k] = *(const PG8_LAS bf16x8*)(lds + PG8_SA(b, h) + aoff + m * 2048 + k * 1024); } while (0)
; #define PG8_LDB(dst, b, h) do { _Pragma("unroll") for (int n = 0; n < 2; ++n) _Pragma("unroll") for (int k = 0; k < 2; ++k) dst[n][k] = *(const PG8_LAS bf16x8*)(lds + PG8_SB(b, h) + boff + n * 2048 + k * 1024); } while (0)
; #define PG8_MMA(ai, bj, At, Bt) do { __builtin_amdgcn_s_setprio(1); _Pragma("unroll") for (int m = 0; m < 4; ++m) _Pragma("unroll") for (int n = 0; n < 2; ++n) _Pragma("unroll") for (int k = 0; k < 2; ++k) \
;         acc[ai][bj][m][n] = __builtin_amdgcn_mfma_f32_16x16x32_bf16(Bt[n][k], At[m][k], acc[ai][bj][m][n], 0, 0, 0); __builtin_amdgcn_s_setprio(0); } while (0)
; #define PG8_WAIT_V(n) asm volatile("s_waitcnt vmcnt(" #n ")" ::: "memory")
; #define PG8_WAIT_L(n) asm volatile("s_waitcnt lgkmcnt(" #n ")" ::: "memory")
; #define PG8_BAR __builtin_amdgcn_s_barrier()
; #define PG8_SCHED __builtin_amdgcn_sched_barrier(0)
; template <class Epi, class Sched, bool ALIGN_EPI, bool SP2, int KK, int LDA, int APN>
; __device__ __forceinline__ void gemm_phase(PG8_LAS unsigned char* lds, const Gemm g, const Sched& S, const Epi& E, const int wid) {
;     ...
;             PG8_WAIT_V(8); PG8_WAIT_L(0); PG8_BAR; PG8_MMA(1, 0, At, B0); PG8_MMA(1, 1, At, B1); PG8_BAR; PG8_SCHED;
;             PG8_LDB(B0, 1, 0); PG8_LDB(B1, 1, 1); PG8_SCHED; PG8_LDA(At, 1, 0); PG8_STAGE(PG8_SA(0, 1), a2 + hstepA, voffA);
;             PG8_WAIT_V(8); PG8_WAIT_L(0); PG8_BAR; PG8_MMA(0, 0, At, B0); PG8_MMA(0, 1, At, B1); PG8_BAR; PG8_SCHED;
;             PG8_LDA(At, 1, 1); PG8_STAGE(PG8_SB(1, 0), b3, voffB); PG8_STAGE(PG8_SB(1, 1), b3 + hstep, voffB); PG8_STAGE(PG8_SA(1, 0), a3, voffA);
	v_mfma_f32_16x16x32_bf16 v[60:63], v[140:143], v[172:175], v[60:63]
	v_mfma_f32_16x16x32_bf16 v[56:59], v[148:151], v[172:175], v[56:59]
	v_mfma_f32_16x16x32_bf16 v[52:55], v[140:143], v[180:183], v[52:55]
	v_mfma_f32_16x16x32_bf16 v[44:47], v[148:151], v[180:183], v[44:47]
	v_mfma_f32_16x16x32_bf16 v[36:39], v[140:143], v[188:191], v[36:39]
	v_mfma_f32_16x16x32_bf16 v[28:31], v[148:151], v[188:191], v[28:31]
	v_mfma_f32_16x16x32_bf16 v[20:23], v[140:143], v[206:209], v[20:23]
	v_mfma_f32_16x16x32_bf16 v[12:15], v[148:151], v[206:209], v[12:15]
	v_mfma_f32_16x16x32_bf16 v[60:63], v[144:147], v[176:179], v[60:63]
	v_mfma_f32_16x16x32_bf16 v[56:59], v[152:155], v[176:179], v[56:59]
	v_mfma_f32_16x16x32_bf16 v[52:55], v[144:147], v[184:187], v[52:55]
	v_mfma_f32_16x16x32_bf16 v[44:47], v[152:155], v[184:187], v[44:47]
	v_mfma_f32_16x16x32_bf16 v[36:39], v[144:147], v[202:205], v[36:39]
	v_mfma_f32_16x16x32_bf16 v[28:31], v[152:155], v[202:205], v[28:31]
	v_mfma_f32_16x16x32_bf16 v[20:23], v[144:147], v[212:215], v[20:23]
	v_mfma_f32_16x16x32_bf16 v[12:15], v[152:155], v[212:215], v[12:15]
	v_mfma_f32_16x16x32_bf16 v[48:51], v[156:159], v[172:175], v[48:51]
	v_mfma_f32_16x16x32_bf16 v[40:43], v[164:167], v[172:175], v[40:43]
	v_mfma_f32_16x16x32_bf16 v[32:35], v[156:159], v[180:183], v[32:35]
	v_mfma_f32_16x16x32_bf16 v[24:27], v[164:167], v[180:183], v[24:27]
	v_mfma_f32_16x16x32_bf16 v[16:19], v[156:159], v[188:191], v[16:19]
	v_mfma_f32_16x16x32_bf16 v[8:11], v[164:167], v[188:191], v[8:11]
	v_mfma_f32_16x16x32_bf16 v[4:7], v[156:159], v[206:209], v[4:7]
	v_mfma_f32_16x16x32_bf16 v[0:3], v[164:167], v[206:209], v[0:3]
	v_mfma_f32_16x16x32_bf16 v[48:51], v[160:163], v[176:179], v[48:51]
	v_mfma_f32_16x16x32_bf16 v[40:43], v[168:171], v[176:179], v[40:43]
	v_mfma_f32_16x16x32_bf16 v[32:35], v[160:163], v[184:187], v[32:35]
	v_mfma_f32_16x16x32_bf16 v[24:27], v[168:171], v[184:187], v[24:27]
	v_mfma_f32_16x16x32_bf16 v[16:19], v[160:163], v[202:205], v[16:19]
	v_mfma_f32_16x16x32_bf16 v[8:11], v[168:171], v[202:205], v[8:11]
	v_mfma_f32_16x16x32_bf16 v[4:7], v[160:163], v[212:215], v[4:7]
	v_mfma_f32_16x16x32_bf16 v[0:3], v[168:171], v[212:215], v[0:3]
	s_barrier
	v_add_u32_e32 v152, s45, v138
	v_add_u32_e32 v168, s44, v138
	ds_read_b128 v[140:143], v152
	ds_read_b128 v[144:147], v152 offset:1024
	ds_read_b128 v[148:151], v152 offset:2048
	ds_read_b128 v[152:155], v152 offset:3072
	ds_read_b128 v[156:159], v168
	ds_read_b128 v[160:163], v168 offset:1024
	ds_read_b128 v[164:167], v168 offset:2048
	ds_read_b128 v[168:171], v168 offset:3072
	s_mov_b32 m0, s42
	v_lshl_add_u64 v[226:227], s[26:27], 0, v[134:135]
	ds_read_b128 v[172:175], v139 offset:32768
	ds_read_b128 v[176:179], v139 offset:33792
	ds_read_b128 v[180:183], v139 offset:34816
	ds_read_b128 v[184:187], v139 offset:35840
	ds_read_b128 v[188:191], v139 offset:36864
	ds_read_b128 v[202:205], v139 offset:37888
	ds_read_b128 v[206:209], v139 offset:38912
	ds_read_b128 v[212:215], v139 offset:39936
	global_load_lds_dwordx4 v[226:227], off
	v_lshl_add_u64 v[226:227], s[26:27], 0, v[132:133]
	s_mov_b32 m0, s43
	s_nop 0
	global_load_lds_dwordx4 v[226:227], off
	s_waitcnt vmcnt(8)
	s_waitcnt lgkmcnt(0)
	s_barrier
	v_mfma_f32_16x16x32_bf16 v[126:129], v[140:143], v[172:175], v[126:129]
	v_mfma_f32_16x16x32_bf16 v[122:125], v[148:151], v[172:175], v[122:125]
	v_mfma_f32_16x16x32_bf16 v[118:121], v[140:143], v[180:183], v[118:121]
	v_mfma_f32_16x16x32_bf16 v[110:113], v[148:151], v[180:183], v[110:113]
	v_mfma_f32_16x16x32_bf16 v[102:105], v[140:143], v[188:191], v[102:105]
	v_mfma_f32_16x16x32_bf16 v[92:95], v[148:151], v[188:191], v[92:95]
	v_mfma_f32_16x16x32_bf16 v[84:87], v[140:143], v[206:209], v[84:87]
	v_mfma_f32_16x16x32_bf16 v[76:79], v[148:151], v[206:209], v[76:79]
	v_mfma_f32_16x16x32_bf16 v[126:129], v[144:147], v[176:179], v[126:129]
	v_mfma_f32_16x16x32_bf16 v[122:125], v[152:155], v[176:179], v[122:125]
	v_mfma_f32_16x16x32_bf16 v[118:121], v[144:147], v[184:187], v[118:121]
	v_mfma_f32_16x16x32_bf16 v[110:113], v[152:155], v[184:187], v[110:113]
	v_mfma_f32_16x16x32_bf16 v[102:105], v[144:147], v[202:205], v[102:105]
	v_mfma_f32_16x16x32_bf16 v[92:95], v[152:155], v[202:205], v[92:95]
	v_mfma_f32_16x16x32_bf16 v[84:87], v[144:147], v[212:215], v[84:87]
	v_mfma_f32_16x16x32_bf16 v[76:79], v[152:155], v[212:215], v[76:79]
	v_mfma_f32_16x16x32_bf16 v[114:117], v[156:159], v[172:175], v[114:117]
	v_mfma_f32_16x16x32_bf16 v[106:109], v[164:167], v[172:175], v[106:109]
	v_mfma_f32_16x16x32_bf16 v[98:101], v[156:159], v[180:183], v[98:101]
	v_mfma_f32_16x16x32_bf16 v[88:91], v[164:167], v[180:183], v[88:91]
	v_mfma_f32_16x16x32_bf16 v[80:83], v[156:159], v[188:191], v[80:83]
	v_mfma_f32_16x16x32_bf16 v[72:75], v[164:167], v[188:191], v[72:75]
	v_mfma_f32_16x16x32_bf16 v[68:71], v[156:159], v[206:209], v[68:71]
	v_mfma_f32_16x16x32_bf16 v[64:67], v[164:167], v[206:209], v[64:67]
	v_mfma_f32_16x16x32_bf16 v[114:117], v[160:163], v[176:179], v[114:117]
	v_mfma_f32_16x16x32_bf16 v[106:109], v[168:171], v[176:179], v[106:109]
	v_mfma_f32_16x16x32_bf16 v[98:101], v[160:163], v[184:187], v[98:101]
	v_mfma_f32_16x16x32_bf16 v[88:91], v[168:171], v[184:187], v[88:91]
	v_mfma_f32_16x16x32_bf16 v[80:83], v[160:163], v[202:205], v[80:83]
	v_mfma_f32_16x16x32_bf16 v[72:75], v[168:171], v[202:205], v[72:75]
	v_mfma_f32_16x16x32_bf16 v[68:71], v[160:163], v[212:215], v[68:71]
	v_mfma_f32_16x16x32_bf16 v[64:67], v[168:171], v[212:215], v[64:67]
	s_barrier
; #define PG8_STAGE(bufoff, gbase, voff) do { _Pragma("unroll") for (int _i = 0; _i < 2; ++_i) \
;         __builtin_amdgcn_global_load_lds((const unsigned*)((const char*)(gbase) + (voff)[_i]), (PG8_LAS unsigned*)(lds + (bufoff) + ldsw + _i * 8192), 16, 0, 0); } while (0)
; #define PG8_LDA(dst, b, h) do { _Pragma("unroll") for (int m = 0; m < 4; ++m) _Pragma("unroll") for (int k = 0; k < 2; ++k) dst[m][k] = *(const PG8_LAS bf16x8*)(lds + PG8_SA(b, h) + aoff + m * 2048 + k * 1024); } while (0)
; #define PG8_MMA(ai, bj, At, Bt) do { __builtin_amdgcn_s_setprio(1); _Pragma("unroll") for (int m = 0; m < 4; ++m) _Pragma("unroll") for (int n = 0; n < 2; ++n) _Pragma("unroll") for (int k = 0; k < 2; ++k) \
;         acc[ai][bj][m][n] = __builtin_amdgcn_mfma_f32_16x16x32_bf16(Bt[n][k], At[m][k], acc[ai][bj][m][n], 0, 0, 0); __builtin_amdgcn_s_setprio(0); } while (0)
; #define PG8_WAIT_V(n) asm volatile("s_waitcnt vmcnt(" #n ")" ::: "memory")
; #define PG8_WAIT_L(n) asm volatile("s_waitcnt lgkmcnt(" #n ")" ::: "memory")
; #define PG8_BAR __builtin_amdgcn_s_barrier()
; #define PG8_SCHED __builtin_amdgcn_sched_barrier(0)
; template <class Epi, class Sched, bool ALIGN_EPI, bool SP2, int KK, int LDA, int APN>
; __device__ __forceinline__ void gemm_phase(PG8_LAS unsigned char* lds, const Gemm g, const Sched& S, const Epi& E, const int wid) {
;     ...
;             PG8_LDA(At, 1, 1); PG8_STAGE(PG8_SB(1, 0), b3, voffB); PG8_STAGE(PG8_SB(1, 1), b3 + hstep, voffB); PG8_STAGE(PG8_SA(1, 0), a3, voffA);
;             PG8_WAIT_V(8); PG8_WAIT_L(0); PG8_BAR; PG8_MMA(1, 0, At, B0); PG8_MMA(1, 1, At, B1); PG8_BAR; PG8_SCHED;
;     ...
;         }
;         if constexpr (ALIGN_EPI) { if (wr == 0) PG8_BAR; }
	s_mov_b32 m0, s9
	v_lshl_add_u64 v[192:193], v[192:193], 0, s[22:23]
	ds_read_b128 v[172:175], v139 offset:49152
	ds_read_b128 v[176:179], v139 offset:50176
	ds_read_b128 v[180:183], v139 offset:51200
	ds_read_b128 v[184:187], v139 offset:52224
	ds_read_b128 v[188:191], v139 offset:53248
	ds_read_b128 v[202:205], v139 offset:54272
	ds_read_b128 v[206:209], v139 offset:55296
	ds_read_b128 v[212:215], v139 offset:56320
	global_load_lds_dwordx4 v[192:193], off
	v_lshl_add_u64 v[192:193], v[196:197], 0, s[22:23]
	s_mov_b32 m0, s8
	s_nop 0
	global_load_lds_dwordx4 v[192:193], off
	v_lshl_add_u64 v[192:193], s[18:19], 0, v[96:97]
	s_mov_b32 m0, s52
	s_nop 0
	global_load_lds_dwordx4 v[192:193], off
	v_lshl_add_u64 v[192:193], s[18:19], 0, v[130:131]
	s_mov_b32 m0, s51
	s_nop 0
	global_load_lds_dwordx4 v[192:193], off
	v_lshl_add_u64 v[192:193], v[198:199], 0, s[22:23]
	s_mov_b32 m0, s6
	s_nop 0
	global_load_lds_dwordx4 v[192:193], off
	v_lshl_add_u64 v[192:193], v[216:217], 0, s[22:23]
	s_mov_b32 m0, s7
	s_nop 0
	global_load_lds_dwordx4 v[192:193], off
	s_waitcnt vmcnt(8)
	s_waitcnt lgkmcnt(0)
	s_barrier
	v_mfma_f32_16x16x32_bf16 v[60:63], v[140:143], v[172:175], v[60:63]
	v_mfma_f32_16x16x32_bf16 v[56:59], v[148:151], v[172:175], v[56:59]
	v_mfma_f32_16x16x32_bf16 v[52:55], v[140:143], v[180:183], v[52:55]
	v_mfma_f32_16x16x32_bf16 v[44:47], v[148:151], v[180:183], v[44:47]
	v_mfma_f32_16x16x32_bf16 v[36:39], v[140:143], v[188:191], v[36:39]
	v_mfma_f32_16x16x32_bf16 v[28:31], v[148:151], v[188:191], v[28:31]
	v_mfma_f32_16x16x32_bf16 v[20:23], v[140:143], v[206:209], v[20:23]
	v_mfma_f32_16x16x32_bf16 v[12:15], v[148:151], v[206:209], v[12:15]
	v_mfma_f32_16x16x32_bf16 v[60:63], v[144:147], v[176:179], v[60:63]
	v_mfma_f32_16x16x32_bf16 v[56:59], v[152:155], v[176:179], v[56:59]
	v_mfma_f32_16x16x32_bf16 v[52:55], v[144:147], v[184:187], v[52:55]
	v_mfma_f32_16x16x32_bf16 v[44:47], v[152:155], v[184:187], v[44:47]
	v_mfma_f32_16x16x32_bf16 v[36:39], v[144:147], v[202:205], v[36:39]
	v_mfma_f32_16x16x32_bf16 v[28:31], v[152:155], v[202:205], v[28:31]
	v_mfma_f32_16x16x32_bf16 v[20:23], v[144:147], v[212:215], v[20:23]
	v_mfma_f32_16x16x32_bf16 v[12:15], v[152:155], v[212:215], v[12:15]
	v_mfma_f32_16x16x32_bf16 v[48:51], v[156:159], v[172:175], v[48:51]
	v_mfma_f32_16x16x32_bf16 v[40:43], v[164:167], v[172:175], v[40:43]
	v_mfma_f32_16x16x32_bf16 v[32:35], v[156:159], v[180:183], v[32:35]
	v_mfma_f32_16x16x32_bf16 v[24:27], v[164:167], v[180:183], v[24:27]
	v_mfma_f32_16x16x32_bf16 v[16:19], v[156:159], v[188:191], v[16:19]
	v_mfma_f32_16x16x32_bf16 v[8:11], v[164:167], v[188:191], v[8:11]
	v_mfma_f32_16x16x32_bf16 v[4:7], v[156:159], v[206:209], v[4:7]
	v_mfma_f32_16x16x32_bf16 v[0:3], v[164:167], v[206:209], v[0:3]
	v_mfma_f32_16x16x32_bf16 v[48:51], v[160:163], v[176:179], v[48:51]
	v_mfma_f32_16x16x32_bf16 v[40:43], v[168:171], v[176:179], v[40:43]
	v_mfma_f32_16x16x32_bf16 v[32:35], v[160:163], v[184:187], v[32:35]
	v_mfma_f32_16x16x32_bf16 v[24:27], v[168:171], v[184:187], v[24:27]
	v_mfma_f32_16x16x32_bf16 v[16:19], v[160:163], v[202:205], v[16:19]
	v_mfma_f32_16x16x32_bf16 v[8:11], v[168:171], v[202:205], v[8:11]
	v_mfma_f32_16x16x32_bf16 v[4:7], v[160:163], v[212:215], v[4:7]
	v_mfma_f32_16x16x32_bf16 v[0:3], v[168:171], v[212:215], v[0:3]
	s_barrier
	s_andn2_b64 vcc, exec, s[16:17]
	s_mov_b64 s[18:19], -1
	s_mov_b64 s[16:17], 0
	s_mov_b64 s[26:27], 0x100
	s_cbranch_vccz .LBB0_231
	s_cmp_lt_u32 s40, 4
	s_cbranch_scc0 .LBB0_234
	s_barrier

; #define PG8_STAGE(bufoff, gbase, voff) do { _Pragma("unroll") for (int _i = 0; _i < 2; ++_i) \
;         __builtin_amdgcn_global_load_lds((const unsigned*)((const char*)(gbase) + (voff)[_i]), (PG8_LAS unsigned*)(lds + (bufoff) + ldsw + _i * 8192), 16, 0, 0); } while (0)
; #define PG8_LDA(dst, b, h) do { _Pragma("unroll") for (int m = 0; m < 4; ++m) _Pragma("unroll") for (int k = 0; k < 2; ++k) dst[m][k] = *(const PG8_LAS bf16x8*)(lds + PG8_SA(b, h) + aoff + m * 2048 + k * 1024); } while (0)
; #define PG8_LDB(dst, b, h) do { _Pragma("unroll") for (int n = 0; n < 2; ++n) _Pragma("unroll") for (int k = 0; k < 2; ++k) dst[n][k] = *(const PG8_LAS bf16x8*)(lds + PG8_SB(b, h) + boff + n * 2048 + k * 1024); } while (0)
; #define PG8_MMA(ai, bj, At, Bt) do { __builtin_amdgcn_s_setprio(1); _Pragma("unroll") for (int m = 0; m < 4; ++m) _Pragma("unroll") for (int n = 0; n < 2; ++n) _Pragma("unroll") for (int k = 0; k < 2; ++k) \
;         acc[ai][bj][m][n] = __builtin_amdgcn_mfma_f32_16x16x32_bf16(Bt[n][k], At[m][k], acc[ai][bj][m][n], 0, 0, 0); __builtin_amdgcn_s_setprio(0); } while (0)
; #define PG8_WAIT_V(n) asm volatile("s_waitcnt vmcnt(" #n ")" ::: "memory")
; #define PG8_BAR __builtin_amdgcn_s_barrier()
; template <class Epi, class Sched, bool ALIGN_EPI, bool SP2, int KK, int LDA, int APN>
; __device__ __forceinline__ void gemm_phase(PG8_LAS unsigned char* lds, const Gemm g, const Sched& S, const Epi& E, const int wid) {
;     ...
;         for (int t = 0; t < nt; t += 2) {
;             const bool last = (t == nt - 2);
;             const char* a1 = cA + (size_t)(t + 1) * kstep;
;             const char* a2 = last ? nA : cA + (size_t)(t + 2) * kstep; const char* b2 = last ? nB : cB + (size_t)(t + 2) * kstep;
;             const char* a3 = a2 + kstep; const char* b3 = b2 + kstep;
;             if (last && has_next) S.a_ready(nxt);
;             if constexpr (SP2) {
;             PG8_LDB(B0, 0, 0); PG8_LDB(B1, 0, 1); PG8_SCHED; PG8_LDA(At, 0, 0); PG8_STAGE(PG8_SA(1, 1), a1 + hstepA, voffA);
;             PG8_WAIT_V(8); PG8_WAIT_L(0); PG8_BAR; PG8_MMA(0, 0, At, B0); PG8_MMA(0, 1, At, B1); PG8_BAR; PG8_SCHED;
;             PG8_LDA(At, 0, 1); PG8_STAGE(PG8_SB(0, 0), b2, voffB); PG8_STAGE(PG8_SB(0, 1), b2 + hstep, voffB); PG8_STAGE(PG8_SA(0, 0), a2, voffA);
;             PG8_WAIT_V(8); PG8_WAIT_L(0); PG8_BAR; PG8_MMA(1, 0, At, B0); PG8_MMA(1, 1, At, B1); PG8_BAR; PG8_SCHED;
.LBB0_309:
	s_add_u32 s40, s26, s42
	s_addc_u32 s41, s27, s43
	s_add_u32 s40, s40, 0x100
	s_addc_u32 s41, s41, 0
	s_add_u32 s48, s68, s42
	s_addc_u32 s49, s69, s43
	s_add_i32 s70, 0, 0x10000
	s_cmpk_eq_i32 s42, 0x2b00
	s_cselect_b32 s51, s31, s41
	s_cselect_b32 s50, s30, s40
	v_add_u32_e32 v144, s70, v148
	s_cselect_b32 s49, s29, s49
	s_cselect_b32 s48, s28, s48
	s_add_i32 s71, 0, 0x14000
	ds_read_b128 v[154:157], v144
	ds_read_b128 v[158:161], v144 offset:1024
	ds_read_b128 v[162:165], v144 offset:2048
	ds_read_b128 v[166:169], v144 offset:3072
	v_add_u32_e32 v144, s71, v148
	ds_read_b128 v[170:173], v144
	ds_read_b128 v[174:177], v144 offset:1024
	ds_read_b128 v[178:181], v144 offset:2048
	ds_read_b128 v[182:185], v144 offset:3072
	v_lshl_add_u64 v[144:145], v[142:143], 0, s[42:43]
	s_add_i32 m0, s13, 0xc000
	ds_read_b128 v[186:189], v150
	ds_read_b128 v[190:193], v150 offset:1024
	ds_read_b128 v[202:205], v150 offset:2048
	ds_read_b128 v[206:209], v150 offset:3072
	ds_read_b128 v[212:215], v150 offset:4096
	ds_read_b128 v[226:229], v150 offset:5120
	ds_read_b128 v[230:233], v150 offset:6144
	ds_read_b128 v[234:237], v150 offset:7168
	global_load_lds_dwordx4 v[144:145], off
	v_lshl_add_u64 v[144:145], v[140:141], 0, s[42:43]
	s_add_i32 m0, s13, 0xe000
	s_nop 0
	global_load_lds_dwordx4 v[144:145], off
	s_waitcnt vmcnt(8)
	s_waitcnt lgkmcnt(0)
	s_barrier
	v_mfma_f32_16x16x32_bf16 v[0:3], v[154:157], v[186:189], v[0:3]
	v_mfma_f32_16x16x32_bf16 v[4:7], v[162:165], v[186:189], v[4:7]
	v_mfma_f32_16x16x32_bf16 v[16:19], v[154:157], v[202:205], v[16:19]
	v_mfma_f32_16x16x32_bf16 v[20:23], v[162:165], v[202:205], v[20:23]
	v_mfma_f32_16x16x32_bf16 v[32:35], v[154:157], v[212:215], v[32:35]
	v_mfma_f32_16x16x32_bf16 v[36:39], v[162:165], v[212:215], v[36:39]
	v_mfma_f32_16x16x32_bf16 v[48:51], v[154:157], v[230:233], v[48:51]
	v_mfma_f32_16x16x32_bf16 v[52:55], v[162:165], v[230:233], v[52:55]
	v_mfma_f32_16x16x32_bf16 v[0:3], v[158:161], v[190:193], v[0:3]
	v_mfma_f32_16x16x32_bf16 v[4:7], v[166:169], v[190:193], v[4:7]
	v_mfma_f32_16x16x32_bf16 v[16:19], v[158:161], v[206:209], v[16:19]
	v_mfma_f32_16x16x32_bf16 v[20:23], v[166:169], v[206:209], v[20:23]
	v_mfma_f32_16x16x32_bf16 v[32:35], v[158:161], v[226:229], v[32:35]
	v_mfma_f32_16x16x32_bf16 v[36:39], v[166:169], v[226:229], v[36:39]
	v_mfma_f32_16x16x32_bf16 v[48:51], v[158:161], v[234:237], v[48:51]
	v_mfma_f32_16x16x32_bf16 v[52:55], v[166:169], v[234:237], v[52:55]
	v_mfma_f32_16x16x32_bf16 v[8:11], v[170:173], v[186:189], v[8:11]
	v_mfma_f32_16x16x32_bf16 v[12:15], v[178:181], v[186:189], v[12:15]
	v_mfma_f32_16x16x32_bf16 v[24:27], v[170:173], v[202:205], v[24:27]
	v_mfma_f32_16x16x32_bf16 v[28:31], v[178:181], v[202:205], v[28:31]
	v_mfma_f32_16x16x32_bf16 v[40:43], v[170:173], v[212:215], v[40:43]
	v_mfma_f32_16x16x32_bf16 v[44:47], v[178:181], v[212:215], v[44:47]
	v_mfma_f32_16x16x32_bf16 v[56:59], v[170:173], v[230:233], v[56:59]
	v_mfma_f32_16x16x32_bf16 v[60:63], v[178:181], v[230:233], v[60:63]
	v_mfma_f32_16x16x32_bf16 v[8:11], v[174:177], v[190:193], v[8:11]
	v_mfma_f32_16x16x32_bf16 v[12:15], v[182:185], v[190:193], v[12:15]
	v_mfma_f32_16x16x32_bf16 v[24:27], v[174:177], v[206:209], v[24:27]
	v_mfma_f32_16x16x32_bf16 v[28:31], v[182:185], v[206:209], v[28:31]
	v_mfma_f32_16x16x32_bf16 v[40:43], v[174:177], v[226:229], v[40:43]
	v_mfma_f32_16x16x32_bf16 v[44:47], v[182:185], v[226:229], v[44:47]
	v_mfma_f32_16x16x32_bf16 v[56:59], v[174:177], v[234:237], v[56:59]
	v_mfma_f32_16x16x32_bf16 v[60:63], v[182:185], v[234:237], v[60:63]
	s_barrier
	s_add_i32 s40, s70, s12
	v_lshl_add_u64 v[144:145], s[48:49], 0, v[96:97]
	s_mov_b32 m0, s40
	ds_read_b128 v[186:189], v150 offset:16384
	ds_read_b128 v[190:193], v150 offset:17408
	ds_read_b128 v[202:205], v150 offset:18432
	ds_read_b128 v[206:209], v150 offset:19456
	ds_read_b128 v[212:215], v150 offset:20480
	ds_read_b128 v[226:229], v150 offset:21504
	ds_read_b128 v[230:233], v150 offset:22528
	ds_read_b128 v[234:237], v150 offset:23552
	global_load_lds_dwordx4 v[144:145], off
	s_add_i32 m0, s40, 0x2000
	s_add_u32 s40, s48, 0x160000
	v_lshl_add_u64 v[196:197], s[48:49], 0, v[134:135]
	s_addc_u32 s41, s49, 0
	s_add_i32 s70, s71, s12
	global_load_lds_dwordx4 v[196:197], off
	v_lshl_add_u64 v[198:199], s[40:41], 0, v[96:97]
	s_mov_b32 m0, s70
	v_lshl_add_u64 v[216:217], s[50:51], 0, v[132:133]
	global_load_lds_dwordx4 v[198:199], off
	v_lshl_add_u64 v[198:199], s[40:41], 0, v[134:135]
	s_add_i32 m0, s70, 0x2000
	s_nop 0
	global_load_lds_dwordx4 v[198:199], off
	v_lshl_add_u64 v[198:199], s[50:51], 0, v[130:131]
	s_mov_b32 m0, s13
	s_nop 0
	global_load_lds_dwordx4 v[198:199], off
	s_mov_b32 m0, s52
	s_nop 0
	global_load_lds_dwordx4 v[216:217], off
	s_waitcnt vmcnt(8)
	s_waitcnt lgkmcnt(0)
	s_barrier
; #define PG8_STAGE(bufoff, gbase, voff) do { _Pragma("unroll") for (int _i = 0; _i < 2; ++_i) \
;         __builtin_amdgcn_global_load_lds((const unsigned*)((const char*)(gbase) + (voff)[_i]), (PG8_LAS unsigned*)(lds + (bufoff) + ldsw + _i * 8192), 16, 0, 0); } while (0)
; #define PG8_LDA(dst, b, h) do { _Pragma("unroll") for (int m = 0; m < 4; ++m) _Pragma("unroll") for (int k = 0; k < 2; ++k) dst[m][k] = *(const PG8_LAS bf16x8*)(lds + PG8_SA(b, h) + aoff + m * 2048 + k * 1024); } while (0)
; #define PG8_LDB(dst, b, h) do { _Pragma("unroll") for (int n = 0; n < 2; ++n) _Pragma("unroll") for (int k = 0; k < 2; ++k) dst[n][k] = *(const PG8_LAS bf16x8*)(lds + PG8_SB(b, h) + boff + n * 2048 + k * 1024); } while (0)
; #define PG8_MMA(ai, bj, At, Bt) do { __builtin_amdgcn_s_setprio(1); _Pragma("unroll") for (int m = 0; m < 4; ++m) _Pragma("unroll") for (int n = 0; n < 2; ++n) _Pragma("unroll") for (int k = 0; k < 2; ++k) \
;         acc[ai][bj][m][n] = __builtin_amdgcn_mfma_f32_16x16x32_bf16(Bt[n][k], At[m][k], acc[ai][bj][m][n], 0, 0, 0); __builtin_amdgcn_s_setprio(0); } while (0)
; #define PG8_WAIT_V(n) asm volatile("s_waitcnt vmcnt(" #n ")" ::: "memory")
; #define PG8_WAIT_L(n) asm volatile("s_waitcnt lgkmcnt(" #n ")" ::: "memory")
; #define PG8_BAR __builtin_amdgcn_s_barrier()
; #define PG8_SCHED __builtin_amdgcn_sched_barrier(0)
; template <class Epi, class Sched, bool ALIGN_EPI, bool SP2, int KK, int LDA, int APN>
; __device__ __forceinline__ void gemm_phase(PG8_LAS unsigned char* lds, const Gemm g, const Sched& S, const Epi& E, const int wid) {
;     ...
;             PG8_WAIT_V(8); PG8_WAIT_L(0); PG8_BAR; PG8_MMA(1, 0, At, B0); PG8_MMA(1, 1, At, B1); PG8_BAR; PG8_SCHED;
;             PG8_LDB(B0, 1, 0); PG8_LDB(B1, 1, 1); PG8_SCHED; PG8_LDA(At, 1, 0); PG8_STAGE(PG8_SA(0, 1), a2 + hstepA, voffA);
;             PG8_WAIT_V(8); PG8_WAIT_L(0); PG8_BAR; PG8_MMA(0, 0, At, B0); PG8_MMA(0, 1, At, B1); PG8_BAR; PG8_SCHED;
;             PG8_LDA(At, 1, 1); PG8_STAGE(PG8_SB(1, 0), b3, voffB); PG8_STAGE(PG8_SB(1, 1), b3 + hstep, voffB); PG8_STAGE(PG8_SA(1, 0), a3, voffA);
	v_mfma_f32_16x16x32_bf16 v[64:67], v[154:157], v[186:189], v[64:67]
	v_mfma_f32_16x16x32_bf16 v[68:71], v[162:165], v[186:189], v[68:71]
	v_mfma_f32_16x16x32_bf16 v[80:83], v[154:157], v[202:205], v[80:83]
	v_mfma_f32_16x16x32_bf16 v[84:87], v[162:165], v[202:205], v[84:87]
	v_mfma_f32_16x16x32_bf16 v[98:101], v[154:157], v[212:215], v[98:101]
	v_mfma_f32_16x16x32_bf16 v[102:105], v[162:165], v[212:215], v[102:105]
	v_mfma_f32_16x16x32_bf16 v[114:117], v[154:157], v[230:233], v[114:117]
	v_mfma_f32_16x16x32_bf16 v[118:121], v[162:165], v[230:233], v[118:121]
	v_mfma_f32_16x16x32_bf16 v[64:67], v[158:161], v[190:193], v[64:67]
	v_mfma_f32_16x16x32_bf16 v[68:71], v[166:169], v[190:193], v[68:71]
	v_mfma_f32_16x16x32_bf16 v[80:83], v[158:161], v[206:209], v[80:83]
	v_mfma_f32_16x16x32_bf16 v[84:87], v[166:169], v[206:209], v[84:87]
	v_mfma_f32_16x16x32_bf16 v[98:101], v[158:161], v[226:229], v[98:101]
	v_mfma_f32_16x16x32_bf16 v[102:105], v[166:169], v[226:229], v[102:105]
	v_mfma_f32_16x16x32_bf16 v[114:117], v[158:161], v[234:237], v[114:117]
	v_mfma_f32_16x16x32_bf16 v[118:121], v[166:169], v[234:237], v[118:121]
	v_mfma_f32_16x16x32_bf16 v[72:75], v[170:173], v[186:189], v[72:75]
	v_mfma_f32_16x16x32_bf16 v[76:79], v[178:181], v[186:189], v[76:79]
	v_mfma_f32_16x16x32_bf16 v[88:91], v[170:173], v[202:205], v[88:91]
	v_mfma_f32_16x16x32_bf16 v[92:95], v[178:181], v[202:205], v[92:95]
	v_mfma_f32_16x16x32_bf16 v[106:109], v[170:173], v[212:215], v[106:109]
	v_mfma_f32_16x16x32_bf16 v[110:113], v[178:181], v[212:215], v[110:113]
	v_mfma_f32_16x16x32_bf16 v[122:125], v[170:173], v[230:233], v[122:125]
	v_mfma_f32_16x16x32_bf16 v[126:129], v[178:181], v[230:233], v[126:129]
	v_mfma_f32_16x16x32_bf16 v[72:75], v[174:177], v[190:193], v[72:75]
	v_mfma_f32_16x16x32_bf16 v[76:79], v[182:185], v[190:193], v[76:79]
	v_mfma_f32_16x16x32_bf16 v[88:91], v[174:177], v[206:209], v[88:91]
	v_mfma_f32_16x16x32_bf16 v[92:95], v[182:185], v[206:209], v[92:95]
	v_mfma_f32_16x16x32_bf16 v[106:109], v[174:177], v[226:229], v[106:109]
	v_mfma_f32_16x16x32_bf16 v[110:113], v[182:185], v[226:229], v[110:113]
	v_mfma_f32_16x16x32_bf16 v[122:125], v[174:177], v[234:237], v[122:125]
	v_mfma_f32_16x16x32_bf16 v[126:129], v[182:185], v[234:237], v[126:129]
	s_barrier
	s_add_i32 s70, 0, 0x18000
	v_add_u32_e32 v153, s70, v148
	s_add_i32 s71, 0, 0x1c000
	ds_read_b128 v[154:157], v153
	ds_read_b128 v[158:161], v153 offset:1024
	ds_read_b128 v[162:165], v153 offset:2048
	ds_read_b128 v[166:169], v153 offset:3072
	v_add_u32_e32 v153, s71, v148
	ds_read_b128 v[170:173], v153
	ds_read_b128 v[174:177], v153 offset:1024
	ds_read_b128 v[178:181], v153 offset:2048
	ds_read_b128 v[182:185], v153 offset:3072
	s_add_u32 s40, s50, 0x160000
	s_addc_u32 s41, s51, 0
	s_mov_b32 m0, s53
	v_lshl_add_u64 v[238:239], s[40:41], 0, v[130:131]
	ds_read_b128 v[186:189], v150 offset:32768
	ds_read_b128 v[190:193], v150 offset:33792
	ds_read_b128 v[202:205], v150 offset:34816
	ds_read_b128 v[206:209], v150 offset:35840
	ds_read_b128 v[212:215], v150 offset:36864
	ds_read_b128 v[226:229], v150 offset:37888
	ds_read_b128 v[230:233], v150 offset:38912
	ds_read_b128 v[234:237], v150 offset:39936
	global_load_lds_dwordx4 v[238:239], off
	v_lshl_add_u64 v[238:239], s[40:41], 0, v[132:133]
	s_mov_b32 m0, s54
	s_nop 0
	global_load_lds_dwordx4 v[238:239], off
	s_waitcnt vmcnt(8)
	s_waitcnt lgkmcnt(0)
	s_barrier
	v_mfma_f32_16x16x32_bf16 v[0:3], v[154:157], v[186:189], v[0:3]
	v_mfma_f32_16x16x32_bf16 v[4:7], v[162:165], v[186:189], v[4:7]
	v_mfma_f32_16x16x32_bf16 v[16:19], v[154:157], v[202:205], v[16:19]
	v_mfma_f32_16x16x32_bf16 v[20:23], v[162:165], v[202:205], v[20:23]
	v_mfma_f32_16x16x32_bf16 v[32:35], v[154:157], v[212:215], v[32:35]
	v_mfma_f32_16x16x32_bf16 v[36:39], v[162:165], v[212:215], v[36:39]
	v_mfma_f32_16x16x32_bf16 v[48:51], v[154:157], v[230:233], v[48:51]
	v_mfma_f32_16x16x32_bf16 v[52:55], v[162:165], v[230:233], v[52:55]
	v_mfma_f32_16x16x32_bf16 v[0:3], v[158:161], v[190:193], v[0:3]
	v_mfma_f32_16x16x32_bf16 v[4:7], v[166:169], v[190:193], v[4:7]
	v_mfma_f32_16x16x32_bf16 v[16:19], v[158:161], v[206:209], v[16:19]
	v_mfma_f32_16x16x32_bf16 v[20:23], v[166:169], v[206:209], v[20:23]
	v_mfma_f32_16x16x32_bf16 v[32:35], v[158:161], v[226:229], v[32:35]
	v_mfma_f32_16x16x32_bf16 v[36:39], v[166:169], v[226:229], v[36:39]
	v_mfma_f32_16x16x32_bf16 v[48:51], v[158:161], v[234:237], v[48:51]
	v_mfma_f32_16x16x32_bf16 v[52:55], v[166:169], v[234:237], v[52:55]
	v_mfma_f32_16x16x32_bf16 v[8:11], v[170:173], v[186:189], v[8:11]
	v_mfma_f32_16x16x32_bf16 v[12:15], v[178:181], v[186:189], v[12:15]
	v_mfma_f32_16x16x32_bf16 v[24:27], v[170:173], v[202:205], v[24:27]
	v_mfma_f32_16x16x32_bf16 v[28:31], v[178:181], v[202:205], v[28:31]
	v_mfma_f32_16x16x32_bf16 v[40:43], v[170:173], v[212:215], v[40:43]
	v_mfma_f32_16x16x32_bf16 v[44:47], v[178:181], v[212:215], v[44:47]
	v_mfma_f32_16x16x32_bf16 v[56:59], v[170:173], v[230:233], v[56:59]
	v_mfma_f32_16x16x32_bf16 v[60:63], v[178:181], v[230:233], v[60:63]
	v_mfma_f32_16x16x32_bf16 v[8:11], v[174:177], v[190:193], v[8:11]
	v_mfma_f32_16x16x32_bf16 v[12:15], v[182:185], v[190:193], v[12:15]
	v_mfma_f32_16x16x32_bf16 v[24:27], v[174:177], v[206:209], v[24:27]
	v_mfma_f32_16x16x32_bf16 v[28:31], v[182:185], v[206:209], v[28:31]
	v_mfma_f32_16x16x32_bf16 v[40:43], v[174:177], v[226:229], v[40:43]
	v_mfma_f32_16x16x32_bf16 v[44:47], v[182:185], v[226:229], v[44:47]
	v_mfma_f32_16x16x32_bf16 v[56:59], v[174:177], v[234:237], v[56:59]
	v_mfma_f32_16x16x32_bf16 v[60:63], v[182:185], v[234:237], v[60:63]
	s_barrier
; #define PG8_STAGE(bufoff, gbase, voff) do { _Pragma("unroll") for (int _i = 0; _i < 2; ++_i) \
;         __builtin_amdgcn_global_load_lds((const unsigned*)((const char*)(gbase) + (voff)[_i]), (PG8_LAS unsigned*)(lds + (bufoff) + ldsw + _i * 8192), 16, 0, 0); } while (0)
; #define PG8_LDA(dst, b, h) do { _Pragma("unroll") for (int m = 0; m < 4; ++m) _Pragma("unroll") for (int k = 0; k < 2; ++k) dst[m][k] = *(const PG8_LAS bf16x8*)(lds + PG8_SA(b, h) + aoff + m * 2048 + k * 1024); } while (0)
; #define PG8_MMA(ai, bj, At, Bt) do { __builtin_amdgcn_s_setprio(1); _Pragma("unroll") for (int m = 0; m < 4; ++m) _Pragma("unroll") for (int n = 0; n < 2; ++n) _Pragma("unroll") for (int k = 0; k < 2; ++k) \
;         acc[ai][bj][m][n] = __builtin_amdgcn_mfma_f32_16x16x32_bf16(Bt[n][k], At[m][k], acc[ai][bj][m][n], 0, 0, 0); __builtin_amdgcn_s_setprio(0); } while (0)
; #define PG8_WAIT_V(n) asm volatile("s_waitcnt vmcnt(" #n ")" ::: "memory")
; #define PG8_WAIT_L(n) asm volatile("s_waitcnt lgkmcnt(" #n ")" ::: "memory")
; #define PG8_BAR __builtin_amdgcn_s_barrier()
; #define PG8_SCHED __builtin_amdgcn_sched_barrier(0)
; template <class Epi, class Sched, bool ALIGN_EPI, bool SP2, int KK, int LDA, int APN>
; __device__ __forceinline__ void gemm_phase(PG8_LAS unsigned char* lds, const Gemm g, const Sched& S, const Epi& E, const int wid) {
;     ...
;             PG8_LDA(At, 1, 1); PG8_STAGE(PG8_SB(1, 0), b3, voffB); PG8_STAGE(PG8_SB(1, 1), b3 + hstep, voffB); PG8_STAGE(PG8_SA(1, 0), a3, voffA);
;             PG8_WAIT_V(8); PG8_WAIT_L(0); PG8_BAR; PG8_MMA(1, 0, At, B0); PG8_MMA(1, 1, At, B1); PG8_BAR; PG8_SCHED;
;     ...
;         }
;         if constexpr (ALIGN_EPI) { if (wr == 0) PG8_BAR; }
	s_add_i32 s40, s70, s12
	v_lshl_add_u64 v[144:145], v[144:145], 0, s[22:23]
	s_mov_b32 m0, s40
	ds_read_b128 v[186:189], v150 offset:49152
	ds_read_b128 v[190:193], v150 offset:50176
	ds_read_b128 v[202:205], v150 offset:51200
	ds_read_b128 v[206:209], v150 offset:52224
	ds_read_b128 v[212:215], v150 offset:53248
	ds_read_b128 v[226:229], v150 offset:54272
	ds_read_b128 v[230:233], v150 offset:55296
	ds_read_b128 v[234:237], v150 offset:56320
	global_load_lds_dwordx4 v[144:145], off
	s_add_i32 m0, s40, 0x2000
	s_add_u32 s40, s48, 0x160080
	v_lshl_add_u64 v[144:145], v[196:197], 0, s[22:23]
	s_addc_u32 s41, s49, 0
	s_add_i32 s48, s71, s12
	global_load_lds_dwordx4 v[144:145], off
	v_lshl_add_u64 v[144:145], s[40:41], 0, v[96:97]
	s_mov_b32 m0, s48
	s_nop 0
	global_load_lds_dwordx4 v[144:145], off
	v_lshl_add_u64 v[144:145], s[40:41], 0, v[134:135]
	s_add_i32 m0, s48, 0x2000
	s_nop 0
	global_load_lds_dwordx4 v[144:145], off
	v_lshl_add_u64 v[144:145], v[198:199], 0, s[22:23]
	s_mov_b32 m0, s57
	s_nop 0
	global_load_lds_dwordx4 v[144:145], off
	v_lshl_add_u64 v[144:145], v[216:217], 0, s[22:23]
	s_mov_b32 m0, s58
	s_nop 0
	global_load_lds_dwordx4 v[144:145], off
	s_waitcnt vmcnt(8)
	s_waitcnt lgkmcnt(0)
	s_barrier
	v_mfma_f32_16x16x32_bf16 v[64:67], v[154:157], v[186:189], v[64:67]
	v_mfma_f32_16x16x32_bf16 v[68:71], v[162:165], v[186:189], v[68:71]
	v_mfma_f32_16x16x32_bf16 v[80:83], v[154:157], v[202:205], v[80:83]
	v_mfma_f32_16x16x32_bf16 v[84:87], v[162:165], v[202:205], v[84:87]
	v_mfma_f32_16x16x32_bf16 v[98:101], v[154:157], v[212:215], v[98:101]
	v_mfma_f32_16x16x32_bf16 v[102:105], v[162:165], v[212:215], v[102:105]
	v_mfma_f32_16x16x32_bf16 v[114:117], v[154:157], v[230:233], v[114:117]
	v_mfma_f32_16x16x32_bf16 v[118:121], v[162:165], v[230:233], v[118:121]
	v_mfma_f32_16x16x32_bf16 v[64:67], v[158:161], v[190:193], v[64:67]
	v_mfma_f32_16x16x32_bf16 v[68:71], v[166:169], v[190:193], v[68:71]
	v_mfma_f32_16x16x32_bf16 v[80:83], v[158:161], v[206:209], v[80:83]
	v_mfma_f32_16x16x32_bf16 v[84:87], v[166:169], v[206:209], v[84:87]
	v_mfma_f32_16x16x32_bf16 v[98:101], v[158:161], v[226:229], v[98:101]
	v_mfma_f32_16x16x32_bf16 v[102:105], v[166:169], v[226:229], v[102:105]
	v_mfma_f32_16x16x32_bf16 v[114:117], v[158:161], v[234:237], v[114:117]
	v_mfma_f32_16x16x32_bf16 v[118:121], v[166:169], v[234:237], v[118:121]
	v_mfma_f32_16x16x32_bf16 v[72:75], v[170:173], v[186:189], v[72:75]
	v_mfma_f32_16x16x32_bf16 v[76:79], v[178:181], v[186:189], v[76:79]
	v_mfma_f32_16x16x32_bf16 v[88:91], v[170:173], v[202:205], v[88:91]
	v_mfma_f32_16x16x32_bf16 v[92:95], v[178:181], v[202:205], v[92:95]
	v_mfma_f32_16x16x32_bf16 v[106:109], v[170:173], v[212:215], v[106:109]
	v_mfma_f32_16x16x32_bf16 v[110:113], v[178:181], v[212:215], v[110:113]
	v_mfma_f32_16x16x32_bf16 v[122:125], v[170:173], v[230:233], v[122:125]
	v_mfma_f32_16x16x32_bf16 v[126:129], v[178:181], v[230:233], v[126:129]
	v_mfma_f32_16x16x32_bf16 v[72:75], v[174:177], v[190:193], v[72:75]
	v_mfma_f32_16x16x32_bf16 v[76:79], v[182:185], v[190:193], v[76:79]
	v_mfma_f32_16x16x32_bf16 v[88:91], v[174:177], v[206:209], v[88:91]
	v_mfma_f32_16x16x32_bf16 v[92:95], v[182:185], v[206:209], v[92:95]
	v_mfma_f32_16x16x32_bf16 v[106:109], v[174:177], v[226:229], v[106:109]
	v_mfma_f32_16x16x32_bf16 v[110:113], v[182:185], v[226:229], v[110:113]
	v_mfma_f32_16x16x32_bf16 v[122:125], v[174:177], v[234:237], v[122:125]
	v_mfma_f32_16x16x32_bf16 v[126:129], v[182:185], v[234:237], v[126:129]
	s_barrier
	s_add_i32 s17, s17, 2
	s_add_u32 s42, s42, 0x100
	s_addc_u32 s43, s43, 0
	s_cmpk_gt_u32 s17, 0x55
	s_cbranch_scc0 .LBB0_309
	s_and_b64 vcc, exec, s[46:47]
	s_cbranch_vccz .LBB0_312
	s_barrier

; #define PG8_STAGE(bufoff, gbase, voff) do { _Pragma("unroll") for (int _i = 0; _i < 2; ++_i) \
;         __builtin_amdgcn_global_load_lds((const unsigned*)((const char*)(gbase) + (voff)[_i]), (PG8_LAS unsigned*)(lds + (bufoff) + ldsw + _i * 8192), 16, 0, 0); } while (0)
; #define PG8_LDA(dst, b, h) do { _Pragma("unroll") for (int m = 0; m < 4; ++m) _Pragma("unroll") for (int k = 0; k < 2; ++k) dst[m][k] = *(const PG8_LAS bf16x8*)(lds + PG8_SA(b, h) + aoff + m * 2048 + k * 1024); } while (0)
; #define PG8_LDB(dst, b, h) do { _Pragma("unroll") for (int n = 0; n < 2; ++n) _Pragma("unroll") for (int k = 0; k < 2; ++k) dst[n][k] = *(const PG8_LAS bf16x8*)(lds + PG8_SB(b, h) + boff + n * 2048 + k * 1024); } while (0)
; #define PG8_MMA(ai, bj, At, Bt) do { __builtin_amdgcn_s_setprio(1); _Pragma("unroll") for (int m = 0; m < 4; ++m) _Pragma("unroll") for (int n = 0; n < 2; ++n) _Pragma("unroll") for (int k = 0; k < 2; ++k) \
;         acc[ai][bj][m][n] = __builtin_amdgcn_mfma_f32_16x16x32_bf16(Bt[n][k], At[m][k], acc[ai][bj][m][n], 0, 0, 0); __builtin_amdgcn_s_setprio(0); } while (0)
; #define PG8_WAIT_V(n) asm volatile("s_waitcnt vmcnt(" #n ")" ::: "memory")
; #define PG8_BAR __builtin_amdgcn_s_barrier()
; template <class Epi, class Sched, bool ALIGN_EPI, bool SP2, int KK, int LDA, int APN>
; __device__ __forceinline__ void gemm_phase(PG8_LAS unsigned char* lds, const Gemm g, const Sched& S, const Epi& E, const int wid) {
;     ...
;         for (int t = 0; t < nt; t += 2) {
;             const bool last = (t == nt - 2);
;             const char* a1 = cA + (size_t)(t + 1) * kstep;
;             const char* a2 = last ? nA : cA + (size_t)(t + 2) * kstep; const char* b2 = last ? nB : cB + (size_t)(t + 2) * kstep;
;             const char* a3 = a2 + kstep; const char* b3 = b2 + kstep;
;             if (last && has_next) S.a_ready(nxt);
;             if constexpr (SP2) {
;             PG8_LDB(B0, 0, 0); PG8_LDB(B1, 0, 1); PG8_SCHED; PG8_LDA(At, 0, 0); PG8_STAGE(PG8_SA(1, 1), a1 + hstepA, voffA);
;             PG8_WAIT_V(8); PG8_WAIT_L(0); PG8_BAR; PG8_MMA(0, 0, At, B0); PG8_MMA(0, 1, At, B1); PG8_BAR; PG8_SCHED;
;             PG8_LDA(At, 0, 1); PG8_STAGE(PG8_SB(0, 0), b2, voffB); PG8_STAGE(PG8_SB(0, 1), b2 + hstep, voffB); PG8_STAGE(PG8_SA(0, 0), a2, voffA);
;             PG8_WAIT_V(8); PG8_WAIT_L(0); PG8_BAR; PG8_MMA(1, 0, At, B0); PG8_MMA(1, 1, At, B1); PG8_BAR; PG8_SCHED;
.LBB0_406:
	s_add_u32 s12, s16, 0xfff80080
	s_addc_u32 s13, s17, -1
	s_add_i32 s15, 0, 0x10000
	s_cmp_eq_u32 s11, 28
	s_cselect_b32 s27, s3, s13
	s_cselect_b32 s26, s6, s12
	s_cselect_b32 s19, s7, s10
	s_cselect_b32 s18, s8, s9
	s_add_i32 s55, 0, 0x14000
	v_add_u32_e32 v142, s15, v169
	v_add_u32_e32 v166, s55, v169
	ds_read_b128 v[130:133], v142
	ds_read_b128 v[134:137], v142 offset:1024
	ds_read_b128 v[138:141], v142 offset:2048
	ds_read_b128 v[142:145], v142 offset:3072
	ds_read_b128 v[162:165], v166
	ds_read_b128 v[176:179], v166 offset:1024
	ds_read_b128 v[180:183], v166 offset:2048
	ds_read_b128 v[184:187], v166 offset:3072
	v_lshl_add_u64 v[166:167], s[16:17], 0, v[160:161]
	s_add_i32 m0, s69, 0xc000
	ds_read_b128 v[188:191], v172
	ds_read_b128 v[202:205], v172 offset:1024
	ds_read_b128 v[206:209], v172 offset:2048
	ds_read_b128 v[212:215], v172 offset:3072
	ds_read_b128 v[226:229], v172 offset:4096
	ds_read_b128 v[230:233], v172 offset:5120
	ds_read_b128 v[234:237], v172 offset:6144
	ds_read_b128 v[238:241], v172 offset:7168
	global_load_lds_dwordx4 v[166:167], off
	v_lshl_add_u64 v[166:167], s[16:17], 0, v[158:159]
	s_add_i32 m0, s69, 0xe000
	s_nop 0
	global_load_lds_dwordx4 v[166:167], off
	s_waitcnt vmcnt(8)
	s_waitcnt lgkmcnt(0)
	s_barrier
	v_mfma_f32_16x16x32_bf16 v[126:129], v[130:133], v[188:191], v[126:129]
	v_mfma_f32_16x16x32_bf16 v[122:125], v[138:141], v[188:191], v[122:125]
	v_mfma_f32_16x16x32_bf16 v[110:113], v[130:133], v[206:209], v[110:113]
	v_mfma_f32_16x16x32_bf16 v[106:109], v[138:141], v[206:209], v[106:109]
	v_mfma_f32_16x16x32_bf16 v[92:95], v[130:133], v[226:229], v[92:95]
	v_mfma_f32_16x16x32_bf16 v[88:91], v[138:141], v[226:229], v[88:91]
	v_mfma_f32_16x16x32_bf16 v[76:79], v[130:133], v[234:237], v[76:79]
	v_mfma_f32_16x16x32_bf16 v[72:75], v[138:141], v[234:237], v[72:75]
	v_mfma_f32_16x16x32_bf16 v[126:129], v[134:137], v[202:205], v[126:129]
	v_mfma_f32_16x16x32_bf16 v[122:125], v[142:145], v[202:205], v[122:125]
	v_mfma_f32_16x16x32_bf16 v[110:113], v[134:137], v[212:215], v[110:113]
	v_mfma_f32_16x16x32_bf16 v[106:109], v[142:145], v[212:215], v[106:109]
	v_mfma_f32_16x16x32_bf16 v[92:95], v[134:137], v[230:233], v[92:95]
	v_mfma_f32_16x16x32_bf16 v[88:91], v[142:145], v[230:233], v[88:91]
	v_mfma_f32_16x16x32_bf16 v[76:79], v[134:137], v[238:241], v[76:79]
	v_mfma_f32_16x16x32_bf16 v[72:75], v[142:145], v[238:241], v[72:75]
	v_mfma_f32_16x16x32_bf16 v[118:121], v[162:165], v[188:191], v[118:121]
	v_mfma_f32_16x16x32_bf16 v[114:117], v[180:183], v[188:191], v[114:117]
	v_mfma_f32_16x16x32_bf16 v[102:105], v[162:165], v[206:209], v[102:105]
	v_mfma_f32_16x16x32_bf16 v[98:101], v[180:183], v[206:209], v[98:101]
	v_mfma_f32_16x16x32_bf16 v[84:87], v[162:165], v[226:229], v[84:87]
	v_mfma_f32_16x16x32_bf16 v[80:83], v[180:183], v[226:229], v[80:83]
	v_mfma_f32_16x16x32_bf16 v[68:71], v[162:165], v[234:237], v[68:71]
	v_mfma_f32_16x16x32_bf16 v[64:67], v[180:183], v[234:237], v[64:67]
	v_mfma_f32_16x16x32_bf16 v[118:121], v[176:179], v[202:205], v[118:121]
	v_mfma_f32_16x16x32_bf16 v[114:117], v[184:187], v[202:205], v[114:117]
	v_mfma_f32_16x16x32_bf16 v[102:105], v[176:179], v[212:215], v[102:105]
	v_mfma_f32_16x16x32_bf16 v[98:101], v[184:187], v[212:215], v[98:101]
	v_mfma_f32_16x16x32_bf16 v[84:87], v[176:179], v[230:233], v[84:87]
	v_mfma_f32_16x16x32_bf16 v[80:83], v[184:187], v[230:233], v[80:83]
	v_mfma_f32_16x16x32_bf16 v[68:71], v[176:179], v[238:241], v[68:71]
	v_mfma_f32_16x16x32_bf16 v[64:67], v[184:187], v[238:241], v[64:67]
	s_barrier
	s_add_i32 s12, s15, s68
	v_lshl_add_u64 v[166:167], s[18:19], 0, v[146:147]
	s_mov_b32 m0, s12
	ds_read_b128 v[188:191], v172 offset:16384
	ds_read_b128 v[202:205], v172 offset:17408
	ds_read_b128 v[206:209], v172 offset:18432
	ds_read_b128 v[212:215], v172 offset:19456
	ds_read_b128 v[226:229], v172 offset:20480
	ds_read_b128 v[230:233], v172 offset:21504
	ds_read_b128 v[234:237], v172 offset:22528
	ds_read_b128 v[238:241], v172 offset:23552
	global_load_lds_dwordx4 v[166:167], off
	s_add_i32 m0, s12, 0x2000
	s_add_u32 s12, s18, 0x80000
	v_lshl_add_u64 v[192:193], s[18:19], 0, v[148:149]
	s_addc_u32 s13, s19, 0
	s_add_i32 s15, s55, s68
	global_load_lds_dwordx4 v[192:193], off
	v_lshl_add_u64 v[196:197], s[12:13], 0, v[146:147]
	s_mov_b32 m0, s15
	v_lshl_add_u64 v[198:199], s[26:27], 0, v[148:149]
	global_load_lds_dwordx4 v[196:197], off
	v_lshl_add_u64 v[196:197], s[12:13], 0, v[148:149]
	s_add_i32 m0, s15, 0x2000
	s_nop 0
	global_load_lds_dwordx4 v[196:197], off
	v_lshl_add_u64 v[196:197], s[26:27], 0, v[146:147]
	s_mov_b32 m0, s69
	s_nop 0
	global_load_lds_dwordx4 v[196:197], off
	s_mov_b32 m0, s70
	s_nop 0
	global_load_lds_dwordx4 v[198:199], off
	s_waitcnt vmcnt(8)
	s_waitcnt lgkmcnt(0)
	s_barrier
; #define PG8_STAGE(bufoff, gbase, voff) do { _Pragma("unroll") for (int _i = 0; _i < 2; ++_i) \
;         __builtin_amdgcn_global_load_lds((const unsigned*)((const char*)(gbase) + (voff)[_i]), (PG8_LAS unsigned*)(lds + (bufoff) + ldsw + _i * 8192), 16, 0, 0); } while (0)
; #define PG8_LDA(dst, b, h) do { _Pragma("unroll") for (int m = 0; m < 4; ++m) _Pragma("unroll") for (int k = 0; k < 2; ++k) dst[m][k] = *(const PG8_LAS bf16x8*)(lds + PG8_SA(b, h) + aoff + m * 2048 + k * 1024); } while (0)
; #define PG8_LDB(dst, b, h) do { _Pragma("unroll") for (int n = 0; n < 2; ++n) _Pragma("unroll") for (int k = 0; k < 2; ++k) dst[n][k] = *(const PG8_LAS bf16x8*)(lds + PG8_SB(b, h) + boff + n * 2048 + k * 1024); } while (0)
; #define PG8_MMA(ai, bj, At, Bt) do { __builtin_amdgcn_s_setprio(1); _Pragma("unroll") for (int m = 0; m < 4; ++m) _Pragma("unroll") for (int n = 0; n < 2; ++n) _Pragma("unroll") for (int k = 0; k < 2; ++k) \
;         acc[ai][bj][m][n] = __builtin_amdgcn_mfma_f32_16x16x32_bf16(Bt[n][k], At[m][k], acc[ai][bj][m][n], 0, 0, 0); __builtin_amdgcn_s_setprio(0); } while (0)
; #define PG8_WAIT_V(n) asm volatile("s_waitcnt vmcnt(" #n ")" ::: "memory")
; #define PG8_WAIT_L(n) asm volatile("s_waitcnt lgkmcnt(" #n ")" ::: "memory")
; #define PG8_BAR __builtin_amdgcn_s_barrier()
; #define PG8_SCHED __builtin_amdgcn_sched_barrier(0)
; template <class Epi, class Sched, bool ALIGN_EPI, bool SP2, int KK, int LDA, int APN>
; __device__ __forceinline__ void gemm_phase(PG8_LAS unsigned char* lds, const Gemm g, const Sched& S, const Epi& E, const int wid) {
;     ...
;             PG8_WAIT_V(8); PG8_WAIT_L(0); PG8_BAR; PG8_MMA(1, 0, At, B0); PG8_MMA(1, 1, At, B1); PG8_BAR; PG8_SCHED;
;             PG8_LDB(B0, 1, 0); PG8_LDB(B1, 1, 1); PG8_SCHED; PG8_LDA(At, 1, 0); PG8_STAGE(PG8_SA(0, 1), a2 + hstepA, voffA);
;             PG8_WAIT_V(8); PG8_WAIT_L(0); PG8_BAR; PG8_MMA(0, 0, At, B0); PG8_MMA(0, 1, At, B1); PG8_BAR; PG8_SCHED;
;             PG8_LDA(At, 1, 1); PG8_STAGE(PG8_SB(1, 0), b3, voffB); PG8_STAGE(PG8_SB(1, 1), b3 + hstep, voffB); PG8_STAGE(PG8_SA(1, 0), a3, voffA);
	v_mfma_f32_16x16x32_bf16 v[60:63], v[130:133], v[188:191], v[60:63]
	v_mfma_f32_16x16x32_bf16 v[56:59], v[138:141], v[188:191], v[56:59]
	v_mfma_f32_16x16x32_bf16 v[44:47], v[130:133], v[206:209], v[44:47]
	v_mfma_f32_16x16x32_bf16 v[40:43], v[138:141], v[206:209], v[40:43]
	v_mfma_f32_16x16x32_bf16 v[28:31], v[130:133], v[226:229], v[28:31]
	v_mfma_f32_16x16x32_bf16 v[24:27], v[138:141], v[226:229], v[24:27]
	v_mfma_f32_16x16x32_bf16 v[12:15], v[130:133], v[234:237], v[12:15]
	v_mfma_f32_16x16x32_bf16 v[8:11], v[138:141], v[234:237], v[8:11]
	v_mfma_f32_16x16x32_bf16 v[60:63], v[134:137], v[202:205], v[60:63]
	v_mfma_f32_16x16x32_bf16 v[56:59], v[142:145], v[202:205], v[56:59]
	v_mfma_f32_16x16x32_bf16 v[44:47], v[134:137], v[212:215], v[44:47]
	v_mfma_f32_16x16x32_bf16 v[40:43], v[142:145], v[212:215], v[40:43]
	v_mfma_f32_16x16x32_bf16 v[28:31], v[134:137], v[230:233], v[28:31]
	v_mfma_f32_16x16x32_bf16 v[24:27], v[142:145], v[230:233], v[24:27]
	v_mfma_f32_16x16x32_bf16 v[12:15], v[134:137], v[238:241], v[12:15]
	v_mfma_f32_16x16x32_bf16 v[8:11], v[142:145], v[238:241], v[8:11]
	v_mfma_f32_16x16x32_bf16 v[52:55], v[162:165], v[188:191], v[52:55]
	v_mfma_f32_16x16x32_bf16 v[48:51], v[180:183], v[188:191], v[48:51]
	v_mfma_f32_16x16x32_bf16 v[36:39], v[162:165], v[206:209], v[36:39]
	v_mfma_f32_16x16x32_bf16 v[32:35], v[180:183], v[206:209], v[32:35]
	v_mfma_f32_16x16x32_bf16 v[20:23], v[162:165], v[226:229], v[20:23]
	v_mfma_f32_16x16x32_bf16 v[16:19], v[180:183], v[226:229], v[16:19]
	v_mfma_f32_16x16x32_bf16 v[4:7], v[162:165], v[234:237], v[4:7]
	v_mfma_f32_16x16x32_bf16 v[0:3], v[180:183], v[234:237], v[0:3]
	v_mfma_f32_16x16x32_bf16 v[52:55], v[176:179], v[202:205], v[52:55]
	v_mfma_f32_16x16x32_bf16 v[48:51], v[184:187], v[202:205], v[48:51]
	v_mfma_f32_16x16x32_bf16 v[36:39], v[176:179], v[212:215], v[36:39]
	v_mfma_f32_16x16x32_bf16 v[32:35], v[184:187], v[212:215], v[32:35]
	v_mfma_f32_16x16x32_bf16 v[20:23], v[176:179], v[230:233], v[20:23]
	v_mfma_f32_16x16x32_bf16 v[16:19], v[184:187], v[230:233], v[16:19]
	v_mfma_f32_16x16x32_bf16 v[4:7], v[176:179], v[238:241], v[4:7]
	v_mfma_f32_16x16x32_bf16 v[0:3], v[184:187], v[238:241], v[0:3]
	s_barrier
	s_add_i32 s15, 0, 0x18000
	s_add_i32 s55, 0, 0x1c000
	v_add_u32_e32 v142, s15, v169
	v_add_u32_e32 v175, s55, v169
	ds_read_b128 v[130:133], v142
	ds_read_b128 v[134:137], v142 offset:1024
	ds_read_b128 v[138:141], v142 offset:2048
	ds_read_b128 v[142:145], v142 offset:3072
	ds_read_b128 v[162:165], v175
	ds_read_b128 v[176:179], v175 offset:1024
	ds_read_b128 v[180:183], v175 offset:2048
	ds_read_b128 v[184:187], v175 offset:3072
	s_add_u32 s12, s26, 0x80000
	s_addc_u32 s13, s27, 0
	s_mov_b32 m0, s71
	v_lshl_add_u64 v[216:217], s[12:13], 0, v[146:147]
	ds_read_b128 v[188:191], v172 offset:32768
	ds_read_b128 v[202:205], v172 offset:33792
	ds_read_b128 v[206:209], v172 offset:34816
	ds_read_b128 v[212:215], v172 offset:35840
	ds_read_b128 v[226:229], v172 offset:36864
	ds_read_b128 v[230:233], v172 offset:37888
	ds_read_b128 v[234:237], v172 offset:38912
	ds_read_b128 v[238:241], v172 offset:39936
	global_load_lds_dwordx4 v[216:217], off
	v_lshl_add_u64 v[216:217], s[12:13], 0, v[148:149]
	s_mov_b32 m0, s72
	s_nop 0
	global_load_lds_dwordx4 v[216:217], off
	s_waitcnt vmcnt(8)
	s_waitcnt lgkmcnt(0)
	s_barrier
	v_mfma_f32_16x16x32_bf16 v[126:129], v[130:133], v[188:191], v[126:129]
	v_mfma_f32_16x16x32_bf16 v[122:125], v[138:141], v[188:191], v[122:125]
	v_mfma_f32_16x16x32_bf16 v[110:113], v[130:133], v[206:209], v[110:113]
	v_mfma_f32_16x16x32_bf16 v[106:109], v[138:141], v[206:209], v[106:109]
	v_mfma_f32_16x16x32_bf16 v[92:95], v[130:133], v[226:229], v[92:95]
	v_mfma_f32_16x16x32_bf16 v[88:91], v[138:141], v[226:229], v[88:91]
	v_mfma_f32_16x16x32_bf16 v[76:79], v[130:133], v[234:237], v[76:79]
	v_mfma_f32_16x16x32_bf16 v[72:75], v[138:141], v[234:237], v[72:75]
	v_mfma_f32_16x16x32_bf16 v[126:129], v[134:137], v[202:205], v[126:129]
	v_mfma_f32_16x16x32_bf16 v[122:125], v[142:145], v[202:205], v[122:125]
	v_mfma_f32_16x16x32_bf16 v[110:113], v[134:137], v[212:215], v[110:113]
	v_mfma_f32_16x16x32_bf16 v[106:109], v[142:145], v[212:215], v[106:109]
	v_mfma_f32_16x16x32_bf16 v[92:95], v[134:137], v[230:233], v[92:95]
	v_mfma_f32_16x16x32_bf16 v[88:91], v[142:145], v[230:233], v[88:91]
	v_mfma_f32_16x16x32_bf16 v[76:79], v[134:137], v[238:241], v[76:79]
	v_mfma_f32_16x16x32_bf16 v[72:75], v[142:145], v[238:241], v[72:75]
	v_mfma_f32_16x16x32_bf16 v[118:121], v[162:165], v[188:191], v[118:121]
	v_mfma_f32_16x16x32_bf16 v[114:117], v[180:183], v[188:191], v[114:117]
	v_mfma_f32_16x16x32_bf16 v[102:105], v[162:165], v[206:209], v[102:105]
	v_mfma_f32_16x16x32_bf16 v[98:101], v[180:183], v[206:209], v[98:101]
	v_mfma_f32_16x16x32_bf16 v[84:87], v[162:165], v[226:229], v[84:87]
	v_mfma_f32_16x16x32_bf16 v[80:83], v[180:183], v[226:229], v[80:83]
	v_mfma_f32_16x16x32_bf16 v[68:71], v[162:165], v[234:237], v[68:71]
	v_mfma_f32_16x16x32_bf16 v[64:67], v[180:183], v[234:237], v[64:67]
	v_mfma_f32_16x16x32_bf16 v[118:121], v[176:179], v[202:205], v[118:121]
	v_mfma_f32_16x16x32_bf16 v[114:117], v[184:187], v[202:205], v[114:117]
	v_mfma_f32_16x16x32_bf16 v[102:105], v[176:179], v[212:215], v[102:105]
	v_mfma_f32_16x16x32_bf16 v[98:101], v[184:187], v[212:215], v[98:101]
	v_mfma_f32_16x16x32_bf16 v[84:87], v[176:179], v[230:233], v[84:87]
	v_mfma_f32_16x16x32_bf16 v[80:83], v[184:187], v[230:233], v[80:83]
	v_mfma_f32_16x16x32_bf16 v[68:71], v[176:179], v[238:241], v[68:71]
	v_mfma_f32_16x16x32_bf16 v[64:67], v[184:187], v[238:241], v[64:67]
	s_barrier
; #define PG8_STAGE(bufoff, gbase, voff) do { _Pragma("unroll") for (int _i = 0; _i < 2; ++_i) \
;         __builtin_amdgcn_global_load_lds((const unsigned*)((const char*)(gbase) + (voff)[_i]), (PG8_LAS unsigned*)(lds + (bufoff) + ldsw + _i * 8192), 16, 0, 0); } while (0)
; #define PG8_LDA(dst, b, h) do { _Pragma("unroll") for (int m = 0; m < 4; ++m) _Pragma("unroll") for (int k = 0; k < 2; ++k) dst[m][k] = *(const PG8_LAS bf16x8*)(lds + PG8_SA(b, h) + aoff + m * 2048 + k * 1024); } while (0)
; #define PG8_MMA(ai, bj, At, Bt) do { __builtin_amdgcn_s_setprio(1); _Pragma("unroll") for (int m = 0; m < 4; ++m) _Pragma("unroll") for (int n = 0; n < 2; ++n) _Pragma("unroll") for (int k = 0; k < 2; ++k) \
;         acc[ai][bj][m][n] = __builtin_amdgcn_mfma_f32_16x16x32_bf16(Bt[n][k], At[m][k], acc[ai][bj][m][n], 0, 0, 0); __builtin_amdgcn_s_setprio(0); } while (0)
; #define PG8_WAIT_V(n) asm volatile("s_waitcnt vmcnt(" #n ")" ::: "memory")
; #define PG8_WAIT_L(n) asm volatile("s_waitcnt lgkmcnt(" #n ")" ::: "memory")
; #define PG8_BAR __builtin_amdgcn_s_barrier()
; #define PG8_SCHED __builtin_amdgcn_sched_barrier(0)
; template <class Epi, class Sched, bool ALIGN_EPI, bool SP2, int KK, int LDA, int APN>
; __device__ __forceinline__ void gemm_phase(PG8_LAS unsigned char* lds, const Gemm g, const Sched& S, const Epi& E, const int wid) {
;     ...
;             PG8_LDA(At, 1, 1); PG8_STAGE(PG8_SB(1, 0), b3, voffB); PG8_STAGE(PG8_SB(1, 1), b3 + hstep, voffB); PG8_STAGE(PG8_SA(1, 0), a3, voffA);
;             PG8_WAIT_V(8); PG8_WAIT_L(0); PG8_BAR; PG8_MMA(1, 0, At, B0); PG8_MMA(1, 1, At, B1); PG8_BAR; PG8_SCHED;
;     ...
;         }
;         if constexpr (ALIGN_EPI) { if (wr == 0) PG8_BAR; }
	s_add_i32 s12, s15, s68
	v_lshl_add_u64 v[166:167], v[166:167], 0, s[22:23]
	s_mov_b32 m0, s12
	ds_read_b128 v[188:191], v172 offset:49152
	ds_read_b128 v[202:205], v172 offset:50176
	ds_read_b128 v[206:209], v172 offset:51200
	ds_read_b128 v[212:215], v172 offset:52224
	ds_read_b128 v[226:229], v172 offset:53248
	ds_read_b128 v[230:233], v172 offset:54272
	ds_read_b128 v[234:237], v172 offset:55296
	ds_read_b128 v[238:241], v172 offset:56320
	global_load_lds_dwordx4 v[166:167], off
	s_add_i32 m0, s12, 0x2000
	s_add_u32 s12, s18, 0x80080
	v_lshl_add_u64 v[166:167], v[192:193], 0, s[22:23]
	s_addc_u32 s13, s19, 0
	s_add_i32 s15, s55, s68
	global_load_lds_dwordx4 v[166:167], off
	v_lshl_add_u64 v[166:167], s[12:13], 0, v[146:147]
	s_mov_b32 m0, s15
	s_nop 0
	global_load_lds_dwordx4 v[166:167], off
	v_lshl_add_u64 v[166:167], s[12:13], 0, v[148:149]
	s_add_i32 m0, s15, 0x2000
	s_nop 0
	global_load_lds_dwordx4 v[166:167], off
	v_lshl_add_u64 v[166:167], v[196:197], 0, s[22:23]
	s_mov_b32 m0, s73
	s_nop 0
	global_load_lds_dwordx4 v[166:167], off
	v_lshl_add_u64 v[166:167], v[198:199], 0, s[22:23]
	s_mov_b32 m0, s78
	s_nop 0
	global_load_lds_dwordx4 v[166:167], off
	s_waitcnt vmcnt(8)
	s_waitcnt lgkmcnt(0)
	s_barrier
	v_mfma_f32_16x16x32_bf16 v[60:63], v[130:133], v[188:191], v[60:63]
	v_mfma_f32_16x16x32_bf16 v[56:59], v[138:141], v[188:191], v[56:59]
	v_mfma_f32_16x16x32_bf16 v[44:47], v[130:133], v[206:209], v[44:47]
	v_mfma_f32_16x16x32_bf16 v[40:43], v[138:141], v[206:209], v[40:43]
	v_mfma_f32_16x16x32_bf16 v[28:31], v[130:133], v[226:229], v[28:31]
	v_mfma_f32_16x16x32_bf16 v[24:27], v[138:141], v[226:229], v[24:27]
	v_mfma_f32_16x16x32_bf16 v[12:15], v[130:133], v[234:237], v[12:15]
	v_mfma_f32_16x16x32_bf16 v[8:11], v[138:141], v[234:237], v[8:11]
	v_mfma_f32_16x16x32_bf16 v[60:63], v[134:137], v[202:205], v[60:63]
	v_mfma_f32_16x16x32_bf16 v[56:59], v[142:145], v[202:205], v[56:59]
	v_mfma_f32_16x16x32_bf16 v[44:47], v[134:137], v[212:215], v[44:47]
	v_mfma_f32_16x16x32_bf16 v[40:43], v[142:145], v[212:215], v[40:43]
	v_mfma_f32_16x16x32_bf16 v[28:31], v[134:137], v[230:233], v[28:31]
	v_mfma_f32_16x16x32_bf16 v[24:27], v[142:145], v[230:233], v[24:27]
	v_mfma_f32_16x16x32_bf16 v[12:15], v[134:137], v[238:241], v[12:15]
	v_mfma_f32_16x16x32_bf16 v[8:11], v[142:145], v[238:241], v[8:11]
	v_mfma_f32_16x16x32_bf16 v[52:55], v[162:165], v[188:191], v[52:55]
	v_mfma_f32_16x16x32_bf16 v[48:51], v[180:183], v[188:191], v[48:51]
	v_mfma_f32_16x16x32_bf16 v[36:39], v[162:165], v[206:209], v[36:39]
	v_mfma_f32_16x16x32_bf16 v[32:35], v[180:183], v[206:209], v[32:35]
	v_mfma_f32_16x16x32_bf16 v[20:23], v[162:165], v[226:229], v[20:23]
	v_mfma_f32_16x16x32_bf16 v[16:19], v[180:183], v[226:229], v[16:19]
	v_mfma_f32_16x16x32_bf16 v[4:7], v[162:165], v[234:237], v[4:7]
	v_mfma_f32_16x16x32_bf16 v[0:3], v[180:183], v[234:237], v[0:3]
	v_mfma_f32_16x16x32_bf16 v[52:55], v[176:179], v[202:205], v[52:55]
	v_mfma_f32_16x16x32_bf16 v[48:51], v[184:187], v[202:205], v[48:51]
	v_mfma_f32_16x16x32_bf16 v[36:39], v[176:179], v[212:215], v[36:39]
	v_mfma_f32_16x16x32_bf16 v[32:35], v[184:187], v[212:215], v[32:35]
	v_mfma_f32_16x16x32_bf16 v[20:23], v[176:179], v[230:233], v[20:23]
	v_mfma_f32_16x16x32_bf16 v[16:19], v[184:187], v[230:233], v[16:19]
	v_mfma_f32_16x16x32_bf16 v[4:7], v[176:179], v[238:241], v[4:7]
	v_mfma_f32_16x16x32_bf16 v[0:3], v[184:187], v[238:241], v[0:3]
	s_barrier
	s_add_i32 s11, s11, 2
	s_add_u32 s9, s9, 0x100
	s_addc_u32 s10, s10, 0
	s_add_u32 s16, s16, 0x100
	s_addc_u32 s17, s17, 0
	s_cmp_gt_u32 s11, 29
	s_cbranch_scc0 .LBB0_406
	s_and_b64 vcc, exec, s[50:51]
	s_cbranch_vccz .LBB0_409
	s_barrier

; #define PG8_STAGE(bufoff, gbase, voff) do { _Pragma("unroll") for (int _i = 0; _i < 2; ++_i) \
;         __builtin_amdgcn_global_load_lds((const unsigned*)((const char*)(gbase) + (voff)[_i]), (PG8_LAS unsigned*)(lds + (bufoff) + ldsw + _i * 8192), 16, 0, 0); } while (0)
; #define PG8_LDA(dst, b, h) do { _Pragma("unroll") for (int m = 0; m < 4; ++m) _Pragma("unroll") for (int k = 0; k < 2; ++k) dst[m][k] = *(const PG8_LAS bf16x8*)(lds + PG8_SA(b, h) + aoff + m * 2048 + k * 1024); } while (0)
; #define PG8_LDB(dst, b, h) do { _Pragma("unroll") for (int n = 0; n < 2; ++n) _Pragma("unroll") for (int k = 0; k < 2; ++k) dst[n][k] = *(const PG8_LAS bf16x8*)(lds + PG8_SB(b, h) + boff + n * 2048 + k * 1024); } while (0)
; #define PG8_MMA(ai, bj, At, Bt) do { __builtin_amdgcn_s_setprio(1); _Pragma("unroll") for (int m = 0; m < 4; ++m) _Pragma("unroll") for (int n = 0; n < 2; ++n) _Pragma("unroll") for (int k = 0; k < 2; ++k) \
;         acc[ai][bj][m][n] = __builtin_amdgcn_mfma_f32_16x16x32_bf16(Bt[n][k], At[m][k], acc[ai][bj][m][n], 0, 0, 0); __builtin_amdgcn_s_setprio(0); } while (0)
; #define PG8_WAIT_V(n) asm volatile("s_waitcnt vmcnt(" #n ")" ::: "memory")
; #define PG8_BAR __builtin_amdgcn_s_barrier()
; template <class Epi, class Sched, bool ALIGN_EPI, bool SP2, int KK, int LDA, int APN>
; __device__ __forceinline__ void gemm_phase(PG8_LAS unsigned char* lds, const Gemm g, const Sched& S, const Epi& E, const int wid) {
;     ...
;         for (int t = 0; t < nt; t += 2) {
;             const bool last = (t == nt - 2);
;             const char* a1 = cA + (size_t)(t + 1) * kstep;
;             const char* a2 = last ? nA : cA + (size_t)(t + 2) * kstep; const char* b2 = last ? nB : cB + (size_t)(t + 2) * kstep;
;             const char* a3 = a2 + kstep; const char* b3 = b2 + kstep;
;             if (last && has_next) S.a_ready(nxt);
;             if constexpr (SP2) {
;             PG8_LDB(B0, 0, 0); PG8_LDB(B1, 0, 1); PG8_SCHED; PG8_LDA(At, 0, 0); PG8_STAGE(PG8_SA(1, 1), a1 + hstepA, voffA);
;             PG8_WAIT_V(8); PG8_WAIT_L(0); PG8_BAR; PG8_MMA(0, 0, At, B0); PG8_MMA(0, 1, At, B1); PG8_BAR; PG8_SCHED;
;             PG8_LDA(At, 0, 1); PG8_STAGE(PG8_SB(0, 0), b2, voffB); PG8_STAGE(PG8_SB(0, 1), b2 + hstep, voffB); PG8_STAGE(PG8_SA(0, 0), a2, voffA);
;             PG8_WAIT_V(8); PG8_WAIT_L(0); PG8_BAR; PG8_MMA(1, 0, At, B0); PG8_MMA(1, 1, At, B1); PG8_BAR; PG8_SCHED;
.LBB0_686:
	s_add_u32 s52, s28, s50
	s_addc_u32 s53, s29, s51
	s_add_u32 s52, s52, 0x100
	s_addc_u32 s53, s53, 0
	s_add_u32 s69, s67, s50
	s_addc_u32 s70, s68, s51
	s_add_i32 s71, 0, 0x10000
	s_cmpk_eq_i32 s50, 0xf00
	s_cselect_b32 s55, s19, s53
	s_cselect_b32 s54, s40, s52
	v_add_u32_e32 v144, s71, v148
	s_cselect_b32 s53, s41, s70
	s_cselect_b32 s52, s43, s69
	s_add_i32 s69, 0, 0x14000
	ds_read_b128 v[154:157], v144
	ds_read_b128 v[158:161], v144 offset:1024
	ds_read_b128 v[162:165], v144 offset:2048
	ds_read_b128 v[166:169], v144 offset:3072
	v_add_u32_e32 v144, s69, v148
	ds_read_b128 v[170:173], v144
	ds_read_b128 v[174:177], v144 offset:1024
	ds_read_b128 v[178:181], v144 offset:2048
	ds_read_b128 v[182:185], v144 offset:3072
	v_lshl_add_u64 v[144:145], v[142:143], 0, s[50:51]
	s_add_i32 m0, s13, 0xc000
	ds_read_b128 v[186:189], v150
	ds_read_b128 v[190:193], v150 offset:1024
	ds_read_b128 v[196:199], v150 offset:2048
	ds_read_b128 v[202:205], v150 offset:3072
	ds_read_b128 v[206:209], v150 offset:4096
	ds_read_b128 v[212:215], v150 offset:5120
	ds_read_b128 v[226:229], v150 offset:6144
	ds_read_b128 v[230:233], v150 offset:7168
	global_load_lds_dwordx4 v[144:145], off
	v_lshl_add_u64 v[144:145], v[140:141], 0, s[50:51]
	s_add_i32 m0, s13, 0xe000
	s_nop 0
	global_load_lds_dwordx4 v[144:145], off
	s_waitcnt vmcnt(8)
	s_waitcnt lgkmcnt(0)
	s_barrier
	v_mfma_f32_16x16x32_bf16 v[0:3], v[154:157], v[186:189], v[0:3]
	v_mfma_f32_16x16x32_bf16 v[4:7], v[162:165], v[186:189], v[4:7]
	v_mfma_f32_16x16x32_bf16 v[16:19], v[154:157], v[196:199], v[16:19]
	v_mfma_f32_16x16x32_bf16 v[20:23], v[162:165], v[196:199], v[20:23]
	v_mfma_f32_16x16x32_bf16 v[32:35], v[154:157], v[206:209], v[32:35]
	v_mfma_f32_16x16x32_bf16 v[36:39], v[162:165], v[206:209], v[36:39]
	v_mfma_f32_16x16x32_bf16 v[48:51], v[154:157], v[226:229], v[48:51]
	v_mfma_f32_16x16x32_bf16 v[52:55], v[162:165], v[226:229], v[52:55]
	v_mfma_f32_16x16x32_bf16 v[0:3], v[158:161], v[190:193], v[0:3]
	v_mfma_f32_16x16x32_bf16 v[4:7], v[166:169], v[190:193], v[4:7]
	v_mfma_f32_16x16x32_bf16 v[16:19], v[158:161], v[202:205], v[16:19]
	v_mfma_f32_16x16x32_bf16 v[20:23], v[166:169], v[202:205], v[20:23]
	v_mfma_f32_16x16x32_bf16 v[32:35], v[158:161], v[212:215], v[32:35]
	v_mfma_f32_16x16x32_bf16 v[36:39], v[166:169], v[212:215], v[36:39]
	v_mfma_f32_16x16x32_bf16 v[48:51], v[158:161], v[230:233], v[48:51]
	v_mfma_f32_16x16x32_bf16 v[52:55], v[166:169], v[230:233], v[52:55]
	v_mfma_f32_16x16x32_bf16 v[8:11], v[170:173], v[186:189], v[8:11]
	v_mfma_f32_16x16x32_bf16 v[12:15], v[178:181], v[186:189], v[12:15]
	v_mfma_f32_16x16x32_bf16 v[24:27], v[170:173], v[196:199], v[24:27]
	v_mfma_f32_16x16x32_bf16 v[28:31], v[178:181], v[196:199], v[28:31]
	v_mfma_f32_16x16x32_bf16 v[40:43], v[170:173], v[206:209], v[40:43]
	v_mfma_f32_16x16x32_bf16 v[44:47], v[178:181], v[206:209], v[44:47]
	v_mfma_f32_16x16x32_bf16 v[56:59], v[170:173], v[226:229], v[56:59]
	v_mfma_f32_16x16x32_bf16 v[60:63], v[178:181], v[226:229], v[60:63]
	v_mfma_f32_16x16x32_bf16 v[8:11], v[174:177], v[190:193], v[8:11]
	v_mfma_f32_16x16x32_bf16 v[12:15], v[182:185], v[190:193], v[12:15]
	v_mfma_f32_16x16x32_bf16 v[24:27], v[174:177], v[202:205], v[24:27]
	v_mfma_f32_16x16x32_bf16 v[28:31], v[182:185], v[202:205], v[28:31]
	v_mfma_f32_16x16x32_bf16 v[40:43], v[174:177], v[212:215], v[40:43]
	v_mfma_f32_16x16x32_bf16 v[44:47], v[182:185], v[212:215], v[44:47]
	v_mfma_f32_16x16x32_bf16 v[56:59], v[174:177], v[230:233], v[56:59]
	v_mfma_f32_16x16x32_bf16 v[60:63], v[182:185], v[230:233], v[60:63]
	s_barrier
	s_add_i32 s70, s71, s12
	v_lshl_add_u64 v[144:145], s[52:53], 0, v[96:97]
	s_mov_b32 m0, s70
	ds_read_b128 v[186:189], v150 offset:16384
	ds_read_b128 v[190:193], v150 offset:17408
	ds_read_b128 v[196:199], v150 offset:18432
	ds_read_b128 v[202:205], v150 offset:19456
	ds_read_b128 v[206:209], v150 offset:20480
	ds_read_b128 v[212:215], v150 offset:21504
	ds_read_b128 v[226:229], v150 offset:22528
	ds_read_b128 v[230:233], v150 offset:23552
	global_load_lds_dwordx4 v[144:145], off
	s_add_i32 m0, s70, 0x2000
	s_add_u32 s70, s52, 0x80000
	v_lshl_add_u64 v[216:217], s[52:53], 0, v[134:135]
	s_addc_u32 s71, s53, 0
	s_add_i32 s69, s69, s12
	global_load_lds_dwordx4 v[216:217], off
	v_lshl_add_u64 v[234:235], s[70:71], 0, v[96:97]
	s_mov_b32 m0, s69
	v_lshl_add_u64 v[236:237], s[54:55], 0, v[132:133]
	global_load_lds_dwordx4 v[234:235], off
	v_lshl_add_u64 v[234:235], s[70:71], 0, v[134:135]
	s_add_i32 m0, s69, 0x2000
	s_nop 0
	global_load_lds_dwordx4 v[234:235], off
	v_lshl_add_u64 v[234:235], s[54:55], 0, v[130:131]
	s_mov_b32 m0, s13
	s_nop 0
	global_load_lds_dwordx4 v[234:235], off
	s_mov_b32 m0, s17
	s_nop 0
	global_load_lds_dwordx4 v[236:237], off
	s_waitcnt vmcnt(8)
	s_waitcnt lgkmcnt(0)
	s_barrier
; #define PG8_STAGE(bufoff, gbase, voff) do { _Pragma("unroll") for (int _i = 0; _i < 2; ++_i) \
;         __builtin_amdgcn_global_load_lds((const unsigned*)((const char*)(gbase) + (voff)[_i]), (PG8_LAS unsigned*)(lds + (bufoff) + ldsw + _i * 8192), 16, 0, 0); } while (0)
; #define PG8_LDA(dst, b, h) do { _Pragma("unroll") for (int m = 0; m < 4; ++m) _Pragma("unroll") for (int k = 0; k < 2; ++k) dst[m][k] = *(const PG8_LAS bf16x8*)(lds + PG8_SA(b, h) + aoff + m * 2048 + k * 1024); } while (0)
; #define PG8_LDB(dst, b, h) do { _Pragma("unroll") for (int n = 0; n < 2; ++n) _Pragma("unroll") for (int k = 0; k < 2; ++k) dst[n][k] = *(const PG8_LAS bf16x8*)(lds + PG8_SB(b, h) + boff + n * 2048 + k * 1024); } while (0)
; #define PG8_MMA(ai, bj, At, Bt) do { __builtin_amdgcn_s_setprio(1); _Pragma("unroll") for (int m = 0; m < 4; ++m) _Pragma("unroll") for (int n = 0; n < 2; ++n) _Pragma("unroll") for (int k = 0; k < 2; ++k) \
;         acc[ai][bj][m][n] = __builtin_amdgcn_mfma_f32_16x16x32_bf16(Bt[n][k], At[m][k], acc[ai][bj][m][n], 0, 0, 0); __builtin_amdgcn_s_setprio(0); } while (0)
; #define PG8_WAIT_V(n) asm volatile("s_waitcnt vmcnt(" #n ")" ::: "memory")
; #define PG8_WAIT_L(n) asm volatile("s_waitcnt lgkmcnt(" #n ")" ::: "memory")
; #define PG8_BAR __builtin_amdgcn_s_barrier()
; #define PG8_SCHED __builtin_amdgcn_sched_barrier(0)
; template <class Epi, class Sched, bool ALIGN_EPI, bool SP2, int KK, int LDA, int APN>
; __device__ __forceinline__ void gemm_phase(PG8_LAS unsigned char* lds, const Gemm g, const Sched& S, const Epi& E, const int wid) {
;     ...
;             PG8_WAIT_V(8); PG8_WAIT_L(0); PG8_BAR; PG8_MMA(1, 0, At, B0); PG8_MMA(1, 1, At, B1); PG8_BAR; PG8_SCHED;
;             PG8_LDB(B0, 1, 0); PG8_LDB(B1, 1, 1); PG8_SCHED; PG8_LDA(At, 1, 0); PG8_STAGE(PG8_SA(0, 1), a2 + hstepA, voffA);
;             PG8_WAIT_V(8); PG8_WAIT_L(0); PG8_BAR; PG8_MMA(0, 0, At, B0); PG8_MMA(0, 1, At, B1); PG8_BAR; PG8_SCHED;
;             PG8_LDA(At, 1, 1); PG8_STAGE(PG8_SB(1, 0), b3, voffB); PG8_STAGE(PG8_SB(1, 1), b3 + hstep, voffB); PG8_STAGE(PG8_SA(1, 0), a3, voffA);
	v_mfma_f32_16x16x32_bf16 v[64:67], v[154:157], v[186:189], v[64:67]
	v_mfma_f32_16x16x32_bf16 v[68:71], v[162:165], v[186:189], v[68:71]
	v_mfma_f32_16x16x32_bf16 v[80:83], v[154:157], v[196:199], v[80:83]
	v_mfma_f32_16x16x32_bf16 v[84:87], v[162:165], v[196:199], v[84:87]
	v_mfma_f32_16x16x32_bf16 v[98:101], v[154:157], v[206:209], v[98:101]
	v_mfma_f32_16x16x32_bf16 v[102:105], v[162:165], v[206:209], v[102:105]
	v_mfma_f32_16x16x32_bf16 v[114:117], v[154:157], v[226:229], v[114:117]
	v_mfma_f32_16x16x32_bf16 v[118:121], v[162:165], v[226:229], v[118:121]
	v_mfma_f32_16x16x32_bf16 v[64:67], v[158:161], v[190:193], v[64:67]
	v_mfma_f32_16x16x32_bf16 v[68:71], v[166:169], v[190:193], v[68:71]
	v_mfma_f32_16x16x32_bf16 v[80:83], v[158:161], v[202:205], v[80:83]
	v_mfma_f32_16x16x32_bf16 v[84:87], v[166:169], v[202:205], v[84:87]
	v_mfma_f32_16x16x32_bf16 v[98:101], v[158:161], v[212:215], v[98:101]
	v_mfma_f32_16x16x32_bf16 v[102:105], v[166:169], v[212:215], v[102:105]
	v_mfma_f32_16x16x32_bf16 v[114:117], v[158:161], v[230:233], v[114:117]
	v_mfma_f32_16x16x32_bf16 v[118:121], v[166:169], v[230:233], v[118:121]
	v_mfma_f32_16x16x32_bf16 v[72:75], v[170:173], v[186:189], v[72:75]
	v_mfma_f32_16x16x32_bf16 v[76:79], v[178:181], v[186:189], v[76:79]
	v_mfma_f32_16x16x32_bf16 v[88:91], v[170:173], v[196:199], v[88:91]
	v_mfma_f32_16x16x32_bf16 v[92:95], v[178:181], v[196:199], v[92:95]
	v_mfma_f32_16x16x32_bf16 v[106:109], v[170:173], v[206:209], v[106:109]
	v_mfma_f32_16x16x32_bf16 v[110:113], v[178:181], v[206:209], v[110:113]
	v_mfma_f32_16x16x32_bf16 v[122:125], v[170:173], v[226:229], v[122:125]
	v_mfma_f32_16x16x32_bf16 v[126:129], v[178:181], v[226:229], v[126:129]
	v_mfma_f32_16x16x32_bf16 v[72:75], v[174:177], v[190:193], v[72:75]
	v_mfma_f32_16x16x32_bf16 v[76:79], v[182:185], v[190:193], v[76:79]
	v_mfma_f32_16x16x32_bf16 v[88:91], v[174:177], v[202:205], v[88:91]
	v_mfma_f32_16x16x32_bf16 v[92:95], v[182:185], v[202:205], v[92:95]
	v_mfma_f32_16x16x32_bf16 v[106:109], v[174:177], v[212:215], v[106:109]
	v_mfma_f32_16x16x32_bf16 v[110:113], v[182:185], v[212:215], v[110:113]
	v_mfma_f32_16x16x32_bf16 v[122:125], v[174:177], v[230:233], v[122:125]
	v_mfma_f32_16x16x32_bf16 v[126:129], v[182:185], v[230:233], v[126:129]
	s_barrier
	s_add_i32 s69, 0, 0x18000
	v_add_u32_e32 v153, s69, v148
	s_add_i32 s70, 0, 0x1c000
	ds_read_b128 v[154:157], v153
	ds_read_b128 v[158:161], v153 offset:1024
	ds_read_b128 v[162:165], v153 offset:2048
	ds_read_b128 v[166:169], v153 offset:3072
	v_add_u32_e32 v153, s70, v148
	ds_read_b128 v[170:173], v153
	ds_read_b128 v[174:177], v153 offset:1024
	ds_read_b128 v[178:181], v153 offset:2048
	ds_read_b128 v[182:185], v153 offset:3072
	s_add_u32 s54, s54, 0x80000
	s_addc_u32 s55, s55, 0
	s_mov_b32 m0, s56
	v_lshl_add_u64 v[238:239], s[54:55], 0, v[130:131]
	ds_read_b128 v[186:189], v150 offset:32768
	ds_read_b128 v[190:193], v150 offset:33792
	ds_read_b128 v[196:199], v150 offset:34816
	ds_read_b128 v[202:205], v150 offset:35840
	ds_read_b128 v[206:209], v150 offset:36864
	ds_read_b128 v[212:215], v150 offset:37888
	ds_read_b128 v[226:229], v150 offset:38912
	ds_read_b128 v[230:233], v150 offset:39936
	global_load_lds_dwordx4 v[238:239], off
	v_lshl_add_u64 v[238:239], s[54:55], 0, v[132:133]
	s_mov_b32 m0, s57
	s_nop 0
	global_load_lds_dwordx4 v[238:239], off
	s_waitcnt vmcnt(8)
	s_waitcnt lgkmcnt(0)
	s_barrier
	v_mfma_f32_16x16x32_bf16 v[0:3], v[154:157], v[186:189], v[0:3]
	v_mfma_f32_16x16x32_bf16 v[4:7], v[162:165], v[186:189], v[4:7]
	v_mfma_f32_16x16x32_bf16 v[16:19], v[154:157], v[196:199], v[16:19]
	v_mfma_f32_16x16x32_bf16 v[20:23], v[162:165], v[196:199], v[20:23]
	v_mfma_f32_16x16x32_bf16 v[32:35], v[154:157], v[206:209], v[32:35]
	v_mfma_f32_16x16x32_bf16 v[36:39], v[162:165], v[206:209], v[36:39]
	v_mfma_f32_16x16x32_bf16 v[48:51], v[154:157], v[226:229], v[48:51]
	v_mfma_f32_16x16x32_bf16 v[52:55], v[162:165], v[226:229], v[52:55]
	v_mfma_f32_16x16x32_bf16 v[0:3], v[158:161], v[190:193], v[0:3]
	v_mfma_f32_16x16x32_bf16 v[4:7], v[166:169], v[190:193], v[4:7]
	v_mfma_f32_16x16x32_bf16 v[16:19], v[158:161], v[202:205], v[16:19]
	v_mfma_f32_16x16x32_bf16 v[20:23], v[166:169], v[202:205], v[20:23]
	v_mfma_f32_16x16x32_bf16 v[32:35], v[158:161], v[212:215], v[32:35]
	v_mfma_f32_16x16x32_bf16 v[36:39], v[166:169], v[212:215], v[36:39]
	v_mfma_f32_16x16x32_bf16 v[48:51], v[158:161], v[230:233], v[48:51]
	v_mfma_f32_16x16x32_bf16 v[52:55], v[166:169], v[230:233], v[52:55]
	v_mfma_f32_16x16x32_bf16 v[8:11], v[170:173], v[186:189], v[8:11]
	v_mfma_f32_16x16x32_bf16 v[12:15], v[178:181], v[186:189], v[12:15]
	v_mfma_f32_16x16x32_bf16 v[24:27], v[170:173], v[196:199], v[24:27]
	v_mfma_f32_16x16x32_bf16 v[28:31], v[178:181], v[196:199], v[28:31]
	v_mfma_f32_16x16x32_bf16 v[40:43], v[170:173], v[206:209], v[40:43]
	v_mfma_f32_16x16x32_bf16 v[44:47], v[178:181], v[206:209], v[44:47]
	v_mfma_f32_16x16x32_bf16 v[56:59], v[170:173], v[226:229], v[56:59]
	v_mfma_f32_16x16x32_bf16 v[60:63], v[178:181], v[226:229], v[60:63]
	v_mfma_f32_16x16x32_bf16 v[8:11], v[174:177], v[190:193], v[8:11]
	v_mfma_f32_16x16x32_bf16 v[12:15], v[182:185], v[190:193], v[12:15]
	v_mfma_f32_16x16x32_bf16 v[24:27], v[174:177], v[202:205], v[24:27]
	v_mfma_f32_16x16x32_bf16 v[28:31], v[182:185], v[202:205], v[28:31]
	v_mfma_f32_16x16x32_bf16 v[40:43], v[174:177], v[212:215], v[40:43]
	v_mfma_f32_16x16x32_bf16 v[44:47], v[182:185], v[212:215], v[44:47]
	v_mfma_f32_16x16x32_bf16 v[56:59], v[174:177], v[230:233], v[56:59]
	v_mfma_f32_16x16x32_bf16 v[60:63], v[182:185], v[230:233], v[60:63]
	s_barrier
; #define PG8_STAGE(bufoff, gbase, voff) do { _Pragma("unroll") for (int _i = 0; _i < 2; ++_i) \
;         __builtin_amdgcn_global_load_lds((const unsigned*)((const char*)(gbase) + (voff)[_i]), (PG8_LAS unsigned*)(lds + (bufoff) + ldsw + _i * 8192), 16, 0, 0); } while (0)
; #define PG8_LDA(dst, b, h) do { _Pragma("unroll") for (int m = 0; m < 4; ++m) _Pragma("unroll") for (int k = 0; k < 2; ++k) dst[m][k] = *(const PG8_LAS bf16x8*)(lds + PG8_SA(b, h) + aoff + m * 2048 + k * 1024); } while (0)
; #define PG8_MMA(ai, bj, At, Bt) do { __builtin_amdgcn_s_setprio(1); _Pragma("unroll") for (int m = 0; m < 4; ++m) _Pragma("unroll") for (int n = 0; n < 2; ++n) _Pragma("unroll") for (int k = 0; k < 2; ++k) \
;         acc[ai][bj][m][n] = __builtin_amdgcn_mfma_f32_16x16x32_bf16(Bt[n][k], At[m][k], acc[ai][bj][m][n], 0, 0, 0); __builtin_amdgcn_s_setprio(0); } while (0)
; #define PG8_WAIT_V(n) asm volatile("s_waitcnt vmcnt(" #n ")" ::: "memory")
; #define PG8_WAIT_L(n) asm volatile("s_waitcnt lgkmcnt(" #n ")" ::: "memory")
; #define PG8_BAR __builtin_amdgcn_s_barrier()
; #define PG8_SCHED __builtin_amdgcn_sched_barrier(0)
; template <class Epi, class Sched, bool ALIGN_EPI, bool SP2, int KK, int LDA, int APN>
; __device__ __forceinline__ void gemm_phase(PG8_LAS unsigned char* lds, const Gemm g, const Sched& S, const Epi& E, const int wid) {
;     ...
;             PG8_LDA(At, 1, 1); PG8_STAGE(PG8_SB(1, 0), b3, voffB); PG8_STAGE(PG8_SB(1, 1), b3 + hstep, voffB); PG8_STAGE(PG8_SA(1, 0), a3, voffA);
;             PG8_WAIT_V(8); PG8_WAIT_L(0); PG8_BAR; PG8_MMA(1, 0, At, B0); PG8_MMA(1, 1, At, B1); PG8_BAR; PG8_SCHED;
;     ...
;         }
;         if constexpr (ALIGN_EPI) { if (wr == 0) PG8_BAR; }
	s_add_i32 s54, s69, s12
	v_lshl_add_u64 v[144:145], v[144:145], 0, s[22:23]
	s_mov_b32 m0, s54
	ds_read_b128 v[186:189], v150 offset:49152
	ds_read_b128 v[190:193], v150 offset:50176
	ds_read_b128 v[196:199], v150 offset:51200
	ds_read_b128 v[202:205], v150 offset:52224
	ds_read_b128 v[206:209], v150 offset:53248
	ds_read_b128 v[212:215], v150 offset:54272
	ds_read_b128 v[226:229], v150 offset:55296
	ds_read_b128 v[230:233], v150 offset:56320
	global_load_lds_dwordx4 v[144:145], off
	s_add_i32 m0, s54, 0x2000
	s_add_u32 s52, s52, 0x80080
	v_lshl_add_u64 v[144:145], v[216:217], 0, s[22:23]
	s_addc_u32 s53, s53, 0
	s_add_i32 s54, s70, s12
	global_load_lds_dwordx4 v[144:145], off
	v_lshl_add_u64 v[144:145], s[52:53], 0, v[96:97]
	s_mov_b32 m0, s54
	s_nop 0
	global_load_lds_dwordx4 v[144:145], off
	v_lshl_add_u64 v[144:145], s[52:53], 0, v[134:135]
	s_add_i32 m0, s54, 0x2000
	s_nop 0
	global_load_lds_dwordx4 v[144:145], off
	v_lshl_add_u64 v[144:145], v[234:235], 0, s[22:23]
	s_mov_b32 m0, s58
	s_nop 0
	global_load_lds_dwordx4 v[144:145], off
	v_lshl_add_u64 v[144:145], v[236:237], 0, s[22:23]
	s_mov_b32 m0, s59
	s_nop 0
	global_load_lds_dwordx4 v[144:145], off
	s_waitcnt vmcnt(8)
	s_waitcnt lgkmcnt(0)
	s_barrier
	v_mfma_f32_16x16x32_bf16 v[64:67], v[154:157], v[186:189], v[64:67]
	v_mfma_f32_16x16x32_bf16 v[68:71], v[162:165], v[186:189], v[68:71]
	v_mfma_f32_16x16x32_bf16 v[80:83], v[154:157], v[196:199], v[80:83]
	v_mfma_f32_16x16x32_bf16 v[84:87], v[162:165], v[196:199], v[84:87]
	v_mfma_f32_16x16x32_bf16 v[98:101], v[154:157], v[206:209], v[98:101]
	v_mfma_f32_16x16x32_bf16 v[102:105], v[162:165], v[206:209], v[102:105]
	v_mfma_f32_16x16x32_bf16 v[114:117], v[154:157], v[226:229], v[114:117]
	v_mfma_f32_16x16x32_bf16 v[118:121], v[162:165], v[226:229], v[118:121]
	v_mfma_f32_16x16x32_bf16 v[64:67], v[158:161], v[190:193], v[64:67]
	v_mfma_f32_16x16x32_bf16 v[68:71], v[166:169], v[190:193], v[68:71]
	v_mfma_f32_16x16x32_bf16 v[80:83], v[158:161], v[202:205], v[80:83]
	v_mfma_f32_16x16x32_bf16 v[84:87], v[166:169], v[202:205], v[84:87]
	v_mfma_f32_16x16x32_bf16 v[98:101], v[158:161], v[212:215], v[98:101]
	v_mfma_f32_16x16x32_bf16 v[102:105], v[166:169], v[212:215], v[102:105]
	v_mfma_f32_16x16x32_bf16 v[114:117], v[158:161], v[230:233], v[114:117]
	v_mfma_f32_16x16x32_bf16 v[118:121], v[166:169], v[230:233], v[118:121]
	v_mfma_f32_16x16x32_bf16 v[72:75], v[170:173], v[186:189], v[72:75]
	v_mfma_f32_16x16x32_bf16 v[76:79], v[178:181], v[186:189], v[76:79]
	v_mfma_f32_16x16x32_bf16 v[88:91], v[170:173], v[196:199], v[88:91]
	v_mfma_f32_16x16x32_bf16 v[92:95], v[178:181], v[196:199], v[92:95]
	v_mfma_f32_16x16x32_bf16 v[106:109], v[170:173], v[206:209], v[106:109]
	v_mfma_f32_16x16x32_bf16 v[110:113], v[178:181], v[206:209], v[110:113]
	v_mfma_f32_16x16x32_bf16 v[122:125], v[170:173], v[226:229], v[122:125]
	v_mfma_f32_16x16x32_bf16 v[126:129], v[178:181], v[226:229], v[126:129]
	v_mfma_f32_16x16x32_bf16 v[72:75], v[174:177], v[190:193], v[72:75]
	v_mfma_f32_16x16x32_bf16 v[76:79], v[182:185], v[190:193], v[76:79]
	v_mfma_f32_16x16x32_bf16 v[88:91], v[174:177], v[202:205], v[88:91]
	v_mfma_f32_16x16x32_bf16 v[92:95], v[182:185], v[202:205], v[92:95]
	v_mfma_f32_16x16x32_bf16 v[106:109], v[174:177], v[212:215], v[106:109]
	v_mfma_f32_16x16x32_bf16 v[110:113], v[182:185], v[212:215], v[110:113]
	v_mfma_f32_16x16x32_bf16 v[122:125], v[174:177], v[230:233], v[122:125]
	v_mfma_f32_16x16x32_bf16 v[126:129], v[182:185], v[230:233], v[126:129]
	s_barrier
	s_add_i32 s45, s45, 2
	s_add_u32 s50, s50, 0x100
	s_addc_u32 s51, s51, 0
	s_cmp_gt_u32 s45, 29
	s_cbranch_scc0 .LBB0_686
	s_and_b64 vcc, exec, s[30:31]
	s_cbranch_vccz .LBB0_689
	s_barrier

; #define PG8_STAGE(bufoff, gbase, voff) do { _Pragma("unroll") for (int _i = 0; _i < 2; ++_i) \
;         __builtin_amdgcn_global_load_lds((const unsigned*)((const char*)(gbase) + (voff)[_i]), (PG8_LAS unsigned*)(lds + (bufoff) + ldsw + _i * 8192), 16, 0, 0); } while (0)
; #define PG8_LDA(dst, b, h) do { _Pragma("unroll") for (int m = 0; m < 4; ++m) _Pragma("unroll") for (int k = 0; k < 2; ++k) dst[m][k] = *(const PG8_LAS bf16x8*)(lds + PG8_SA(b, h) + aoff + m * 2048 + k * 1024); } while (0)
; #define PG8_LDB(dst, b, h) do { _Pragma("unroll") for (int n = 0; n < 2; ++n) _Pragma("unroll") for (int k = 0; k < 2; ++k) dst[n][k] = *(const PG8_LAS bf16x8*)(lds + PG8_SB(b, h) + boff + n * 2048 + k * 1024); } while (0)
; #define PG8_MMA(ai, bj, At, Bt) do { __builtin_amdgcn_s_setprio(1); _Pragma("unroll") for (int m = 0; m < 4; ++m) _Pragma("unroll") for (int n = 0; n < 2; ++n) _Pragma("unroll") for (int k = 0; k < 2; ++k) \
;         acc[ai][bj][m][n] = __builtin_amdgcn_mfma_f32_16x16x32_bf16(Bt[n][k], At[m][k], acc[ai][bj][m][n], 0, 0, 0); __builtin_amdgcn_s_setprio(0); } while (0)
; #define PG8_WAIT_V(n) asm volatile("s_waitcnt vmcnt(" #n ")" ::: "memory")
; #define PG8_BAR __builtin_amdgcn_s_barrier()
; template <class Epi, class Sched, bool ALIGN_EPI, bool SP2, int KK, int LDA, int APN>
; __device__ __forceinline__ void gemm_phase(PG8_LAS unsigned char* lds, const Gemm g, const Sched& S, const Epi& E, const int wid) {
;     ...
;         for (int t = 0; t < nt; t += 2) {
;             const bool last = (t == nt - 2);
;             const char* a1 = cA + (size_t)(t + 1) * kstep;
;             const char* a2 = last ? nA : cA + (size_t)(t + 2) * kstep; const char* b2 = last ? nB : cB + (size_t)(t + 2) * kstep;
;             const char* a3 = a2 + kstep; const char* b3 = b2 + kstep;
;             if (last && has_next) S.a_ready(nxt);
;             if constexpr (SP2) {
;             PG8_LDB(B0, 0, 0); PG8_LDB(B1, 0, 1); PG8_SCHED; PG8_LDA(At, 0, 0); PG8_STAGE(PG8_SA(1, 1), a1 + hstepA, voffA);
;             PG8_WAIT_V(8); PG8_WAIT_L(0); PG8_BAR; PG8_MMA(0, 0, At, B0); PG8_MMA(0, 1, At, B1); PG8_BAR; PG8_SCHED;
;             PG8_LDA(At, 0, 1); PG8_STAGE(PG8_SB(0, 0), b2, voffB); PG8_STAGE(PG8_SB(0, 1), b2 + hstep, voffB); PG8_STAGE(PG8_SA(0, 0), a2, voffA);
;             PG8_WAIT_V(8); PG8_WAIT_L(0); PG8_BAR; PG8_MMA(1, 0, At, B0); PG8_MMA(1, 1, At, B1); PG8_BAR; PG8_SCHED;
.LBB0_779:
	s_add_u32 s42, s30, 0xfff80080
	s_addc_u32 s43, s31, -1
	s_add_i32 s56, 0, 0x10000
	s_cmp_eq_u32 s55, 28
	s_cselect_b32 s45, s35, s43
	s_cselect_b32 s44, s51, s42
	v_add_u32_e32 v140, s56, v143
	s_cselect_b32 s43, s27, s54
	s_cselect_b32 s42, s52, s53
	s_add_i32 s58, 0, 0x14000
	ds_read_b128 v[148:151], v140
	ds_read_b128 v[152:155], v140 offset:1024
	ds_read_b128 v[156:159], v140 offset:2048
	ds_read_b128 v[160:163], v140 offset:3072
	v_add_u32_e32 v140, s58, v143
	ds_read_b128 v[164:167], v140
	ds_read_b128 v[168:171], v140 offset:1024
	ds_read_b128 v[172:175], v140 offset:2048
	ds_read_b128 v[176:179], v140 offset:3072
	v_lshl_add_u64 v[140:141], s[30:31], 0, v[138:139]
	s_add_i32 m0, s13, 0xc000
	ds_read_b128 v[180:183], v146
	ds_read_b128 v[184:187], v146 offset:1024
	ds_read_b128 v[188:191], v146 offset:2048
	ds_read_b128 v[196:199], v146 offset:3072
	ds_read_b128 v[202:205], v146 offset:4096
	ds_read_b128 v[206:209], v146 offset:5120
	ds_read_b128 v[212:215], v146 offset:6144
	ds_read_b128 v[226:229], v146 offset:7168
	global_load_lds_dwordx4 v[140:141], off
	v_lshl_add_u64 v[140:141], s[30:31], 0, v[136:137]
	s_add_i32 m0, s13, 0xe000
	s_nop 0
	global_load_lds_dwordx4 v[140:141], off
	s_waitcnt vmcnt(8)
	s_waitcnt lgkmcnt(0)
	s_barrier
	v_mfma_f32_16x16x32_bf16 v[126:129], v[148:151], v[180:183], v[126:129]
	v_mfma_f32_16x16x32_bf16 v[118:121], v[156:159], v[180:183], v[118:121]
	v_mfma_f32_16x16x32_bf16 v[110:113], v[148:151], v[188:191], v[110:113]
	v_mfma_f32_16x16x32_bf16 v[102:105], v[156:159], v[188:191], v[102:105]
	v_mfma_f32_16x16x32_bf16 v[92:95], v[148:151], v[202:205], v[92:95]
	v_mfma_f32_16x16x32_bf16 v[84:87], v[156:159], v[202:205], v[84:87]
	v_mfma_f32_16x16x32_bf16 v[76:79], v[148:151], v[212:215], v[76:79]
	v_mfma_f32_16x16x32_bf16 v[68:71], v[156:159], v[212:215], v[68:71]
	v_mfma_f32_16x16x32_bf16 v[126:129], v[152:155], v[184:187], v[126:129]
	v_mfma_f32_16x16x32_bf16 v[118:121], v[160:163], v[184:187], v[118:121]
	v_mfma_f32_16x16x32_bf16 v[110:113], v[152:155], v[196:199], v[110:113]
	v_mfma_f32_16x16x32_bf16 v[102:105], v[160:163], v[196:199], v[102:105]
	v_mfma_f32_16x16x32_bf16 v[92:95], v[152:155], v[206:209], v[92:95]
	v_mfma_f32_16x16x32_bf16 v[84:87], v[160:163], v[206:209], v[84:87]
	v_mfma_f32_16x16x32_bf16 v[76:79], v[152:155], v[226:229], v[76:79]
	v_mfma_f32_16x16x32_bf16 v[68:71], v[160:163], v[226:229], v[68:71]
	v_mfma_f32_16x16x32_bf16 v[122:125], v[164:167], v[180:183], v[122:125]
	v_mfma_f32_16x16x32_bf16 v[114:117], v[172:175], v[180:183], v[114:117]
	v_mfma_f32_16x16x32_bf16 v[106:109], v[164:167], v[188:191], v[106:109]
	v_mfma_f32_16x16x32_bf16 v[98:101], v[172:175], v[188:191], v[98:101]
	v_mfma_f32_16x16x32_bf16 v[88:91], v[164:167], v[202:205], v[88:91]
	v_mfma_f32_16x16x32_bf16 v[80:83], v[172:175], v[202:205], v[80:83]
	v_mfma_f32_16x16x32_bf16 v[72:75], v[164:167], v[212:215], v[72:75]
	v_mfma_f32_16x16x32_bf16 v[64:67], v[172:175], v[212:215], v[64:67]
	v_mfma_f32_16x16x32_bf16 v[122:125], v[168:171], v[184:187], v[122:125]
	v_mfma_f32_16x16x32_bf16 v[114:117], v[176:179], v[184:187], v[114:117]
	v_mfma_f32_16x16x32_bf16 v[106:109], v[168:171], v[196:199], v[106:109]
	v_mfma_f32_16x16x32_bf16 v[98:101], v[176:179], v[196:199], v[98:101]
	v_mfma_f32_16x16x32_bf16 v[88:91], v[168:171], v[206:209], v[88:91]
	v_mfma_f32_16x16x32_bf16 v[80:83], v[176:179], v[206:209], v[80:83]
	v_mfma_f32_16x16x32_bf16 v[72:75], v[168:171], v[226:229], v[72:75]
	v_mfma_f32_16x16x32_bf16 v[64:67], v[176:179], v[226:229], v[64:67]
	s_barrier
	s_add_i32 s56, s56, s12
	v_lshl_add_u64 v[140:141], s[42:43], 0, v[96:97]
	s_mov_b32 m0, s56
	ds_read_b128 v[180:183], v146 offset:16384
	ds_read_b128 v[184:187], v146 offset:17408
	ds_read_b128 v[188:191], v146 offset:18432
	ds_read_b128 v[196:199], v146 offset:19456
	ds_read_b128 v[202:205], v146 offset:20480
	ds_read_b128 v[206:209], v146 offset:21504
	ds_read_b128 v[212:215], v146 offset:22528
	ds_read_b128 v[226:229], v146 offset:23552
	global_load_lds_dwordx4 v[140:141], off
	s_add_i32 m0, s56, 0x2000
	s_add_u32 s56, s42, 0x80000
	v_lshl_add_u64 v[192:193], s[42:43], 0, v[134:135]
	s_addc_u32 s57, s43, 0
	s_add_i32 s58, s58, s12
	global_load_lds_dwordx4 v[192:193], off
	v_lshl_add_u64 v[216:217], s[56:57], 0, v[96:97]
	s_mov_b32 m0, s58
	v_lshl_add_u64 v[230:231], s[44:45], 0, v[132:133]
	global_load_lds_dwordx4 v[216:217], off
	v_lshl_add_u64 v[216:217], s[56:57], 0, v[134:135]
	s_add_i32 m0, s58, 0x2000
	s_nop 0
	global_load_lds_dwordx4 v[216:217], off
	v_lshl_add_u64 v[216:217], s[44:45], 0, v[130:131]
	s_mov_b32 m0, s13
	s_nop 0
	global_load_lds_dwordx4 v[216:217], off
	s_mov_b32 m0, s40
	s_nop 0
	global_load_lds_dwordx4 v[230:231], off
	s_waitcnt vmcnt(8)
	s_waitcnt lgkmcnt(0)
	s_barrier
; #define PG8_STAGE(bufoff, gbase, voff) do { _Pragma("unroll") for (int _i = 0; _i < 2; ++_i) \
;         __builtin_amdgcn_global_load_lds((const unsigned*)((const char*)(gbase) + (voff)[_i]), (PG8_LAS unsigned*)(lds + (bufoff) + ldsw + _i * 8192), 16, 0, 0); } while (0)
; #define PG8_LDA(dst, b, h) do { _Pragma("unroll") for (int m = 0; m < 4; ++m) _Pragma("unroll") for (int k = 0; k < 2; ++k) dst[m][k] = *(const PG8_LAS bf16x8*)(lds + PG8_SA(b, h) + aoff + m * 2048 + k * 1024); } while (0)
; #define PG8_LDB(dst, b, h) do { _Pragma("unroll") for (int n = 0; n < 2; ++n) _Pragma("unroll") for (int k = 0; k < 2; ++k) dst[n][k] = *(const PG8_LAS bf16x8*)(lds + PG8_SB(b, h) + boff + n * 2048 + k * 1024); } while (0)
; #define PG8_MMA(ai, bj, At, Bt) do { __builtin_amdgcn_s_setprio(1); _Pragma("unroll") for (int m = 0; m < 4; ++m) _Pragma("unroll") for (int n = 0; n < 2; ++n) _Pragma("unroll") for (int k = 0; k < 2; ++k) \
;         acc[ai][bj][m][n] = __builtin_amdgcn_mfma_f32_16x16x32_bf16(Bt[n][k], At[m][k], acc[ai][bj][m][n], 0, 0, 0); __builtin_amdgcn_s_setprio(0); } while (0)
; #define PG8_WAIT_V(n) asm volatile("s_waitcnt vmcnt(" #n ")" ::: "memory")
; #define PG8_WAIT_L(n) asm volatile("s_waitcnt lgkmcnt(" #n ")" ::: "memory")
; #define PG8_BAR __builtin_amdgcn_s_barrier()
; #define PG8_SCHED __builtin_amdgcn_sched_barrier(0)
; template <class Epi, class Sched, bool ALIGN_EPI, bool SP2, int KK, int LDA, int APN>
; __device__ __forceinline__ void gemm_phase(PG8_LAS unsigned char* lds, const Gemm g, const Sched& S, const Epi& E, const int wid) {
;     ...
;             PG8_WAIT_V(8); PG8_WAIT_L(0); PG8_BAR; PG8_MMA(1, 0, At, B0); PG8_MMA(1, 1, At, B1); PG8_BAR; PG8_SCHED;
;             PG8_LDB(B0, 1, 0); PG8_LDB(B1, 1, 1); PG8_SCHED; PG8_LDA(At, 1, 0); PG8_STAGE(PG8_SA(0, 1), a2 + hstepA, voffA);
;             PG8_WAIT_V(8); PG8_WAIT_L(0); PG8_BAR; PG8_MMA(0, 0, At, B0); PG8_MMA(0, 1, At, B1); PG8_BAR; PG8_SCHED;
;             PG8_LDA(At, 1, 1); PG8_STAGE(PG8_SB(1, 0), b3, voffB); PG8_STAGE(PG8_SB(1, 1), b3 + hstep, voffB); PG8_STAGE(PG8_SA(1, 0), a3, voffA);
	v_mfma_f32_16x16x32_bf16 v[60:63], v[148:151], v[180:183], v[60:63]
	v_mfma_f32_16x16x32_bf16 v[52:55], v[156:159], v[180:183], v[52:55]
	v_mfma_f32_16x16x32_bf16 v[44:47], v[148:151], v[188:191], v[44:47]
	v_mfma_f32_16x16x32_bf16 v[36:39], v[156:159], v[188:191], v[36:39]
	v_mfma_f32_16x16x32_bf16 v[28:31], v[148:151], v[202:205], v[28:31]
	v_mfma_f32_16x16x32_bf16 v[20:23], v[156:159], v[202:205], v[20:23]
	v_mfma_f32_16x16x32_bf16 v[12:15], v[148:151], v[212:215], v[12:15]
	v_mfma_f32_16x16x32_bf16 v[4:7], v[156:159], v[212:215], v[4:7]
	v_mfma_f32_16x16x32_bf16 v[60:63], v[152:155], v[184:187], v[60:63]
	v_mfma_f32_16x16x32_bf16 v[52:55], v[160:163], v[184:187], v[52:55]
	v_mfma_f32_16x16x32_bf16 v[44:47], v[152:155], v[196:199], v[44:47]
	v_mfma_f32_16x16x32_bf16 v[36:39], v[160:163], v[196:199], v[36:39]
	v_mfma_f32_16x16x32_bf16 v[28:31], v[152:155], v[206:209], v[28:31]
	v_mfma_f32_16x16x32_bf16 v[20:23], v[160:163], v[206:209], v[20:23]
	v_mfma_f32_16x16x32_bf16 v[12:15], v[152:155], v[226:229], v[12:15]
	v_mfma_f32_16x16x32_bf16 v[4:7], v[160:163], v[226:229], v[4:7]
	v_mfma_f32_16x16x32_bf16 v[56:59], v[164:167], v[180:183], v[56:59]
	v_mfma_f32_16x16x32_bf16 v[48:51], v[172:175], v[180:183], v[48:51]
	v_mfma_f32_16x16x32_bf16 v[40:43], v[164:167], v[188:191], v[40:43]
	v_mfma_f32_16x16x32_bf16 v[32:35], v[172:175], v[188:191], v[32:35]
	v_mfma_f32_16x16x32_bf16 v[24:27], v[164:167], v[202:205], v[24:27]
	v_mfma_f32_16x16x32_bf16 v[16:19], v[172:175], v[202:205], v[16:19]
	v_mfma_f32_16x16x32_bf16 v[8:11], v[164:167], v[212:215], v[8:11]
	v_mfma_f32_16x16x32_bf16 v[0:3], v[172:175], v[212:215], v[0:3]
	v_mfma_f32_16x16x32_bf16 v[56:59], v[168:171], v[184:187], v[56:59]
	v_mfma_f32_16x16x32_bf16 v[48:51], v[176:179], v[184:187], v[48:51]
	v_mfma_f32_16x16x32_bf16 v[40:43], v[168:171], v[196:199], v[40:43]
	v_mfma_f32_16x16x32_bf16 v[32:35], v[176:179], v[196:199], v[32:35]
	v_mfma_f32_16x16x32_bf16 v[24:27], v[168:171], v[206:209], v[24:27]
	v_mfma_f32_16x16x32_bf16 v[16:19], v[176:179], v[206:209], v[16:19]
	v_mfma_f32_16x16x32_bf16 v[8:11], v[168:171], v[226:229], v[8:11]
	v_mfma_f32_16x16x32_bf16 v[0:3], v[176:179], v[226:229], v[0:3]
	s_barrier
	s_add_i32 s56, 0, 0x18000
	v_add_u32_e32 v147, s56, v143
	s_add_i32 s57, 0, 0x1c000
	ds_read_b128 v[148:151], v147
	ds_read_b128 v[152:155], v147 offset:1024
	ds_read_b128 v[156:159], v147 offset:2048
	ds_read_b128 v[160:163], v147 offset:3072
	v_add_u32_e32 v147, s57, v143
	ds_read_b128 v[164:167], v147
	ds_read_b128 v[168:171], v147 offset:1024
	ds_read_b128 v[172:175], v147 offset:2048
	ds_read_b128 v[176:179], v147 offset:3072
	s_add_u32 s44, s44, 0x80000
	s_addc_u32 s45, s45, 0
	s_mov_b32 m0, s41
	v_lshl_add_u64 v[232:233], s[44:45], 0, v[130:131]
	ds_read_b128 v[180:183], v146 offset:32768
	ds_read_b128 v[184:187], v146 offset:33792
	ds_read_b128 v[188:191], v146 offset:34816
	ds_read_b128 v[196:199], v146 offset:35840
	ds_read_b128 v[202:205], v146 offset:36864
	ds_read_b128 v[206:209], v146 offset:37888
	ds_read_b128 v[212:215], v146 offset:38912
	ds_read_b128 v[226:229], v146 offset:39936
	global_load_lds_dwordx4 v[232:233], off
	v_lshl_add_u64 v[232:233], s[44:45], 0, v[132:133]
	s_mov_b32 m0, s46
	s_nop 0
	global_load_lds_dwordx4 v[232:233], off
	s_waitcnt vmcnt(8)
	s_waitcnt lgkmcnt(0)
	s_barrier
	v_mfma_f32_16x16x32_bf16 v[126:129], v[148:151], v[180:183], v[126:129]
	v_mfma_f32_16x16x32_bf16 v[118:121], v[156:159], v[180:183], v[118:121]
	v_mfma_f32_16x16x32_bf16 v[110:113], v[148:151], v[188:191], v[110:113]
	v_mfma_f32_16x16x32_bf16 v[102:105], v[156:159], v[188:191], v[102:105]
	v_mfma_f32_16x16x32_bf16 v[92:95], v[148:151], v[202:205], v[92:95]
	v_mfma_f32_16x16x32_bf16 v[84:87], v[156:159], v[202:205], v[84:87]
	v_mfma_f32_16x16x32_bf16 v[76:79], v[148:151], v[212:215], v[76:79]
	v_mfma_f32_16x16x32_bf16 v[68:71], v[156:159], v[212:215], v[68:71]
	v_mfma_f32_16x16x32_bf16 v[126:129], v[152:155], v[184:187], v[126:129]
	v_mfma_f32_16x16x32_bf16 v[118:121], v[160:163], v[184:187], v[118:121]
	v_mfma_f32_16x16x32_bf16 v[110:113], v[152:155], v[196:199], v[110:113]
	v_mfma_f32_16x16x32_bf16 v[102:105], v[160:163], v[196:199], v[102:105]
	v_mfma_f32_16x16x32_bf16 v[92:95], v[152:155], v[206:209], v[92:95]
	v_mfma_f32_16x16x32_bf16 v[84:87], v[160:163], v[206:209], v[84:87]
	v_mfma_f32_16x16x32_bf16 v[76:79], v[152:155], v[226:229], v[76:79]
	v_mfma_f32_16x16x32_bf16 v[68:71], v[160:163], v[226:229], v[68:71]
	v_mfma_f32_16x16x32_bf16 v[122:125], v[164:167], v[180:183], v[122:125]
	v_mfma_f32_16x16x32_bf16 v[114:117], v[172:175], v[180:183], v[114:117]
	v_mfma_f32_16x16x32_bf16 v[106:109], v[164:167], v[188:191], v[106:109]
	v_mfma_f32_16x16x32_bf16 v[98:101], v[172:175], v[188:191], v[98:101]
	v_mfma_f32_16x16x32_bf16 v[88:91], v[164:167], v[202:205], v[88:91]
	v_mfma_f32_16x16x32_bf16 v[80:83], v[172:175], v[202:205], v[80:83]
	v_mfma_f32_16x16x32_bf16 v[72:75], v[164:167], v[212:215], v[72:75]
	v_mfma_f32_16x16x32_bf16 v[64:67], v[172:175], v[212:215], v[64:67]
	v_mfma_f32_16x16x32_bf16 v[122:125], v[168:171], v[184:187], v[122:125]
	v_mfma_f32_16x16x32_bf16 v[114:117], v[176:179], v[184:187], v[114:117]
	v_mfma_f32_16x16x32_bf16 v[106:109], v[168:171], v[196:199], v[106:109]
	v_mfma_f32_16x16x32_bf16 v[98:101], v[176:179], v[196:199], v[98:101]
	v_mfma_f32_16x16x32_bf16 v[88:91], v[168:171], v[206:209], v[88:91]
	v_mfma_f32_16x16x32_bf16 v[80:83], v[176:179], v[206:209], v[80:83]
	v_mfma_f32_16x16x32_bf16 v[72:75], v[168:171], v[226:229], v[72:75]
	v_mfma_f32_16x16x32_bf16 v[64:67], v[176:179], v[226:229], v[64:67]
	s_barrier
; #define PG8_STAGE(bufoff, gbase, voff) do { _Pragma("unroll") for (int _i = 0; _i < 2; ++_i) \
;         __builtin_amdgcn_global_load_lds((const unsigned*)((const char*)(gbase) + (voff)[_i]), (PG8_LAS unsigned*)(lds + (bufoff) + ldsw + _i * 8192), 16, 0, 0); } while (0)
; #define PG8_LDA(dst, b, h) do { _Pragma("unroll") for (int m = 0; m < 4; ++m) _Pragma("unroll") for (int k = 0; k < 2; ++k) dst[m][k] = *(const PG8_LAS bf16x8*)(lds + PG8_SA(b, h) + aoff + m * 2048 + k * 1024); } while (0)
; #define PG8_MMA(ai, bj, At, Bt) do { __builtin_amdgcn_s_setprio(1); _Pragma("unroll") for (int m = 0; m < 4; ++m) _Pragma("unroll") for (int n = 0; n < 2; ++n) _Pragma("unroll") for (int k = 0; k < 2; ++k) \
;         acc[ai][bj][m][n] = __builtin_amdgcn_mfma_f32_16x16x32_bf16(Bt[n][k], At[m][k], acc[ai][bj][m][n], 0, 0, 0); __builtin_amdgcn_s_setprio(0); } while (0)
; #define PG8_WAIT_V(n) asm volatile("s_waitcnt vmcnt(" #n ")" ::: "memory")
; #define PG8_WAIT_L(n) asm volatile("s_waitcnt lgkmcnt(" #n ")" ::: "memory")
; #define PG8_BAR __builtin_amdgcn_s_barrier()
; #define PG8_SCHED __builtin_amdgcn_sched_barrier(0)
; template <class Epi, class Sched, bool ALIGN_EPI, bool SP2, int KK, int LDA, int APN>
; __device__ __forceinline__ void gemm_phase(PG8_LAS unsigned char* lds, const Gemm g, const Sched& S, const Epi& E, const int wid) {
;     ...
;             PG8_LDA(At, 1, 1); PG8_STAGE(PG8_SB(1, 0), b3, voffB); PG8_STAGE(PG8_SB(1, 1), b3 + hstep, voffB); PG8_STAGE(PG8_SA(1, 0), a3, voffA);
;             PG8_WAIT_V(8); PG8_WAIT_L(0); PG8_BAR; PG8_MMA(1, 0, At, B0); PG8_MMA(1, 1, At, B1); PG8_BAR; PG8_SCHED;
;     ...
;         }
;         if constexpr (ALIGN_EPI) { if (wr == 0) PG8_BAR; }
	s_add_i32 s44, s56, s12
	v_lshl_add_u64 v[140:141], v[140:141], 0, s[22:23]
	s_mov_b32 m0, s44
	ds_read_b128 v[180:183], v146 offset:49152
	ds_read_b128 v[184:187], v146 offset:50176
	ds_read_b128 v[188:191], v146 offset:51200
	ds_read_b128 v[196:199], v146 offset:52224
	ds_read_b128 v[202:205], v146 offset:53248
	ds_read_b128 v[206:209], v146 offset:54272
	ds_read_b128 v[212:215], v146 offset:55296
	ds_read_b128 v[226:229], v146 offset:56320
	global_load_lds_dwordx4 v[140:141], off
	s_add_i32 m0, s44, 0x2000
	s_add_u32 s42, s42, 0x80080
	v_lshl_add_u64 v[140:141], v[192:193], 0, s[22:23]
	s_addc_u32 s43, s43, 0
	s_add_i32 s44, s57, s12
	global_load_lds_dwordx4 v[140:141], off
	v_lshl_add_u64 v[140:141], s[42:43], 0, v[96:97]
	s_mov_b32 m0, s44
	s_nop 0
	global_load_lds_dwordx4 v[140:141], off
	v_lshl_add_u64 v[140:141], s[42:43], 0, v[134:135]
	s_add_i32 m0, s44, 0x2000
	s_nop 0
	global_load_lds_dwordx4 v[140:141], off
	v_lshl_add_u64 v[140:141], v[216:217], 0, s[22:23]
	s_mov_b32 m0, s47
	s_nop 0
	global_load_lds_dwordx4 v[140:141], off
	v_lshl_add_u64 v[140:141], v[230:231], 0, s[22:23]
	s_mov_b32 m0, s48
	s_nop 0
	global_load_lds_dwordx4 v[140:141], off
	s_waitcnt vmcnt(8)
	s_waitcnt lgkmcnt(0)
	s_barrier
	v_mfma_f32_16x16x32_bf16 v[60:63], v[148:151], v[180:183], v[60:63]
	v_mfma_f32_16x16x32_bf16 v[52:55], v[156:159], v[180:183], v[52:55]
	v_mfma_f32_16x16x32_bf16 v[44:47], v[148:151], v[188:191], v[44:47]
	v_mfma_f32_16x16x32_bf16 v[36:39], v[156:159], v[188:191], v[36:39]
	v_mfma_f32_16x16x32_bf16 v[28:31], v[148:151], v[202:205], v[28:31]
	v_mfma_f32_16x16x32_bf16 v[20:23], v[156:159], v[202:205], v[20:23]
	v_mfma_f32_16x16x32_bf16 v[12:15], v[148:151], v[212:215], v[12:15]
	v_mfma_f32_16x16x32_bf16 v[4:7], v[156:159], v[212:215], v[4:7]
	v_mfma_f32_16x16x32_bf16 v[60:63], v[152:155], v[184:187], v[60:63]
	v_mfma_f32_16x16x32_bf16 v[52:55], v[160:163], v[184:187], v[52:55]
	v_mfma_f32_16x16x32_bf16 v[44:47], v[152:155], v[196:199], v[44:47]
	v_mfma_f32_16x16x32_bf16 v[36:39], v[160:163], v[196:199], v[36:39]
	v_mfma_f32_16x16x32_bf16 v[28:31], v[152:155], v[206:209], v[28:31]
	v_mfma_f32_16x16x32_bf16 v[20:23], v[160:163], v[206:209], v[20:23]
	v_mfma_f32_16x16x32_bf16 v[12:15], v[152:155], v[226:229], v[12:15]
	v_mfma_f32_16x16x32_bf16 v[4:7], v[160:163], v[226:229], v[4:7]
	v_mfma_f32_16x16x32_bf16 v[56:59], v[164:167], v[180:183], v[56:59]
	v_mfma_f32_16x16x32_bf16 v[48:51], v[172:175], v[180:183], v[48:51]
	v_mfma_f32_16x16x32_bf16 v[40:43], v[164:167], v[188:191], v[40:43]
	v_mfma_f32_16x16x32_bf16 v[32:35], v[172:175], v[188:191], v[32:35]
	v_mfma_f32_16x16x32_bf16 v[24:27], v[164:167], v[202:205], v[24:27]
	v_mfma_f32_16x16x32_bf16 v[16:19], v[172:175], v[202:205], v[16:19]
	v_mfma_f32_16x16x32_bf16 v[8:11], v[164:167], v[212:215], v[8:11]
	v_mfma_f32_16x16x32_bf16 v[0:3], v[172:175], v[212:215], v[0:3]
	v_mfma_f32_16x16x32_bf16 v[56:59], v[168:171], v[184:187], v[56:59]
	v_mfma_f32_16x16x32_bf16 v[48:51], v[176:179], v[184:187], v[48:51]
	v_mfma_f32_16x16x32_bf16 v[40:43], v[168:171], v[196:199], v[40:43]
	v_mfma_f32_16x16x32_bf16 v[32:35], v[176:179], v[196:199], v[32:35]
	v_mfma_f32_16x16x32_bf16 v[24:27], v[168:171], v[206:209], v[24:27]
	v_mfma_f32_16x16x32_bf16 v[16:19], v[176:179], v[206:209], v[16:19]
	v_mfma_f32_16x16x32_bf16 v[8:11], v[168:171], v[226:229], v[8:11]
	v_mfma_f32_16x16x32_bf16 v[0:3], v[176:179], v[226:229], v[0:3]
	s_barrier
	s_add_i32 s55, s55, 2
	s_add_u32 s53, s53, 0x100
	s_addc_u32 s54, s54, 0
	s_add_u32 s30, s30, 0x100
	s_addc_u32 s31, s31, 0
	s_cmp_gt_u32 s55, 29
	s_cbranch_scc0 .LBB0_779
	s_and_b64 vcc, exec, s[18:19]
	s_cbranch_vccz .LBB0_782
	s_barrier

; #define PG8_STAGE(bufoff, gbase, voff) do { _Pragma("unroll") for (int _i = 0; _i < 2; ++_i) \
;         __builtin_amdgcn_global_load_lds((const unsigned*)((const char*)(gbase) + (voff)[_i]), (PG8_LAS unsigned*)(lds + (bufoff) + ldsw + _i * 8192), 16, 0, 0); } while (0)
; #define PG8_LDA(dst, b, h) do { _Pragma("unroll") for (int m = 0; m < 4; ++m) _Pragma("unroll") for (int k = 0; k < 2; ++k) dst[m][k] = *(const PG8_LAS bf16x8*)(lds + PG8_SA(b, h) + aoff + m * 2048 + k * 1024); } while (0)
; #define PG8_LDB(dst, b, h) do { _Pragma("unroll") for (int n = 0; n < 2; ++n) _Pragma("unroll") for (int k = 0; k < 2; ++k) dst[n][k] = *(const PG8_LAS bf16x8*)(lds + PG8_SB(b, h) + boff + n * 2048 + k * 1024); } while (0)
; #define PG8_MMA(ai, bj, At, Bt) do { __builtin_amdgcn_s_setprio(1); _Pragma("unroll") for (int m = 0; m < 4; ++m) _Pragma("unroll") for (int n = 0; n < 2; ++n) _Pragma("unroll") for (int k = 0; k < 2; ++k) \
;         acc[ai][bj][m][n] = __builtin_amdgcn_mfma_f32_16x16x32_bf16(Bt[n][k], At[m][k], acc[ai][bj][m][n], 0, 0, 0); __builtin_amdgcn_s_setprio(0); } while (0)
; #define PG8_WAIT_V(n) asm volatile("s_waitcnt vmcnt(" #n ")" ::: "memory")
; #define PG8_BAR __builtin_amdgcn_s_barrier()
; template <class Epi, class Sched, bool ALIGN_EPI, bool SP2, int KK, int LDA, int APN>
; __device__ __forceinline__ void gemm_phase(PG8_LAS unsigned char* lds, const Gemm g, const Sched& S, const Epi& E, const int wid) {
;     ...
;         for (int t = 0; t < nt; t += 2) {
;             const bool last = (t == nt - 2);
;             const char* a1 = cA + (size_t)(t + 1) * kstep;
;             const char* a2 = last ? nA : cA + (size_t)(t + 2) * kstep; const char* b2 = last ? nB : cB + (size_t)(t + 2) * kstep;
;             const char* a3 = a2 + kstep; const char* b3 = b2 + kstep;
;             if (last && has_next) S.a_ready(nxt);
;             if constexpr (SP2) {
;             PG8_LDB(B0, 0, 0); PG8_LDB(B1, 0, 1); PG8_SCHED; PG8_LDA(At, 0, 0); PG8_STAGE(PG8_SA(1, 1), a1 + hstepA, voffA);
;             PG8_WAIT_V(8); PG8_WAIT_L(0); PG8_BAR; PG8_MMA(0, 0, At, B0); PG8_MMA(0, 1, At, B1); PG8_BAR; PG8_SCHED;
;             PG8_LDA(At, 0, 1); PG8_STAGE(PG8_SB(0, 0), b2, voffB); PG8_STAGE(PG8_SB(0, 1), b2 + hstep, voffB); PG8_STAGE(PG8_SA(0, 0), a2, voffA);
;             PG8_WAIT_V(8); PG8_WAIT_L(0); PG8_BAR; PG8_MMA(1, 0, At, B0); PG8_MMA(1, 1, At, B1); PG8_BAR; PG8_SCHED;
.LBB0_860:
	s_add_u32 s30, s16, s28
	s_addc_u32 s31, s17, s29
	s_add_u32 s30, s30, 0x100
	s_addc_u32 s31, s31, 0
	s_add_u32 s61, s59, s28
	s_addc_u32 s66, s60, s29
	s_add_i32 s67, 0, 0x10000
	s_cmpk_eq_i32 s28, 0x2b00
	s_cselect_b32 s49, s43, s31
	s_cselect_b32 s48, s42, s30
	s_cselect_b32 s31, s27, s66
	s_cselect_b32 s30, s26, s61
	s_add_i32 s61, 0, 0x14000
	v_add_u32_e32 v146, s67, v174
	v_add_u32_e32 v179, s61, v174
	ds_read_b128 v[134:137], v146
	ds_read_b128 v[138:141], v146 offset:1024
	ds_read_b128 v[142:145], v146 offset:2048
	ds_read_b128 v[146:149], v146 offset:3072
	ds_read_b128 v[150:153], v179
	ds_read_b128 v[164:167], v179 offset:1024
	ds_read_b128 v[168:171], v179 offset:2048
	ds_read_b128 v[180:183], v179 offset:3072
	v_lshl_add_u64 v[192:193], v[132:133], 0, s[28:29]
	s_add_i32 m0, s55, 0xc000
	ds_read_b128 v[184:187], v176
	ds_read_b128 v[188:191], v176 offset:1024
	ds_read_b128 v[196:199], v176 offset:2048
	ds_read_b128 v[202:205], v176 offset:3072
	ds_read_b128 v[206:209], v176 offset:4096
	ds_read_b128 v[212:215], v176 offset:5120
	ds_read_b128 v[226:229], v176 offset:6144
	ds_read_b128 v[230:233], v176 offset:7168
	global_load_lds_dwordx4 v[192:193], off
	v_lshl_add_u64 v[192:193], v[130:131], 0, s[28:29]
	s_add_i32 m0, s55, 0xe000
	s_nop 0
	global_load_lds_dwordx4 v[192:193], off
	s_waitcnt vmcnt(8)
	s_waitcnt lgkmcnt(0)
	s_barrier
	v_mfma_f32_16x16x32_bf16 v[0:3], v[134:137], v[184:187], v[0:3]
	v_mfma_f32_16x16x32_bf16 v[4:7], v[142:145], v[184:187], v[4:7]
	v_mfma_f32_16x16x32_bf16 v[16:19], v[134:137], v[196:199], v[16:19]
	v_mfma_f32_16x16x32_bf16 v[20:23], v[142:145], v[196:199], v[20:23]
	v_mfma_f32_16x16x32_bf16 v[32:35], v[134:137], v[206:209], v[32:35]
	v_mfma_f32_16x16x32_bf16 v[36:39], v[142:145], v[206:209], v[36:39]
	v_mfma_f32_16x16x32_bf16 v[48:51], v[134:137], v[226:229], v[48:51]
	v_mfma_f32_16x16x32_bf16 v[52:55], v[142:145], v[226:229], v[52:55]
	v_mfma_f32_16x16x32_bf16 v[0:3], v[138:141], v[188:191], v[0:3]
	v_mfma_f32_16x16x32_bf16 v[4:7], v[146:149], v[188:191], v[4:7]
	v_mfma_f32_16x16x32_bf16 v[16:19], v[138:141], v[202:205], v[16:19]
	v_mfma_f32_16x16x32_bf16 v[20:23], v[146:149], v[202:205], v[20:23]
	v_mfma_f32_16x16x32_bf16 v[32:35], v[138:141], v[212:215], v[32:35]
	v_mfma_f32_16x16x32_bf16 v[36:39], v[146:149], v[212:215], v[36:39]
	v_mfma_f32_16x16x32_bf16 v[48:51], v[138:141], v[230:233], v[48:51]
	v_mfma_f32_16x16x32_bf16 v[52:55], v[146:149], v[230:233], v[52:55]
	v_mfma_f32_16x16x32_bf16 v[8:11], v[150:153], v[184:187], v[8:11]
	v_mfma_f32_16x16x32_bf16 v[12:15], v[168:171], v[184:187], v[12:15]
	v_mfma_f32_16x16x32_bf16 v[24:27], v[150:153], v[196:199], v[24:27]
	v_mfma_f32_16x16x32_bf16 v[28:31], v[168:171], v[196:199], v[28:31]
	v_mfma_f32_16x16x32_bf16 v[40:43], v[150:153], v[206:209], v[40:43]
	v_mfma_f32_16x16x32_bf16 v[44:47], v[168:171], v[206:209], v[44:47]
	v_mfma_f32_16x16x32_bf16 v[56:59], v[150:153], v[226:229], v[56:59]
	v_mfma_f32_16x16x32_bf16 v[60:63], v[168:171], v[226:229], v[60:63]
	v_mfma_f32_16x16x32_bf16 v[8:11], v[164:167], v[188:191], v[8:11]
	v_mfma_f32_16x16x32_bf16 v[12:15], v[180:183], v[188:191], v[12:15]
	v_mfma_f32_16x16x32_bf16 v[24:27], v[164:167], v[202:205], v[24:27]
	v_mfma_f32_16x16x32_bf16 v[28:31], v[180:183], v[202:205], v[28:31]
	v_mfma_f32_16x16x32_bf16 v[40:43], v[164:167], v[212:215], v[40:43]
	v_mfma_f32_16x16x32_bf16 v[44:47], v[180:183], v[212:215], v[44:47]
	v_mfma_f32_16x16x32_bf16 v[56:59], v[164:167], v[230:233], v[56:59]
	v_mfma_f32_16x16x32_bf16 v[60:63], v[180:183], v[230:233], v[60:63]
	s_barrier
	s_add_i32 s66, s67, s54
	v_lshl_add_u64 v[192:193], s[30:31], 0, v[96:97]
	s_mov_b32 m0, s66
	ds_read_b128 v[184:187], v176 offset:16384
	ds_read_b128 v[188:191], v176 offset:17408
	ds_read_b128 v[196:199], v176 offset:18432
	ds_read_b128 v[202:205], v176 offset:19456
	ds_read_b128 v[206:209], v176 offset:20480
	ds_read_b128 v[212:215], v176 offset:21504
	ds_read_b128 v[226:229], v176 offset:22528
	ds_read_b128 v[230:233], v176 offset:23552
	global_load_lds_dwordx4 v[192:193], off
	s_add_i32 m0, s66, 0x2000
	s_add_u32 s66, s30, 0x160000
	v_lshl_add_u64 v[216:217], s[30:31], 0, v[158:159]
	s_addc_u32 s67, s31, 0
	s_add_i32 s61, s61, s54
	global_load_lds_dwordx4 v[216:217], off
	v_lshl_add_u64 v[234:235], s[66:67], 0, v[96:97]
	s_mov_b32 m0, s61
	v_lshl_add_u64 v[236:237], s[48:49], 0, v[156:157]
	global_load_lds_dwordx4 v[234:235], off
	v_lshl_add_u64 v[234:235], s[66:67], 0, v[158:159]
	s_add_i32 m0, s61, 0x2000
	s_nop 0
	global_load_lds_dwordx4 v[234:235], off
	v_lshl_add_u64 v[234:235], s[48:49], 0, v[154:155]
	s_mov_b32 m0, s55
	s_nop 0
	global_load_lds_dwordx4 v[234:235], off
	s_mov_b32 m0, s56
	s_nop 0
	global_load_lds_dwordx4 v[236:237], off
	s_waitcnt vmcnt(8)
	s_waitcnt lgkmcnt(0)
	s_barrier
; #define PG8_STAGE(bufoff, gbase, voff) do { _Pragma("unroll") for (int _i = 0; _i < 2; ++_i) \
;         __builtin_amdgcn_global_load_lds((const unsigned*)((const char*)(gbase) + (voff)[_i]), (PG8_LAS unsigned*)(lds + (bufoff) + ldsw + _i * 8192), 16, 0, 0); } while (0)
; #define PG8_LDA(dst, b, h) do { _Pragma("unroll") for (int m = 0; m < 4; ++m) _Pragma("unroll") for (int k = 0; k < 2; ++k) dst[m][k] = *(const PG8_LAS bf16x8*)(lds + PG8_SA(b, h) + aoff + m * 2048 + k * 1024); } while (0)
; #define PG8_LDB(dst, b, h) do { _Pragma("unroll") for (int n = 0; n < 2; ++n) _Pragma("unroll") for (int k = 0; k < 2; ++k) dst[n][k] = *(const PG8_LAS bf16x8*)(lds + PG8_SB(b, h) + boff + n * 2048 + k * 1024); } while (0)
; #define PG8_MMA(ai, bj, At, Bt) do { __builtin_amdgcn_s_setprio(1); _Pragma("unroll") for (int m = 0; m < 4; ++m) _Pragma("unroll") for (int n = 0; n < 2; ++n) _Pragma("unroll") for (int k = 0; k < 2; ++k) \
;         acc[ai][bj][m][n] = __builtin_amdgcn_mfma_f32_16x16x32_bf16(Bt[n][k], At[m][k], acc[ai][bj][m][n], 0, 0, 0); __builtin_amdgcn_s_setprio(0); } while (0)
; #define PG8_WAIT_V(n) asm volatile("s_waitcnt vmcnt(" #n ")" ::: "memory")
; #define PG8_WAIT_L(n) asm volatile("s_waitcnt lgkmcnt(" #n ")" ::: "memory")
; #define PG8_BAR __builtin_amdgcn_s_barrier()
; #define PG8_SCHED __builtin_amdgcn_sched_barrier(0)
; template <class Epi, class Sched, bool ALIGN_EPI, bool SP2, int KK, int LDA, int APN>
; __device__ __forceinline__ void gemm_phase(PG8_LAS unsigned char* lds, const Gemm g, const Sched& S, const Epi& E, const int wid) {
;     ...
;             PG8_WAIT_V(8); PG8_WAIT_L(0); PG8_BAR; PG8_MMA(1, 0, At, B0); PG8_MMA(1, 1, At, B1); PG8_BAR; PG8_SCHED;
;             PG8_LDB(B0, 1, 0); PG8_LDB(B1, 1, 1); PG8_SCHED; PG8_LDA(At, 1, 0); PG8_STAGE(PG8_SA(0, 1), a2 + hstepA, voffA);
;             PG8_WAIT_V(8); PG8_WAIT_L(0); PG8_BAR; PG8_MMA(0, 0, At, B0); PG8_MMA(0, 1, At, B1); PG8_BAR; PG8_SCHED;
;             PG8_LDA(At, 1, 1); PG8_STAGE(PG8_SB(1, 0), b3, voffB); PG8_STAGE(PG8_SB(1, 1), b3 + hstep, voffB); PG8_STAGE(PG8_SA(1, 0), a3, voffA);
	v_mfma_f32_16x16x32_bf16 v[64:67], v[134:137], v[184:187], v[64:67]
	v_mfma_f32_16x16x32_bf16 v[68:71], v[142:145], v[184:187], v[68:71]
	v_mfma_f32_16x16x32_bf16 v[80:83], v[134:137], v[196:199], v[80:83]
	v_mfma_f32_16x16x32_bf16 v[84:87], v[142:145], v[196:199], v[84:87]
	v_mfma_f32_16x16x32_bf16 v[98:101], v[134:137], v[206:209], v[98:101]
	v_mfma_f32_16x16x32_bf16 v[102:105], v[142:145], v[206:209], v[102:105]
	v_mfma_f32_16x16x32_bf16 v[114:117], v[134:137], v[226:229], v[114:117]
	v_mfma_f32_16x16x32_bf16 v[118:121], v[142:145], v[226:229], v[118:121]
	v_mfma_f32_16x16x32_bf16 v[64:67], v[138:141], v[188:191], v[64:67]
	v_mfma_f32_16x16x32_bf16 v[68:71], v[146:149], v[188:191], v[68:71]
	v_mfma_f32_16x16x32_bf16 v[80:83], v[138:141], v[202:205], v[80:83]
	v_mfma_f32_16x16x32_bf16 v[84:87], v[146:149], v[202:205], v[84:87]
	v_mfma_f32_16x16x32_bf16 v[98:101], v[138:141], v[212:215], v[98:101]
	v_mfma_f32_16x16x32_bf16 v[102:105], v[146:149], v[212:215], v[102:105]
	v_mfma_f32_16x16x32_bf16 v[114:117], v[138:141], v[230:233], v[114:117]
	v_mfma_f32_16x16x32_bf16 v[118:121], v[146:149], v[230:233], v[118:121]
	v_mfma_f32_16x16x32_bf16 v[72:75], v[150:153], v[184:187], v[72:75]
	v_mfma_f32_16x16x32_bf16 v[76:79], v[168:171], v[184:187], v[76:79]
	v_mfma_f32_16x16x32_bf16 v[88:91], v[150:153], v[196:199], v[88:91]
	v_mfma_f32_16x16x32_bf16 v[92:95], v[168:171], v[196:199], v[92:95]
	v_mfma_f32_16x16x32_bf16 v[106:109], v[150:153], v[206:209], v[106:109]
	v_mfma_f32_16x16x32_bf16 v[110:113], v[168:171], v[206:209], v[110:113]
	v_mfma_f32_16x16x32_bf16 v[122:125], v[150:153], v[226:229], v[122:125]
	v_mfma_f32_16x16x32_bf16 v[126:129], v[168:171], v[226:229], v[126:129]
	v_mfma_f32_16x16x32_bf16 v[72:75], v[164:167], v[188:191], v[72:75]
	v_mfma_f32_16x16x32_bf16 v[76:79], v[180:183], v[188:191], v[76:79]
	v_mfma_f32_16x16x32_bf16 v[88:91], v[164:167], v[202:205], v[88:91]
	v_mfma_f32_16x16x32_bf16 v[92:95], v[180:183], v[202:205], v[92:95]
	v_mfma_f32_16x16x32_bf16 v[106:109], v[164:167], v[212:215], v[106:109]
	v_mfma_f32_16x16x32_bf16 v[110:113], v[180:183], v[212:215], v[110:113]
	v_mfma_f32_16x16x32_bf16 v[122:125], v[164:167], v[230:233], v[122:125]
	v_mfma_f32_16x16x32_bf16 v[126:129], v[180:183], v[230:233], v[126:129]
	s_barrier
	s_add_i32 s61, 0, 0x18000
	s_add_i32 s66, 0, 0x1c000
	v_add_u32_e32 v146, s61, v174
	v_add_u32_e32 v179, s66, v174
	ds_read_b128 v[134:137], v146
	ds_read_b128 v[138:141], v146 offset:1024
	ds_read_b128 v[142:145], v146 offset:2048
	ds_read_b128 v[146:149], v146 offset:3072
	ds_read_b128 v[150:153], v179
	ds_read_b128 v[164:167], v179 offset:1024
	ds_read_b128 v[168:171], v179 offset:2048
	ds_read_b128 v[180:183], v179 offset:3072
	s_add_u32 s48, s48, 0x160000
	s_addc_u32 s49, s49, 0
	s_mov_b32 m0, s57
	v_lshl_add_u64 v[238:239], s[48:49], 0, v[154:155]
	ds_read_b128 v[184:187], v176 offset:32768
	ds_read_b128 v[188:191], v176 offset:33792
	ds_read_b128 v[196:199], v176 offset:34816
	ds_read_b128 v[202:205], v176 offset:35840
	ds_read_b128 v[206:209], v176 offset:36864
	ds_read_b128 v[212:215], v176 offset:37888
	ds_read_b128 v[226:229], v176 offset:38912
	ds_read_b128 v[230:233], v176 offset:39936
	global_load_lds_dwordx4 v[238:239], off
	v_lshl_add_u64 v[238:239], s[48:49], 0, v[156:157]
	s_mov_b32 m0, s58
	s_nop 0
	global_load_lds_dwordx4 v[238:239], off
	s_waitcnt vmcnt(8)
	s_waitcnt lgkmcnt(0)
	s_barrier
	v_mfma_f32_16x16x32_bf16 v[0:3], v[134:137], v[184:187], v[0:3]
	v_mfma_f32_16x16x32_bf16 v[4:7], v[142:145], v[184:187], v[4:7]
	v_mfma_f32_16x16x32_bf16 v[16:19], v[134:137], v[196:199], v[16:19]
	v_mfma_f32_16x16x32_bf16 v[20:23], v[142:145], v[196:199], v[20:23]
	v_mfma_f32_16x16x32_bf16 v[32:35], v[134:137], v[206:209], v[32:35]
	v_mfma_f32_16x16x32_bf16 v[36:39], v[142:145], v[206:209], v[36:39]
	v_mfma_f32_16x16x32_bf16 v[48:51], v[134:137], v[226:229], v[48:51]
	v_mfma_f32_16x16x32_bf16 v[52:55], v[142:145], v[226:229], v[52:55]
	v_mfma_f32_16x16x32_bf16 v[0:3], v[138:141], v[188:191], v[0:3]
	v_mfma_f32_16x16x32_bf16 v[4:7], v[146:149], v[188:191], v[4:7]
	v_mfma_f32_16x16x32_bf16 v[16:19], v[138:141], v[202:205], v[16:19]
	v_mfma_f32_16x16x32_bf16 v[20:23], v[146:149], v[202:205], v[20:23]
	v_mfma_f32_16x16x32_bf16 v[32:35], v[138:141], v[212:215], v[32:35]
	v_mfma_f32_16x16x32_bf16 v[36:39], v[146:149], v[212:215], v[36:39]
	v_mfma_f32_16x16x32_bf16 v[48:51], v[138:141], v[230:233], v[48:51]
	v_mfma_f32_16x16x32_bf16 v[52:55], v[146:149], v[230:233], v[52:55]
	v_mfma_f32_16x16x32_bf16 v[8:11], v[150:153], v[184:187], v[8:11]
	v_mfma_f32_16x16x32_bf16 v[12:15], v[168:171], v[184:187], v[12:15]
	v_mfma_f32_16x16x32_bf16 v[24:27], v[150:153], v[196:199], v[24:27]
	v_mfma_f32_16x16x32_bf16 v[28:31], v[168:171], v[196:199], v[28:31]
	v_mfma_f32_16x16x32_bf16 v[40:43], v[150:153], v[206:209], v[40:43]
	v_mfma_f32_16x16x32_bf16 v[44:47], v[168:171], v[206:209], v[44:47]
	v_mfma_f32_16x16x32_bf16 v[56:59], v[150:153], v[226:229], v[56:59]
	v_mfma_f32_16x16x32_bf16 v[60:63], v[168:171], v[226:229], v[60:63]
	v_mfma_f32_16x16x32_bf16 v[8:11], v[164:167], v[188:191], v[8:11]
	v_mfma_f32_16x16x32_bf16 v[12:15], v[180:183], v[188:191], v[12:15]
	v_mfma_f32_16x16x32_bf16 v[24:27], v[164:167], v[202:205], v[24:27]
	v_mfma_f32_16x16x32_bf16 v[28:31], v[180:183], v[202:205], v[28:31]
	v_mfma_f32_16x16x32_bf16 v[40:43], v[164:167], v[212:215], v[40:43]
	v_mfma_f32_16x16x32_bf16 v[44:47], v[180:183], v[212:215], v[44:47]
	v_mfma_f32_16x16x32_bf16 v[56:59], v[164:167], v[230:233], v[56:59]
	v_mfma_f32_16x16x32_bf16 v[60:63], v[180:183], v[230:233], v[60:63]
	s_barrier
; #define PG8_STAGE(bufoff, gbase, voff) do { _Pragma("unroll") for (int _i = 0; _i < 2; ++_i) \
;         __builtin_amdgcn_global_load_lds((const unsigned*)((const char*)(gbase) + (voff)[_i]), (PG8_LAS unsigned*)(lds + (bufoff) + ldsw + _i * 8192), 16, 0, 0); } while (0)
; #define PG8_LDA(dst, b, h) do { _Pragma("unroll") for (int m = 0; m < 4; ++m) _Pragma("unroll") for (int k = 0; k < 2; ++k) dst[m][k] = *(const PG8_LAS bf16x8*)(lds + PG8_SA(b, h) + aoff + m * 2048 + k * 1024); } while (0)
; #define PG8_MMA(ai, bj, At, Bt) do { __builtin_amdgcn_s_setprio(1); _Pragma("unroll") for (int m = 0; m < 4; ++m) _Pragma("unroll") for (int n = 0; n < 2; ++n) _Pragma("unroll") for (int k = 0; k < 2; ++k) \
;         acc[ai][bj][m][n] = __builtin_amdgcn_mfma_f32_16x16x32_bf16(Bt[n][k], At[m][k], acc[ai][bj][m][n], 0, 0, 0); __builtin_amdgcn_s_setprio(0); } while (0)
; #define PG8_WAIT_V(n) asm volatile("s_waitcnt vmcnt(" #n ")" ::: "memory")
; #define PG8_WAIT_L(n) asm volatile("s_waitcnt lgkmcnt(" #n ")" ::: "memory")
; #define PG8_BAR __builtin_amdgcn_s_barrier()
; #define PG8_SCHED __builtin_amdgcn_sched_barrier(0)
; template <class Epi, class Sched, bool ALIGN_EPI, bool SP2, int KK, int LDA, int APN>
; __device__ __forceinline__ void gemm_phase(PG8_LAS unsigned char* lds, const Gemm g, const Sched& S, const Epi& E, const int wid) {
;     ...
;             PG8_LDA(At, 1, 1); PG8_STAGE(PG8_SB(1, 0), b3, voffB); PG8_STAGE(PG8_SB(1, 1), b3 + hstep, voffB); PG8_STAGE(PG8_SA(1, 0), a3, voffA);
;             PG8_WAIT_V(8); PG8_WAIT_L(0); PG8_BAR; PG8_MMA(1, 0, At, B0); PG8_MMA(1, 1, At, B1); PG8_BAR; PG8_SCHED;
;     ...
;         }
;         if constexpr (ALIGN_EPI) { if (wr == 0) PG8_BAR; }
	s_add_i32 s48, s61, s54
	v_lshl_add_u64 v[192:193], v[192:193], 0, s[22:23]
	s_mov_b32 m0, s48
	ds_read_b128 v[184:187], v176 offset:49152
	ds_read_b128 v[188:191], v176 offset:50176
	ds_read_b128 v[196:199], v176 offset:51200
	ds_read_b128 v[202:205], v176 offset:52224
	ds_read_b128 v[206:209], v176 offset:53248
	ds_read_b128 v[212:215], v176 offset:54272
	ds_read_b128 v[226:229], v176 offset:55296
	ds_read_b128 v[230:233], v176 offset:56320
	global_load_lds_dwordx4 v[192:193], off
	s_add_i32 m0, s48, 0x2000
	s_add_u32 s30, s30, 0x160080
	v_lshl_add_u64 v[192:193], v[216:217], 0, s[22:23]
	s_addc_u32 s31, s31, 0
	s_add_i32 s48, s66, s54
	global_load_lds_dwordx4 v[192:193], off
	v_lshl_add_u64 v[192:193], s[30:31], 0, v[96:97]
	s_mov_b32 m0, s48
	s_nop 0
	global_load_lds_dwordx4 v[192:193], off
	v_lshl_add_u64 v[192:193], s[30:31], 0, v[158:159]
	s_add_i32 m0, s48, 0x2000
	s_nop 0
	global_load_lds_dwordx4 v[192:193], off
	v_lshl_add_u64 v[192:193], v[234:235], 0, s[22:23]
	s_mov_b32 m0, s7
	s_nop 0
	global_load_lds_dwordx4 v[192:193], off
	v_lshl_add_u64 v[192:193], v[236:237], 0, s[22:23]
	s_mov_b32 m0, s8
	s_nop 0
	global_load_lds_dwordx4 v[192:193], off
	s_waitcnt vmcnt(8)
	s_waitcnt lgkmcnt(0)
	s_barrier
	v_mfma_f32_16x16x32_bf16 v[64:67], v[134:137], v[184:187], v[64:67]
	v_mfma_f32_16x16x32_bf16 v[68:71], v[142:145], v[184:187], v[68:71]
	v_mfma_f32_16x16x32_bf16 v[80:83], v[134:137], v[196:199], v[80:83]
	v_mfma_f32_16x16x32_bf16 v[84:87], v[142:145], v[196:199], v[84:87]
	v_mfma_f32_16x16x32_bf16 v[98:101], v[134:137], v[206:209], v[98:101]
	v_mfma_f32_16x16x32_bf16 v[102:105], v[142:145], v[206:209], v[102:105]
	v_mfma_f32_16x16x32_bf16 v[114:117], v[134:137], v[226:229], v[114:117]
	v_mfma_f32_16x16x32_bf16 v[118:121], v[142:145], v[226:229], v[118:121]
	v_mfma_f32_16x16x32_bf16 v[64:67], v[138:141], v[188:191], v[64:67]
	v_mfma_f32_16x16x32_bf16 v[68:71], v[146:149], v[188:191], v[68:71]
	v_mfma_f32_16x16x32_bf16 v[80:83], v[138:141], v[202:205], v[80:83]
	v_mfma_f32_16x16x32_bf16 v[84:87], v[146:149], v[202:205], v[84:87]
	v_mfma_f32_16x16x32_bf16 v[98:101], v[138:141], v[212:215], v[98:101]
	v_mfma_f32_16x16x32_bf16 v[102:105], v[146:149], v[212:215], v[102:105]
	v_mfma_f32_16x16x32_bf16 v[114:117], v[138:141], v[230:233], v[114:117]
	v_mfma_f32_16x16x32_bf16 v[118:121], v[146:149], v[230:233], v[118:121]
	v_mfma_f32_16x16x32_bf16 v[72:75], v[150:153], v[184:187], v[72:75]
	v_mfma_f32_16x16x32_bf16 v[76:79], v[168:171], v[184:187], v[76:79]
	v_mfma_f32_16x16x32_bf16 v[88:91], v[150:153], v[196:199], v[88:91]
	v_mfma_f32_16x16x32_bf16 v[92:95], v[168:171], v[196:199], v[92:95]
	v_mfma_f32_16x16x32_bf16 v[106:109], v[150:153], v[206:209], v[106:109]
	v_mfma_f32_16x16x32_bf16 v[110:113], v[168:171], v[206:209], v[110:113]
	v_mfma_f32_16x16x32_bf16 v[122:125], v[150:153], v[226:229], v[122:125]
	v_mfma_f32_16x16x32_bf16 v[126:129], v[168:171], v[226:229], v[126:129]
	v_mfma_f32_16x16x32_bf16 v[72:75], v[164:167], v[188:191], v[72:75]
	v_mfma_f32_16x16x32_bf16 v[76:79], v[180:183], v[188:191], v[76:79]
	v_mfma_f32_16x16x32_bf16 v[88:91], v[164:167], v[202:205], v[88:91]
	v_mfma_f32_16x16x32_bf16 v[92:95], v[180:183], v[202:205], v[92:95]
	v_mfma_f32_16x16x32_bf16 v[106:109], v[164:167], v[212:215], v[106:109]
	v_mfma_f32_16x16x32_bf16 v[110:113], v[180:183], v[212:215], v[110:113]
	v_mfma_f32_16x16x32_bf16 v[122:125], v[164:167], v[230:233], v[122:125]
	v_mfma_f32_16x16x32_bf16 v[126:129], v[180:183], v[230:233], v[126:129]
	s_barrier
	s_add_i32 s3, s3, 2
	s_add_u32 s28, s28, 0x100
	s_addc_u32 s29, s29, 0
	s_cmpk_gt_u32 s3, 0x55
	s_cbranch_scc0 .LBB0_860
	s_and_b64 vcc, exec, s[18:19]
	s_cbranch_vccz .LBB0_863
	s_barrier
